# in-proj bf16 stores (q/k/v/u) transposed through LDS: 8 consecutive lanes write one full 128-B line (replaces the permlane widening)
# baseline (speedup 1.0000x reference)
.LBB0_599:
	s_waitcnt vmcnt(0)
	s_barrier
	v_readfirstlane_b32 s7, v225
	s_lshr_b32 s7, s7, 6
	s_mulk_i32 s7, 0x1100
	s_mov_b32 m0, s7
	s_cmp_lt_i32 s6, 32
	s_cselect_b64 s[60:61], -1, 0
	s_sub_i32 s2, s6, 32
	s_lshr_b32 s2, s2, 3
	s_add_i32 s7, s2, 1
	s_cmp_gt_i32 s6, 31
	s_cselect_b64 s[2:3], -1, 0
	s_and_b64 s[4:5], s[2:3], exec
	s_cselect_b32 s5, s7, 0
	s_lshl_b32 s4, s6, 8
	s_add_i32 s4, s4, s73
	s_mul_i32 s6, s18, 3
	s_add_u32 s5, s6, s5
	s_mul_hi_i32 s6, s18, 3
	s_addc_u32 s6, s6, 0
	s_mulk_i32 s6, 0x1400
	s_mul_hi_u32 s7, s5, 0x1400
	s_add_i32 s7, s7, s6
	s_mulk_i32 s5, 0x1400
	s_add_u32 s5, s86, s5
	v_mov_b32_e32 v0, v225
	s_addc_u32 s13, s87, s7
	s_lshl_b32 s6, s42, 8
	s_ashr_i32 s7, s6, 31
	v_and_b32_e32 v132, 15, v0
	v_or_b32_e32 v190, s4, v132
	s_lshl_b64 s[44:45], s[6:7], 2
	v_ashrrev_i32_e32 v191, 31, v190
	s_add_u32 s5, s5, s44
	v_lshl_add_u64 v[130:131], s[30:31], 0, v[190:191]
	s_addc_u32 s7, s13, s45
	v_lshrrev_b32_e32 v0, 2, v0
	v_lshl_add_u64 v[188:189], v[130:131], 4, s[28:29]
	s_add_u32 s44, s5, s97
	v_and_b32_e32 v217, 12, v0
	v_mov_b32_e32 v130, s4
	s_movk_i32 s5, 0x7cf
	s_addc_u32 s45, s7, 0
	v_lshlrev_b32_e32 v0, 2, v217
	v_bitop3_b32 v149, v132, s5, v130 bitop3:0xc8
	v_lshl_add_u64 v[186:187], s[44:45], 0, v[0:1]
	v_mov_b32_e32 v216, v149
	s_cmp_gt_i32 s42, 1
	s_mov_b64 s[44:45], -1
	s_cbranch_scc1 .LBB0_602
	s_andn2_b64 vcc, exec, s[44:45]
	s_mov_b64 s[60:61], 0x1600000
	s_cbranch_vccz .LBB0_660

.LBB0_602:
	s_cmp_lg_u32 s42, 2
	s_mov_b64 s[42:43], -1
	s_cbranch_scc0 .LBB0_604
	v_lshlrev_b64 v[130:131], 10, v[190:191]
	v_lshl_add_u64 v[130:131], s[34:35], 0, v[130:131]
	s_add_i32 s42, s6, 0xfffffd00
	s_mov_b32 s43, s55
	v_lshl_add_u64 v[130:131], s[42:43], 1, v[130:131]
	s_lshl_b32 s42, s76, 1
	v_lshl_add_u64 v[130:131], v[130:131], 0, s[42:43]
	v_lshlrev_b32_e32 v132, 1, v217
	v_mov_b32_e32 v133, v1
	v_lshl_add_u64 v[146:147], v[130:131], 0, v[132:133]
	global_load_dwordx4 v[130:133], v[188:189], off
	v_mov_b64_e32 v[164:165], 0
	v_mov_b64_e32 v[166:167], v[146:147]
	s_movk_i32 s5, 0x4000
	s_waitcnt vmcnt(0)
	v_mov_b32_e32 v134, v131
	v_mov_b32_e32 v135, v132
	v_mov_b32_e32 v131, v133
	v_pk_add_f32 v[130:131], v[134:135], v[130:131]
	s_nop 0
	v_add_f32_e32 v130, v130, v131
	v_fmamk_f32 v130, v130, 0x3a800000, v223
	v_rsq_f32_e32 v162, v130
	global_load_dwordx4 v[130:133], v[188:189], off offset:256
	s_waitcnt vmcnt(0)
	v_mov_b32_e32 v134, v131
	v_mov_b32_e32 v135, v132
	v_mov_b32_e32 v131, v133
	v_pk_add_f32 v[130:131], v[134:135], v[130:131]
	s_nop 0
	v_add_f32_e32 v130, v130, v131
	v_fmamk_f32 v130, v130, 0x3a800000, v223
	v_rsq_f32_e32 v160, v130
	global_load_dwordx4 v[130:133], v[188:189], off offset:512
	s_waitcnt vmcnt(0)
	v_mov_b32_e32 v134, v131
	v_mov_b32_e32 v135, v132
	v_mov_b32_e32 v131, v133
	v_pk_add_f32 v[130:131], v[134:135], v[130:131]
	s_nop 0
	v_add_f32_e32 v130, v130, v131
	v_fmamk_f32 v130, v130, 0x3a800000, v223
	v_rsq_f32_e32 v152, v130
	global_load_dwordx4 v[130:133], v[188:189], off offset:768
	s_waitcnt vmcnt(0)
	v_mov_b32_e32 v134, v131
	v_mov_b32_e32 v135, v132
	v_mov_b32_e32 v131, v133
	v_pk_add_f32 v[130:131], v[134:135], v[130:131]
	s_nop 0
	v_add_f32_e32 v130, v130, v131
	v_fmamk_f32 v130, v130, 0x3a800000, v223
	v_rsq_f32_e32 v158, v130
	global_load_dwordx4 v[130:133], v[188:189], off offset:2048
	s_waitcnt vmcnt(0)
	v_mov_b32_e32 v134, v131
	v_mov_b32_e32 v135, v132
	v_mov_b32_e32 v131, v133
	v_pk_add_f32 v[130:131], v[134:135], v[130:131]
	s_nop 0
	v_add_f32_e32 v130, v130, v131
	v_fmamk_f32 v130, v130, 0x3a800000, v223
	v_rsq_f32_e32 v154, v130
	global_load_dwordx4 v[130:133], v[188:189], off offset:2304
	s_waitcnt vmcnt(0)
	v_mov_b32_e32 v134, v131
	v_mov_b32_e32 v135, v132
	v_mov_b32_e32 v131, v133
	v_pk_add_f32 v[130:131], v[134:135], v[130:131]
	s_nop 0
	v_add_f32_e32 v130, v130, v131
	v_fmamk_f32 v130, v130, 0x3a800000, v223
	v_rsq_f32_e32 v150, v130
	global_load_dwordx4 v[130:133], v[188:189], off offset:2560
	s_waitcnt vmcnt(0)
	v_mov_b32_e32 v134, v131
	v_mov_b32_e32 v135, v132
	v_mov_b32_e32 v131, v133
	v_pk_add_f32 v[130:131], v[134:135], v[130:131]
	s_nop 0
	v_add_f32_e32 v130, v130, v131
	v_fmamk_f32 v130, v130, 0x3a800000, v223
	v_rsq_f32_e32 v148, v130
	global_load_dwordx4 v[130:133], v[188:189], off offset:2816
	s_waitcnt vmcnt(0)
	v_mov_b32_e32 v134, v131
	v_mov_b32_e32 v135, v132
	v_mov_b32_e32 v131, v133
	v_pk_add_f32 v[130:131], v[134:135], v[130:131]
	s_nop 0
	v_add_f32_e32 v130, v130, v131
	v_fmamk_f32 v130, v130, 0x3a800000, v223
	v_rsq_f32_e32 v156, v130
	global_load_dwordx4 v[142:145], v[186:187], off
	global_load_dwordx4 v[138:141], v[186:187], off offset:64
	global_load_dwordx4 v[134:137], v[186:187], off offset:512
	global_load_dwordx4 v[130:133], v[186:187], off offset:576
	s_waitcnt vmcnt(3)
	v_pk_fma_f32 v[168:169], v[126:127], v[162:163], v[142:143] op_sel_hi:[1,0,1]
	v_pk_fma_f32 v[164:165], v[128:129], v[162:163], v[144:145] op_sel_hi:[1,0,1]
	s_waitcnt vmcnt(2)
	v_pk_fma_f32 v[170:171], v[124:125], v[162:163], v[140:141] op_sel_hi:[1,0,1]
	v_pk_fma_f32 v[172:173], v[122:123], v[162:163], v[138:139] op_sel_hi:[1,0,1]
	s_waitcnt vmcnt(1)
	v_pk_fma_f32 v[174:175], v[120:121], v[162:163], v[136:137] op_sel_hi:[1,0,1]
	v_pk_fma_f32 v[176:177], v[118:119], v[162:163], v[134:135] op_sel_hi:[1,0,1]
	s_waitcnt vmcnt(0)
	v_pk_fma_f32 v[192:193], v[116:117], v[162:163], v[132:133] op_sel_hi:[1,0,1]
	v_pk_fma_f32 v[162:163], v[114:115], v[162:163], v[130:131] op_sel_hi:[1,0,1]
	v_mbcnt_lo_u32_b32 v232, -1, 0
	v_mbcnt_hi_u32_b32 v232, -1, v232
	v_and_b32_e32 v233, 15, v232
	v_lshrrev_b32_e32 v234, 4, v232
	v_mul_u32_u24_e32 v222, 0x90, v233
	v_lshl_add_u32 v222, v234, 3, v222
	v_add_u32_e32 v222, m0, v222
	v_bfe_u32 v235, v232, 3, 1
	v_lshlrev_b32_e32 v235, 3, v235
	v_lshl_add_u32 v235, v234, 1, v235
	v_and_b32_e32 v232, 7, v232
	v_mul_u32_u24_e32 v224, 0x90, v235
	v_lshl_add_u32 v224, v232, 4, v224
	v_add_u32_e32 v224, m0, v224
	v_sub_u32_e32 v235, v235, v233
	v_mul_i32_i24_e32 v236, 0x400, v235
	v_lshl_add_u32 v236, v232, 4, v236
	v_lshlrev_b32_e32 v234, 3, v234
	v_sub_u32_e32 v236, v236, v234
	v_ashrrev_i32_e32 v237, 31, v236
	v_cvt_pk_bf16_f32 v228, v168, v169
	v_cvt_pk_bf16_f32 v229, v164, v165
	v_lshl_add_u64 v[236:237], v[166:167], 0, v[236:237]
	v_cvt_pk_bf16_f32 v230, v172, v173
	v_cvt_pk_bf16_f32 v231, v170, v171
	ds_write_b64 v222, v[228:229] offset:36864
	ds_write_b64 v222, v[230:231] offset:36896
	v_cvt_pk_bf16_f32 v232, v176, v177
	v_cvt_pk_bf16_f32 v233, v174, v175
	s_nop 0
	v_cvt_pk_bf16_f32 v234, v162, v163
	v_cvt_pk_bf16_f32 v235, v192, v193
	ds_write_b64 v222, v[232:233] offset:36928
	ds_write_b64 v222, v[234:235] offset:36960
	ds_read_b128 v[228:231], v224 offset:36864
	ds_read_b128 v[232:235], v224 offset:37008
	s_waitcnt lgkmcnt(1)
	global_store_dwordx4 v[236:237], v[228:231], off
	s_waitcnt lgkmcnt(0)
	global_store_dwordx4 v[236:237], v[232:235], off offset:1024
	v_mov_b64_e32 v[162:163], 0
	v_mov_b64_e32 v[164:165], v[146:147]
	v_pk_fma_f32 v[166:167], v[110:111], v[160:161], v[142:143] op_sel_hi:[1,0,1]
	v_pk_fma_f32 v[162:163], v[112:113], v[160:161], v[144:145] op_sel_hi:[1,0,1]
	v_mbcnt_lo_u32_b32 v232, -1, 0
	v_mbcnt_hi_u32_b32 v232, -1, v232
	v_and_b32_e32 v233, 15, v232
	v_lshrrev_b32_e32 v234, 4, v232
	v_mul_u32_u24_e32 v222, 0x90, v233
	v_lshl_add_u32 v222, v234, 3, v222
	v_add_u32_e32 v222, m0, v222
	v_bfe_u32 v235, v232, 3, 1
	v_lshlrev_b32_e32 v235, 3, v235
	v_lshl_add_u32 v235, v234, 1, v235
	v_and_b32_e32 v232, 7, v232
	v_mul_u32_u24_e32 v224, 0x90, v235
	v_lshl_add_u32 v224, v232, 4, v224
	v_add_u32_e32 v224, m0, v224
	v_sub_u32_e32 v235, v235, v233
	v_mul_i32_i24_e32 v236, 0x400, v235
	v_lshl_add_u32 v236, v232, 4, v236
	v_lshlrev_b32_e32 v234, 3, v234
	v_sub_u32_e32 v236, v236, v234
	v_ashrrev_i32_e32 v237, 31, v236
	v_cvt_pk_bf16_f32 v228, v166, v167
	v_pk_fma_f32 v[168:169], v[108:109], v[160:161], v[140:141] op_sel_hi:[1,0,1]
	v_cvt_pk_bf16_f32 v229, v162, v163
	v_add_co_u32_e32 v162, vcc, s5, v164
	v_pk_fma_f32 v[170:171], v[106:107], v[160:161], v[138:139] op_sel_hi:[1,0,1]
	s_nop 0
	v_addc_co_u32_e32 v163, vcc, 0, v165, vcc
	v_pk_fma_f32 v[172:173], v[104:105], v[160:161], v[136:137] op_sel_hi:[1,0,1]
	v_pk_fma_f32 v[174:175], v[102:103], v[160:161], v[134:135] op_sel_hi:[1,0,1]
	v_pk_fma_f32 v[176:177], v[100:101], v[160:161], v[132:133] op_sel_hi:[1,0,1]
	v_pk_fma_f32 v[160:161], v[98:99], v[160:161], v[130:131] op_sel_hi:[1,0,1]
	v_lshl_add_u64 v[236:237], v[162:163], 0, v[236:237]
	v_cvt_pk_bf16_f32 v230, v170, v171
	v_cvt_pk_bf16_f32 v231, v168, v169
	ds_write_b64 v222, v[228:229] offset:36864
	ds_write_b64 v222, v[230:231] offset:36896
	v_cvt_pk_bf16_f32 v232, v174, v175
	v_cvt_pk_bf16_f32 v233, v172, v173
	s_nop 0
	v_cvt_pk_bf16_f32 v234, v160, v161
	v_cvt_pk_bf16_f32 v235, v176, v177
	ds_write_b64 v222, v[232:233] offset:36928
	ds_write_b64 v222, v[234:235] offset:36960
	ds_read_b128 v[228:231], v224 offset:36864
	ds_read_b128 v[232:235], v224 offset:37008
	s_waitcnt lgkmcnt(1)
	global_store_dwordx4 v[236:237], v[228:231], off
	s_waitcnt lgkmcnt(0)
	global_store_dwordx4 v[236:237], v[232:235], off offset:1024
	v_mov_b64_e32 v[160:161], 0
	v_mov_b64_e32 v[162:163], v[146:147]
	v_pk_fma_f32 v[164:165], v[94:95], v[152:153], v[142:143] op_sel_hi:[1,0,1]
	v_pk_fma_f32 v[160:161], v[96:97], v[152:153], v[144:145] op_sel_hi:[1,0,1]
	s_mov_b32 s5, 0x8000
	v_mbcnt_lo_u32_b32 v232, -1, 0
	v_mbcnt_hi_u32_b32 v232, -1, v232
	v_and_b32_e32 v233, 15, v232
	v_lshrrev_b32_e32 v234, 4, v232
	v_mul_u32_u24_e32 v222, 0x90, v233
	v_lshl_add_u32 v222, v234, 3, v222
	v_add_u32_e32 v222, m0, v222
	v_bfe_u32 v235, v232, 3, 1
	v_lshlrev_b32_e32 v235, 3, v235
	v_lshl_add_u32 v235, v234, 1, v235
	v_and_b32_e32 v232, 7, v232
	v_mul_u32_u24_e32 v224, 0x90, v235
	v_lshl_add_u32 v224, v232, 4, v224
	v_add_u32_e32 v224, m0, v224
	v_sub_u32_e32 v235, v235, v233
	v_mul_i32_i24_e32 v236, 0x400, v235
	v_lshl_add_u32 v236, v232, 4, v236
	v_lshlrev_b32_e32 v234, 3, v234
	v_sub_u32_e32 v236, v236, v234
	v_ashrrev_i32_e32 v237, 31, v236
	v_cvt_pk_bf16_f32 v228, v164, v165
	v_cvt_pk_bf16_f32 v229, v160, v161
	v_add_co_u32_e32 v160, vcc, s5, v162
	v_pk_fma_f32 v[166:167], v[92:93], v[152:153], v[140:141] op_sel_hi:[1,0,1]
	s_nop 0
	v_addc_co_u32_e32 v161, vcc, 0, v163, vcc
	v_pk_fma_f32 v[168:169], v[90:91], v[152:153], v[138:139] op_sel_hi:[1,0,1]
	v_pk_fma_f32 v[170:171], v[88:89], v[152:153], v[136:137] op_sel_hi:[1,0,1]
	v_pk_fma_f32 v[172:173], v[86:87], v[152:153], v[134:135] op_sel_hi:[1,0,1]
	v_pk_fma_f32 v[174:175], v[84:85], v[152:153], v[132:133] op_sel_hi:[1,0,1]
	v_pk_fma_f32 v[152:153], v[82:83], v[152:153], v[130:131] op_sel_hi:[1,0,1]
	v_lshl_add_u64 v[236:237], v[160:161], 0, v[236:237]
	v_cvt_pk_bf16_f32 v230, v168, v169
	v_cvt_pk_bf16_f32 v231, v166, v167
	ds_write_b64 v222, v[228:229] offset:36864
	ds_write_b64 v222, v[230:231] offset:36896
	v_cvt_pk_bf16_f32 v232, v172, v173
	v_cvt_pk_bf16_f32 v233, v170, v171
	s_nop 0
	v_cvt_pk_bf16_f32 v234, v152, v153
	v_cvt_pk_bf16_f32 v235, v174, v175
	ds_write_b64 v222, v[232:233] offset:36928
	ds_write_b64 v222, v[234:235] offset:36960
	ds_read_b128 v[228:231], v224 offset:36864
	ds_read_b128 v[232:235], v224 offset:37008
	s_waitcnt lgkmcnt(1)
	global_store_dwordx4 v[236:237], v[228:231], off
	s_waitcnt lgkmcnt(0)
	global_store_dwordx4 v[236:237], v[232:235], off offset:1024
	v_mov_b64_e32 v[152:153], 0
	v_mov_b64_e32 v[160:161], v[146:147]
	v_pk_fma_f32 v[162:163], v[78:79], v[158:159], v[142:143] op_sel_hi:[1,0,1]
	v_pk_fma_f32 v[152:153], v[80:81], v[158:159], v[144:145] op_sel_hi:[1,0,1]
	s_mov_b32 s5, 0xc000
	v_mbcnt_lo_u32_b32 v232, -1, 0
	v_mbcnt_hi_u32_b32 v232, -1, v232
	v_and_b32_e32 v233, 15, v232
	v_lshrrev_b32_e32 v234, 4, v232
	v_mul_u32_u24_e32 v222, 0x90, v233
	v_lshl_add_u32 v222, v234, 3, v222
	v_add_u32_e32 v222, m0, v222
	v_bfe_u32 v235, v232, 3, 1
	v_lshlrev_b32_e32 v235, 3, v235
	v_lshl_add_u32 v235, v234, 1, v235
	v_and_b32_e32 v232, 7, v232
	v_mul_u32_u24_e32 v224, 0x90, v235
	v_lshl_add_u32 v224, v232, 4, v224
	v_add_u32_e32 v224, m0, v224
	v_sub_u32_e32 v235, v235, v233
	v_mul_i32_i24_e32 v236, 0x400, v235
	v_lshl_add_u32 v236, v232, 4, v236
	v_lshlrev_b32_e32 v234, 3, v234
	v_sub_u32_e32 v236, v236, v234
	v_ashrrev_i32_e32 v237, 31, v236
	v_cvt_pk_bf16_f32 v228, v162, v163
	v_cvt_pk_bf16_f32 v229, v152, v153
	v_add_co_u32_e32 v152, vcc, s5, v160
	v_pk_fma_f32 v[164:165], v[76:77], v[158:159], v[140:141] op_sel_hi:[1,0,1]
	s_nop 0
	v_addc_co_u32_e32 v153, vcc, 0, v161, vcc
	v_pk_fma_f32 v[166:167], v[74:75], v[158:159], v[138:139] op_sel_hi:[1,0,1]
	v_pk_fma_f32 v[168:169], v[72:73], v[158:159], v[136:137] op_sel_hi:[1,0,1]
	v_pk_fma_f32 v[170:171], v[70:71], v[158:159], v[134:135] op_sel_hi:[1,0,1]
	v_pk_fma_f32 v[172:173], v[68:69], v[158:159], v[132:133] op_sel_hi:[1,0,1]
	v_pk_fma_f32 v[158:159], v[66:67], v[158:159], v[130:131] op_sel_hi:[1,0,1]
	v_lshl_add_u64 v[236:237], v[152:153], 0, v[236:237]
	v_cvt_pk_bf16_f32 v230, v166, v167
	v_cvt_pk_bf16_f32 v231, v164, v165
	ds_write_b64 v222, v[228:229] offset:36864
	ds_write_b64 v222, v[230:231] offset:36896
	v_cvt_pk_bf16_f32 v232, v170, v171
	v_cvt_pk_bf16_f32 v233, v168, v169
	s_nop 0
	v_cvt_pk_bf16_f32 v234, v158, v159
	v_cvt_pk_bf16_f32 v235, v172, v173
	ds_write_b64 v222, v[232:233] offset:36928
	ds_write_b64 v222, v[234:235] offset:36960
	ds_read_b128 v[228:231], v224 offset:36864
	ds_read_b128 v[232:235], v224 offset:37008
	s_waitcnt lgkmcnt(1)
	global_store_dwordx4 v[236:237], v[228:231], off
	s_waitcnt lgkmcnt(0)
	global_store_dwordx4 v[236:237], v[232:235], off offset:1024
	v_mov_b64_e32 v[152:153], 0
	v_mov_b64_e32 v[158:159], v[146:147]
	v_pk_fma_f32 v[160:161], v[62:63], v[154:155], v[142:143] op_sel_hi:[1,0,1]
	v_pk_fma_f32 v[152:153], v[64:65], v[154:155], v[144:145] op_sel_hi:[1,0,1]
	s_mov_b32 s5, 0x20000
	v_mbcnt_lo_u32_b32 v232, -1, 0
	v_mbcnt_hi_u32_b32 v232, -1, v232
	v_and_b32_e32 v233, 15, v232
	v_lshrrev_b32_e32 v234, 4, v232
	v_mul_u32_u24_e32 v222, 0x90, v233
	v_lshl_add_u32 v222, v234, 3, v222
	v_add_u32_e32 v222, m0, v222
	v_bfe_u32 v235, v232, 3, 1
	v_lshlrev_b32_e32 v235, 3, v235
	v_lshl_add_u32 v235, v234, 1, v235
	v_and_b32_e32 v232, 7, v232
	v_mul_u32_u24_e32 v224, 0x90, v235
	v_lshl_add_u32 v224, v232, 4, v224
	v_add_u32_e32 v224, m0, v224
	v_sub_u32_e32 v235, v235, v233
	v_mul_i32_i24_e32 v236, 0x400, v235
	v_lshl_add_u32 v236, v232, 4, v236
	v_lshlrev_b32_e32 v234, 3, v234
	v_sub_u32_e32 v236, v236, v234
	v_ashrrev_i32_e32 v237, 31, v236
	v_cvt_pk_bf16_f32 v228, v160, v161
	v_cvt_pk_bf16_f32 v229, v152, v153
	v_add_co_u32_e32 v152, vcc, s5, v158
	v_pk_fma_f32 v[162:163], v[60:61], v[154:155], v[140:141] op_sel_hi:[1,0,1]
	s_nop 0
	v_addc_co_u32_e32 v153, vcc, 0, v159, vcc
	v_pk_fma_f32 v[164:165], v[58:59], v[154:155], v[138:139] op_sel_hi:[1,0,1]
	v_pk_fma_f32 v[166:167], v[56:57], v[154:155], v[136:137] op_sel_hi:[1,0,1]
	v_pk_fma_f32 v[168:169], v[54:55], v[154:155], v[134:135] op_sel_hi:[1,0,1]
	v_pk_fma_f32 v[170:171], v[52:53], v[154:155], v[132:133] op_sel_hi:[1,0,1]
	v_pk_fma_f32 v[154:155], v[50:51], v[154:155], v[130:131] op_sel_hi:[1,0,1]
	v_lshl_add_u64 v[236:237], v[152:153], 0, v[236:237]
	v_cvt_pk_bf16_f32 v230, v164, v165
	v_cvt_pk_bf16_f32 v231, v162, v163
	ds_write_b64 v222, v[228:229] offset:36864
	ds_write_b64 v222, v[230:231] offset:36896
	v_cvt_pk_bf16_f32 v232, v168, v169
	v_cvt_pk_bf16_f32 v233, v166, v167
	s_nop 0
	v_cvt_pk_bf16_f32 v234, v154, v155
	v_cvt_pk_bf16_f32 v235, v170, v171
	ds_write_b64 v222, v[232:233] offset:36928
	ds_write_b64 v222, v[234:235] offset:36960
	ds_read_b128 v[228:231], v224 offset:36864
	ds_read_b128 v[232:235], v224 offset:37008
	s_waitcnt lgkmcnt(1)
	global_store_dwordx4 v[236:237], v[228:231], off
	s_waitcnt lgkmcnt(0)
	global_store_dwordx4 v[236:237], v[232:235], off offset:1024
	v_mov_b64_e32 v[152:153], 0
	v_mov_b64_e32 v[154:155], v[146:147]
	v_pk_fma_f32 v[158:159], v[46:47], v[150:151], v[142:143] op_sel_hi:[1,0,1]
	v_pk_fma_f32 v[152:153], v[48:49], v[150:151], v[144:145] op_sel_hi:[1,0,1]
	s_mov_b32 s5, 0x24000
	v_mbcnt_lo_u32_b32 v232, -1, 0
	v_mbcnt_hi_u32_b32 v232, -1, v232
	v_and_b32_e32 v233, 15, v232
	v_lshrrev_b32_e32 v234, 4, v232
	v_mul_u32_u24_e32 v222, 0x90, v233
	v_lshl_add_u32 v222, v234, 3, v222
	v_add_u32_e32 v222, m0, v222
	v_bfe_u32 v235, v232, 3, 1
	v_lshlrev_b32_e32 v235, 3, v235
	v_lshl_add_u32 v235, v234, 1, v235
	v_and_b32_e32 v232, 7, v232
	v_mul_u32_u24_e32 v224, 0x90, v235
	v_lshl_add_u32 v224, v232, 4, v224
	v_add_u32_e32 v224, m0, v224
	v_sub_u32_e32 v235, v235, v233
	v_mul_i32_i24_e32 v236, 0x400, v235
	v_lshl_add_u32 v236, v232, 4, v236
	v_lshlrev_b32_e32 v234, 3, v234
	v_sub_u32_e32 v236, v236, v234
	v_ashrrev_i32_e32 v237, 31, v236
	v_cvt_pk_bf16_f32 v228, v158, v159
	v_cvt_pk_bf16_f32 v229, v152, v153
	v_add_co_u32_e32 v152, vcc, s5, v154
	v_pk_fma_f32 v[160:161], v[44:45], v[150:151], v[140:141] op_sel_hi:[1,0,1]
	s_nop 0
	v_addc_co_u32_e32 v153, vcc, 0, v155, vcc
	v_pk_fma_f32 v[162:163], v[42:43], v[150:151], v[138:139] op_sel_hi:[1,0,1]
	v_pk_fma_f32 v[164:165], v[40:41], v[150:151], v[136:137] op_sel_hi:[1,0,1]
	v_pk_fma_f32 v[166:167], v[38:39], v[150:151], v[134:135] op_sel_hi:[1,0,1]
	v_pk_fma_f32 v[168:169], v[36:37], v[150:151], v[132:133] op_sel_hi:[1,0,1]
	v_pk_fma_f32 v[150:151], v[34:35], v[150:151], v[130:131] op_sel_hi:[1,0,1]
	v_lshl_add_u64 v[236:237], v[152:153], 0, v[236:237]
	v_cvt_pk_bf16_f32 v230, v162, v163
	v_cvt_pk_bf16_f32 v231, v160, v161
	ds_write_b64 v222, v[228:229] offset:36864
	ds_write_b64 v222, v[230:231] offset:36896
	v_cvt_pk_bf16_f32 v232, v166, v167
	v_cvt_pk_bf16_f32 v233, v164, v165
	s_nop 0
	v_cvt_pk_bf16_f32 v234, v150, v151
	v_cvt_pk_bf16_f32 v235, v168, v169
	ds_write_b64 v222, v[232:233] offset:36928
	ds_write_b64 v222, v[234:235] offset:36960
	ds_read_b128 v[228:231], v224 offset:36864
	ds_read_b128 v[232:235], v224 offset:37008
	s_waitcnt lgkmcnt(1)
	global_store_dwordx4 v[236:237], v[228:231], off
	s_waitcnt lgkmcnt(0)
	global_store_dwordx4 v[236:237], v[232:235], off offset:1024
	v_mov_b64_e32 v[150:151], 0
	v_mov_b64_e32 v[152:153], v[146:147]
	v_pk_fma_f32 v[154:155], v[30:31], v[148:149], v[142:143] op_sel_hi:[1,0,1]
	v_pk_fma_f32 v[150:151], v[32:33], v[148:149], v[144:145] op_sel_hi:[1,0,1]
	s_mov_b32 s5, 0x28000
	v_mbcnt_lo_u32_b32 v232, -1, 0
	v_mbcnt_hi_u32_b32 v232, -1, v232
	v_and_b32_e32 v233, 15, v232
	v_lshrrev_b32_e32 v234, 4, v232
	v_mul_u32_u24_e32 v222, 0x90, v233
	v_lshl_add_u32 v222, v234, 3, v222
	v_add_u32_e32 v222, m0, v222
	v_bfe_u32 v235, v232, 3, 1
	v_lshlrev_b32_e32 v235, 3, v235
	v_lshl_add_u32 v235, v234, 1, v235
	v_and_b32_e32 v232, 7, v232
	v_mul_u32_u24_e32 v224, 0x90, v235
	v_lshl_add_u32 v224, v232, 4, v224
	v_add_u32_e32 v224, m0, v224
	v_sub_u32_e32 v235, v235, v233
	v_mul_i32_i24_e32 v236, 0x400, v235
	v_lshl_add_u32 v236, v232, 4, v236
	v_lshlrev_b32_e32 v234, 3, v234
	v_sub_u32_e32 v236, v236, v234
	v_ashrrev_i32_e32 v237, 31, v236
	v_cvt_pk_bf16_f32 v228, v154, v155
	v_cvt_pk_bf16_f32 v229, v150, v151
	v_add_co_u32_e32 v150, vcc, s5, v152
	v_pk_fma_f32 v[158:159], v[28:29], v[148:149], v[140:141] op_sel_hi:[1,0,1]
	s_nop 0
	v_addc_co_u32_e32 v151, vcc, 0, v153, vcc
	v_pk_fma_f32 v[160:161], v[26:27], v[148:149], v[138:139] op_sel_hi:[1,0,1]
	v_lshl_add_u64 v[236:237], v[150:151], 0, v[236:237]
	v_cvt_pk_bf16_f32 v230, v160, v161
	v_cvt_pk_bf16_f32 v231, v158, v159
	v_pk_fma_f32 v[162:163], v[24:25], v[148:149], v[136:137] op_sel_hi:[1,0,1]
	v_pk_fma_f32 v[164:165], v[22:23], v[148:149], v[134:135] op_sel_hi:[1,0,1]
	ds_write_b64 v222, v[228:229] offset:36864
	ds_write_b64 v222, v[230:231] offset:36896
	v_cvt_pk_bf16_f32 v232, v164, v165
	v_cvt_pk_bf16_f32 v233, v162, v163
	v_pk_fma_f32 v[166:167], v[20:21], v[148:149], v[132:133] op_sel_hi:[1,0,1]
	v_pk_fma_f32 v[168:169], v[18:19], v[148:149], v[130:131] op_sel_hi:[1,0,1]
	s_nop 0
	v_cvt_pk_bf16_f32 v234, v168, v169
	v_cvt_pk_bf16_f32 v235, v166, v167
	ds_write_b64 v222, v[232:233] offset:36928
	ds_write_b64 v222, v[234:235] offset:36960
	ds_read_b128 v[228:231], v224 offset:36864
	ds_read_b128 v[232:235], v224 offset:37008
	s_waitcnt lgkmcnt(1)
	global_store_dwordx4 v[236:237], v[228:231], off
	s_waitcnt lgkmcnt(0)
	global_store_dwordx4 v[236:237], v[232:235], off offset:1024
	v_mov_b64_e32 v[150:151], 0
	v_pk_fma_f32 v[144:145], v[16:17], v[156:157], v[144:145] op_sel_hi:[1,0,1]
	v_pk_fma_f32 v[142:143], v[14:15], v[156:157], v[142:143] op_sel_hi:[1,0,1]
	s_mov_b32 s5, 0x2c000
	v_mbcnt_lo_u32_b32 v232, -1, 0
	v_mbcnt_hi_u32_b32 v232, -1, v232
	v_and_b32_e32 v233, 15, v232
	v_lshrrev_b32_e32 v234, 4, v232
	v_mul_u32_u24_e32 v222, 0x90, v233
	v_lshl_add_u32 v222, v234, 3, v222
	v_add_u32_e32 v222, m0, v222
	v_bfe_u32 v235, v232, 3, 1
	v_lshlrev_b32_e32 v235, 3, v235
	v_lshl_add_u32 v235, v234, 1, v235
	v_and_b32_e32 v232, 7, v232
	v_mul_u32_u24_e32 v224, 0x90, v235
	v_lshl_add_u32 v224, v232, 4, v224
	v_add_u32_e32 v224, m0, v224
	v_sub_u32_e32 v235, v235, v233
	v_mul_i32_i24_e32 v236, 0x400, v235
	v_lshl_add_u32 v236, v232, 4, v236
	v_lshlrev_b32_e32 v234, 3, v234
	v_sub_u32_e32 v236, v236, v234
	v_ashrrev_i32_e32 v237, 31, v236
	v_cvt_pk_bf16_f32 v228, v142, v143
	v_cvt_pk_bf16_f32 v229, v144, v145
	v_pk_fma_f32 v[138:139], v[10:11], v[156:157], v[138:139] op_sel_hi:[1,0,1]
	v_add_co_u32_e32 v144, vcc, s5, v146
	v_pk_fma_f32 v[134:135], v[6:7], v[156:157], v[134:135] op_sel_hi:[1,0,1]
	v_pk_fma_f32 v[130:131], v[2:3], v[156:157], v[130:131] op_sel_hi:[1,0,1]
	v_addc_co_u32_e32 v145, vcc, 0, v147, vcc
	v_pk_fma_f32 v[140:141], v[12:13], v[156:157], v[140:141] op_sel_hi:[1,0,1]
	v_pk_fma_f32 v[136:137], v[8:9], v[156:157], v[136:137] op_sel_hi:[1,0,1]
	v_pk_fma_f32 v[132:133], v[4:5], v[156:157], v[132:133] op_sel_hi:[1,0,1]
	v_lshl_add_u64 v[236:237], v[144:145], 0, v[236:237]
	v_cvt_pk_bf16_f32 v230, v138, v139
	v_cvt_pk_bf16_f32 v231, v140, v141
	ds_write_b64 v222, v[228:229] offset:36864
	ds_write_b64 v222, v[230:231] offset:36896
	v_cvt_pk_bf16_f32 v232, v134, v135
	v_cvt_pk_bf16_f32 v233, v136, v137
	s_nop 0
	v_cvt_pk_bf16_f32 v234, v130, v131
	v_cvt_pk_bf16_f32 v235, v132, v133
	ds_write_b64 v222, v[232:233] offset:36928
	ds_write_b64 v222, v[234:235] offset:36960
	ds_read_b128 v[228:231], v224 offset:36864
	ds_read_b128 v[232:235], v224 offset:37008
	s_waitcnt lgkmcnt(1)
	global_store_dwordx4 v[236:237], v[228:231], off
	s_waitcnt lgkmcnt(0)
	global_store_dwordx4 v[236:237], v[232:235], off offset:1024
	s_mov_b64 s[42:43], 0

.LBB0_607:
	s_add_u32 s42, s94, s42
	s_addc_u32 s43, s95, s43
	s_ashr_i32 s4, s4, 6
	s_and_b32 s4, s4, -4
	s_add_i32 s4, s4, s18
	v_lshlrev_b64 v[130:131], 8, v[130:131]
	s_ashr_i32 s5, s4, 31
	v_lshl_add_u64 v[130:131], s[42:43], 0, v[130:131]
	v_lshlrev_b32_e32 v132, 1, v217
	v_mov_b32_e32 v133, v1
	s_lshl_b64 s[4:5], s[4:5], 17
	v_lshl_add_u64 v[192:193], v[130:131], 0, v[132:133]
	s_add_u32 s4, s88, s4
	v_lshlrev_b32_e32 v130, 9, v190
	s_addc_u32 s5, s89, s5
	v_and_b32_e32 v130, 0x19e00, v130
	v_mov_b32_e32 v131, v1
	v_lshl_add_u64 v[130:131], s[4:5], 0, v[130:131]
	v_lshl_add_u64 v[130:131], v[130:131], 0, s[54:55]
	v_lshl_add_u64 v[194:195], v[130:131], 0, v[0:1]
	v_cndmask_b32_e64 v130, 0, 1, s[60:61]
	s_mov_b64 s[56:57], -1
	s_and_b64 vcc, exec, s[48:49]
	v_cmp_ne_u32_e64 s[42:43], 1, v130
	s_cbranch_vccz .LBB0_625
	global_load_dwordx4 v[130:133], v[188:189], off
	global_load_dwordx4 v[134:137], v[188:189], off offset:256
	global_load_dwordx4 v[138:141], v[188:189], off offset:512
	global_load_dwordx4 v[142:145], v[188:189], off offset:768
	global_load_dwordx4 v[228:231], v[188:189], off offset:2048
	global_load_dwordx4 v[232:235], v[188:189], off offset:2304
	global_load_dwordx4 v[240:243], v[188:189], off offset:2560
	global_load_dwordx4 v[158:161], v[188:189], off offset:2816
	global_load_dwordx4 v[244:247], v[186:187], off
	global_load_dwordx4 v[248:251], v[186:187], off offset:64
	global_load_dwordx4 v[150:153], v[186:187], off offset:512
	global_load_dwordx4 v[218:221], v[186:187], off offset:576
	v_mov_b64_e32 v[196:197], v[194:195]
	v_mov_b64_e32 v[176:177], v[192:193]
	s_and_b64 vcc, exec, s[42:43]
	s_waitcnt vmcnt(8)
	v_mov_b32_e32 v146, v131
	v_mov_b32_e32 v147, v132
	v_mov_b32_e32 v131, v133
	v_mov_b32_e32 v132, v135
	v_mov_b32_e32 v133, v136
	v_mov_b32_e32 v135, v137
	v_mov_b32_e32 v136, v139
	v_mov_b32_e32 v137, v140
	v_mov_b32_e32 v139, v141
	v_mov_b32_e32 v140, v143
	v_mov_b32_e32 v141, v144
	v_mov_b32_e32 v143, v145
	v_pk_add_f32 v[130:131], v[146:147], v[130:131]
	v_pk_add_f32 v[132:133], v[132:133], v[134:135]
	v_pk_add_f32 v[134:135], v[136:137], v[138:139]
	v_pk_add_f32 v[136:137], v[140:141], v[142:143]
	v_add_f32_e32 v130, v130, v131
	v_add_f32_e32 v131, v132, v133
	v_add_f32_e32 v132, v134, v135
	v_add_f32_e32 v133, v136, v137
	v_fmamk_f32 v130, v130, 0x3a800000, v223
	v_fmamk_f32 v131, v131, 0x3a800000, v223
	v_fmamk_f32 v132, v132, 0x3a800000, v223
	v_fmamk_f32 v133, v133, 0x3a800000, v223
	v_rsq_f32_e32 v148, v130
	v_rsq_f32_e32 v174, v131
	v_rsq_f32_e32 v172, v132
	v_rsq_f32_e32 v170, v133
	s_waitcnt vmcnt(7)
	v_add_f32_e32 v228, v228, v229
	v_add_f32_e32 v229, v230, v231
	s_waitcnt vmcnt(6)
	v_add_f32_e32 v230, v232, v233
	v_add_f32_e32 v231, v234, v235
	s_waitcnt vmcnt(5)
	v_add_f32_e32 v232, v240, v241
	v_add_f32_e32 v233, v242, v243
	s_waitcnt vmcnt(4)
	v_add_f32_e32 v234, v158, v159
	v_add_f32_e32 v235, v160, v161
	v_add_f32_e32 v228, v228, v229
	v_add_f32_e32 v229, v230, v231
	v_add_f32_e32 v230, v232, v233
	v_add_f32_e32 v231, v234, v235
	v_fmamk_f32 v228, v228, 0x3a800000, v223
	v_fmamk_f32 v229, v229, 0x3a800000, v223
	v_fmamk_f32 v230, v230, 0x3a800000, v223
	v_fmamk_f32 v231, v231, 0x3a800000, v223
	v_rsq_f32_e32 v168, v228
	v_rsq_f32_e32 v166, v229
	v_rsq_f32_e32 v164, v230
	v_rsq_f32_e32 v162, v231
	s_waitcnt vmcnt(3)
	v_mov_b64_e32 v[142:143], v[244:245]
	v_mov_b64_e32 v[144:145], v[246:247]
	v_pk_fma_f32 v[158:159], v[126:127], v[148:149], v[142:143] op_sel_hi:[1,0,1]
	v_pk_fma_f32 v[160:161], v[128:129], v[148:149], v[144:145] op_sel_hi:[1,0,1]
	s_waitcnt vmcnt(2)
	v_mov_b64_e32 v[138:139], v[248:249]
	v_mov_b64_e32 v[140:141], v[250:251]
	v_pk_fma_f32 v[154:155], v[122:123], v[148:149], v[138:139] op_sel_hi:[1,0,1]
	v_pk_fma_f32 v[156:157], v[124:125], v[148:149], v[140:141] op_sel_hi:[1,0,1]
	s_waitcnt vmcnt(1)
	v_mov_b64_e32 v[134:135], v[150:151]
	v_mov_b64_e32 v[136:137], v[152:153]
	v_pk_fma_f32 v[150:151], v[118:119], v[148:149], v[134:135] op_sel_hi:[1,0,1]
	v_pk_fma_f32 v[152:153], v[120:121], v[148:149], v[136:137] op_sel_hi:[1,0,1]
	s_waitcnt vmcnt(0)
	v_mov_b64_e32 v[130:131], v[218:219]
	v_mov_b64_e32 v[132:133], v[220:221]
	v_pk_fma_f32 v[146:147], v[114:115], v[148:149], v[130:131] op_sel_hi:[1,0,1]
	v_pk_fma_f32 v[148:149], v[116:117], v[148:149], v[132:133] op_sel_hi:[1,0,1]
	s_cbranch_vccnz .LBB0_610
	v_mbcnt_lo_u32_b32 v228, -1, 0
	v_mbcnt_hi_u32_b32 v228, -1, v228
	v_and_b32_e32 v229, 15, v228
	v_lshrrev_b32_e32 v228, 4, v228
	v_mul_u32_u24_e32 v230, 0x110, v229
	v_lshl_add_u32 v222, v228, 4, v230
	v_add_u32_e32 v222, m0, v222
	v_mul_u32_u24_e32 v230, 0x110, v228
	v_lshl_add_u32 v224, v229, 4, v230
	v_add_u32_e32 v224, m0, v224
	v_sub_u32_e32 v236, v228, v229
	v_mul_i32_i24_e32 v236, 0x1f0, v236
	v_ashrrev_i32_e32 v237, 31, v236
	ds_write_b128 v222, v[158:161]
	ds_write_b128 v222, v[154:157] offset:64
	ds_write_b128 v222, v[150:153] offset:128
	ds_write_b128 v222, v[146:149] offset:192
	v_lshl_add_u64 v[236:237], v[196:197], 0, v[236:237]
	ds_read_b128 v[228:231], v224
	ds_read_b128 v[232:235], v224 offset:1088
	s_waitcnt lgkmcnt(1)
	global_store_dwordx4 v[236:237], v[228:231], off
	s_waitcnt lgkmcnt(0)
	global_store_dwordx4 v[236:237], v[232:235], off offset:2048
	v_add_co_u32_e32 v236, vcc, 0x1000, v236
	s_nop 1
	v_addc_co_u32_e32 v237, vcc, 0, v237, vcc
	ds_read_b128 v[228:231], v224 offset:2176
	ds_read_b128 v[232:235], v224 offset:3264
	s_waitcnt lgkmcnt(1)
	global_store_dwordx4 v[236:237], v[228:231], off
	s_waitcnt lgkmcnt(0)
	global_store_dwordx4 v[236:237], v[232:235], off offset:2048
	s_nop 1
.LBB0_610:
	v_mbcnt_lo_u32_b32 v232, -1, 0
	v_mbcnt_hi_u32_b32 v232, -1, v232
	v_and_b32_e32 v233, 15, v232
	v_lshrrev_b32_e32 v234, 4, v232
	v_mul_u32_u24_e32 v222, 0x90, v233
	v_lshl_add_u32 v222, v234, 3, v222
	v_add_u32_e32 v222, m0, v222
	v_bfe_u32 v235, v232, 3, 1
	v_lshlrev_b32_e32 v235, 3, v235
	v_lshl_add_u32 v235, v234, 1, v235
	v_and_b32_e32 v232, 7, v232
	v_mul_u32_u24_e32 v224, 0x90, v235
	v_lshl_add_u32 v224, v232, 4, v224
	v_add_u32_e32 v224, m0, v224
	v_sub_u32_e32 v235, v235, v233
	v_mul_i32_i24_e32 v236, 0x100, v235
	v_lshl_add_u32 v236, v232, 4, v236
	v_lshlrev_b32_e32 v234, 3, v234
	v_sub_u32_e32 v236, v236, v234
	v_ashrrev_i32_e32 v237, 31, v236
	v_cvt_pk_bf16_f32 v228, v158, v159
	v_cvt_pk_bf16_f32 v229, v160, v161
	v_lshl_add_u64 v[236:237], v[176:177], 0, v[236:237]
	v_cvt_pk_bf16_f32 v230, v154, v155
	v_cvt_pk_bf16_f32 v231, v156, v157
	ds_write_b64 v222, v[228:229] offset:36864
	ds_write_b64 v222, v[230:231] offset:36896
	v_cvt_pk_bf16_f32 v232, v150, v151
	v_cvt_pk_bf16_f32 v233, v152, v153
	s_nop 0
	v_cvt_pk_bf16_f32 v234, v146, v147
	v_cvt_pk_bf16_f32 v235, v148, v149
	ds_write_b64 v222, v[232:233] offset:36928
	ds_write_b64 v222, v[234:235] offset:36960
	ds_read_b128 v[228:231], v224 offset:36864
	ds_read_b128 v[232:235], v224 offset:37008
	s_waitcnt lgkmcnt(1)
	global_store_dwordx4 v[236:237], v[228:231], off
	s_waitcnt lgkmcnt(0)
	global_store_dwordx4 v[236:237], v[232:235], off offset:256
	v_mov_b64_e32 v[176:177], v[192:193]
	v_mov_b64_e32 v[196:197], v[194:195]
	v_pk_fma_f32 v[160:161], v[112:113], v[174:175], v[144:145] op_sel_hi:[1,0,1]
	v_pk_fma_f32 v[158:159], v[110:111], v[174:175], v[142:143] op_sel_hi:[1,0,1]
	v_pk_fma_f32 v[156:157], v[108:109], v[174:175], v[140:141] op_sel_hi:[1,0,1]
	v_pk_fma_f32 v[154:155], v[106:107], v[174:175], v[138:139] op_sel_hi:[1,0,1]
	v_pk_fma_f32 v[152:153], v[104:105], v[174:175], v[136:137] op_sel_hi:[1,0,1]
	v_pk_fma_f32 v[150:151], v[102:103], v[174:175], v[134:135] op_sel_hi:[1,0,1]
	v_pk_fma_f32 v[148:149], v[100:101], v[174:175], v[132:133] op_sel_hi:[1,0,1]
	s_and_b64 vcc, exec, s[42:43]
	v_pk_fma_f32 v[146:147], v[98:99], v[174:175], v[130:131] op_sel_hi:[1,0,1]
	s_cbranch_vccnz .LBB0_612
	v_add_co_u32_e32 v174, vcc, 0x2000, v196
	s_nop 1
	v_addc_co_u32_e32 v175, vcc, 0, v197, vcc
	v_mbcnt_lo_u32_b32 v228, -1, 0
	v_mbcnt_hi_u32_b32 v228, -1, v228
	v_and_b32_e32 v229, 15, v228
	v_lshrrev_b32_e32 v228, 4, v228
	v_mul_u32_u24_e32 v230, 0x110, v229
	v_lshl_add_u32 v222, v228, 4, v230
	v_add_u32_e32 v222, m0, v222
	v_mul_u32_u24_e32 v230, 0x110, v228
	v_lshl_add_u32 v224, v229, 4, v230
	v_add_u32_e32 v224, m0, v224
	v_sub_u32_e32 v236, v228, v229
	v_mul_i32_i24_e32 v236, 0x1f0, v236
	v_ashrrev_i32_e32 v237, 31, v236
	ds_write_b128 v222, v[158:161]
	ds_write_b128 v222, v[154:157] offset:64
	ds_write_b128 v222, v[150:153] offset:128
	ds_write_b128 v222, v[146:149] offset:192
	v_lshl_add_u64 v[236:237], v[174:175], 0, v[236:237]
	ds_read_b128 v[228:231], v224
	ds_read_b128 v[232:235], v224 offset:1088
	s_waitcnt lgkmcnt(1)
	global_store_dwordx4 v[236:237], v[228:231], off
	s_waitcnt lgkmcnt(0)
	global_store_dwordx4 v[236:237], v[232:235], off offset:2048
	v_add_co_u32_e32 v236, vcc, 0x1000, v236
	s_nop 1
	v_addc_co_u32_e32 v237, vcc, 0, v237, vcc
	ds_read_b128 v[228:231], v224 offset:2176
	ds_read_b128 v[232:235], v224 offset:3264
	s_waitcnt lgkmcnt(1)
	global_store_dwordx4 v[236:237], v[228:231], off
	s_waitcnt lgkmcnt(0)
	global_store_dwordx4 v[236:237], v[232:235], off offset:2048
	s_nop 1
.LBB0_612:
	v_mbcnt_lo_u32_b32 v232, -1, 0
	v_mbcnt_hi_u32_b32 v232, -1, v232
	v_and_b32_e32 v233, 15, v232
	v_lshrrev_b32_e32 v234, 4, v232
	v_mul_u32_u24_e32 v222, 0x90, v233
	v_lshl_add_u32 v222, v234, 3, v222
	v_add_u32_e32 v222, m0, v222
	v_bfe_u32 v235, v232, 3, 1
	v_lshlrev_b32_e32 v235, 3, v235
	v_lshl_add_u32 v235, v234, 1, v235
	v_and_b32_e32 v232, 7, v232
	v_mul_u32_u24_e32 v224, 0x90, v235
	v_lshl_add_u32 v224, v232, 4, v224
	v_add_u32_e32 v224, m0, v224
	v_sub_u32_e32 v235, v235, v233
	v_mul_i32_i24_e32 v236, 0x100, v235
	v_lshl_add_u32 v236, v232, 4, v236
	v_lshlrev_b32_e32 v234, 3, v234
	v_sub_u32_e32 v236, v236, v234
	v_ashrrev_i32_e32 v237, 31, v236
	v_cvt_pk_bf16_f32 v228, v158, v159
	v_cvt_pk_bf16_f32 v229, v160, v161
	v_add_co_u32_e32 v160, vcc, 0x1000, v176
	s_nop 1
	v_addc_co_u32_e32 v161, vcc, 0, v177, vcc
	v_lshl_add_u64 v[236:237], v[160:161], 0, v[236:237]
	v_cvt_pk_bf16_f32 v230, v154, v155
	v_cvt_pk_bf16_f32 v231, v156, v157
	ds_write_b64 v222, v[228:229] offset:36864
	ds_write_b64 v222, v[230:231] offset:36896
	v_cvt_pk_bf16_f32 v232, v150, v151
	v_cvt_pk_bf16_f32 v233, v152, v153
	s_nop 0
	v_cvt_pk_bf16_f32 v234, v146, v147
	v_cvt_pk_bf16_f32 v235, v148, v149
	ds_write_b64 v222, v[232:233] offset:36928
	ds_write_b64 v222, v[234:235] offset:36960
	ds_read_b128 v[228:231], v224 offset:36864
	ds_read_b128 v[232:235], v224 offset:37008
	s_waitcnt lgkmcnt(1)
	global_store_dwordx4 v[236:237], v[228:231], off
	s_waitcnt lgkmcnt(0)
	global_store_dwordx4 v[236:237], v[232:235], off offset:256
	v_mov_b64_e32 v[176:177], v[194:195]
	v_mov_b64_e32 v[174:175], v[192:193]
	v_pk_fma_f32 v[160:161], v[96:97], v[172:173], v[144:145] op_sel_hi:[1,0,1]
	v_pk_fma_f32 v[158:159], v[94:95], v[172:173], v[142:143] op_sel_hi:[1,0,1]
	v_pk_fma_f32 v[148:149], v[92:93], v[172:173], v[140:141] op_sel_hi:[1,0,1]
	v_pk_fma_f32 v[146:147], v[90:91], v[172:173], v[138:139] op_sel_hi:[1,0,1]
	v_pk_fma_f32 v[152:153], v[88:89], v[172:173], v[136:137] op_sel_hi:[1,0,1]
	v_pk_fma_f32 v[150:151], v[86:87], v[172:173], v[134:135] op_sel_hi:[1,0,1]
	v_pk_fma_f32 v[156:157], v[84:85], v[172:173], v[132:133] op_sel_hi:[1,0,1]
	s_and_b64 vcc, exec, s[42:43]
	v_pk_fma_f32 v[154:155], v[82:83], v[172:173], v[130:131] op_sel_hi:[1,0,1]
	s_cbranch_vccnz .LBB0_614
	v_add_co_u32_e32 v172, vcc, 0x4000, v176
	s_nop 1
	v_addc_co_u32_e32 v173, vcc, 0, v177, vcc
	v_mbcnt_lo_u32_b32 v228, -1, 0
	v_mbcnt_hi_u32_b32 v228, -1, v228
	v_and_b32_e32 v229, 15, v228
	v_lshrrev_b32_e32 v228, 4, v228
	v_mul_u32_u24_e32 v230, 0x110, v229
	v_lshl_add_u32 v222, v228, 4, v230
	v_add_u32_e32 v222, m0, v222
	v_mul_u32_u24_e32 v230, 0x110, v228
	v_lshl_add_u32 v224, v229, 4, v230
	v_add_u32_e32 v224, m0, v224
	v_sub_u32_e32 v236, v228, v229
	v_mul_i32_i24_e32 v236, 0x1f0, v236
	v_ashrrev_i32_e32 v237, 31, v236
	ds_write_b128 v222, v[158:161]
	ds_write_b128 v222, v[146:149] offset:64
	ds_write_b128 v222, v[150:153] offset:128
	ds_write_b128 v222, v[154:157] offset:192
	v_lshl_add_u64 v[236:237], v[172:173], 0, v[236:237]
	ds_read_b128 v[228:231], v224
	ds_read_b128 v[232:235], v224 offset:1088
	s_waitcnt lgkmcnt(1)
	global_store_dwordx4 v[236:237], v[228:231], off
	s_waitcnt lgkmcnt(0)
	global_store_dwordx4 v[236:237], v[232:235], off offset:2048
	v_add_co_u32_e32 v236, vcc, 0x1000, v236
	s_nop 1
	v_addc_co_u32_e32 v237, vcc, 0, v237, vcc
	ds_read_b128 v[228:231], v224 offset:2176
	ds_read_b128 v[232:235], v224 offset:3264
	s_waitcnt lgkmcnt(1)
	global_store_dwordx4 v[236:237], v[228:231], off
	s_waitcnt lgkmcnt(0)
	global_store_dwordx4 v[236:237], v[232:235], off offset:2048
	s_nop 1
.LBB0_614:
	v_mbcnt_lo_u32_b32 v232, -1, 0
	v_mbcnt_hi_u32_b32 v232, -1, v232
	v_and_b32_e32 v233, 15, v232
	v_lshrrev_b32_e32 v234, 4, v232
	v_mul_u32_u24_e32 v222, 0x90, v233
	v_lshl_add_u32 v222, v234, 3, v222
	v_add_u32_e32 v222, m0, v222
	v_bfe_u32 v235, v232, 3, 1
	v_lshlrev_b32_e32 v235, 3, v235
	v_lshl_add_u32 v235, v234, 1, v235
	v_and_b32_e32 v232, 7, v232
	v_mul_u32_u24_e32 v224, 0x90, v235
	v_lshl_add_u32 v224, v232, 4, v224
	v_add_u32_e32 v224, m0, v224
	v_sub_u32_e32 v235, v235, v233
	v_mul_i32_i24_e32 v236, 0x100, v235
	v_lshl_add_u32 v236, v232, 4, v236
	v_lshlrev_b32_e32 v234, 3, v234
	v_sub_u32_e32 v236, v236, v234
	v_ashrrev_i32_e32 v237, 31, v236
	v_cvt_pk_bf16_f32 v228, v158, v159
	v_cvt_pk_bf16_f32 v229, v160, v161
	v_add_co_u32_e32 v160, vcc, 0x2000, v174
	v_mov_b64_e32 v[172:173], v[192:193]
	s_nop 0
	v_addc_co_u32_e32 v161, vcc, 0, v175, vcc
	v_lshl_add_u64 v[236:237], v[160:161], 0, v[236:237]
	v_cvt_pk_bf16_f32 v230, v146, v147
	v_cvt_pk_bf16_f32 v231, v148, v149
	ds_write_b64 v222, v[228:229] offset:36864
	ds_write_b64 v222, v[230:231] offset:36896
	v_cvt_pk_bf16_f32 v232, v150, v151
	v_cvt_pk_bf16_f32 v233, v152, v153
	s_nop 0
	v_cvt_pk_bf16_f32 v234, v154, v155
	v_cvt_pk_bf16_f32 v235, v156, v157
	ds_write_b64 v222, v[232:233] offset:36928
	ds_write_b64 v222, v[234:235] offset:36960
	ds_read_b128 v[228:231], v224 offset:36864
	ds_read_b128 v[232:235], v224 offset:37008
	s_waitcnt lgkmcnt(1)
	global_store_dwordx4 v[236:237], v[228:231], off
	s_waitcnt lgkmcnt(0)
	global_store_dwordx4 v[236:237], v[232:235], off offset:256
	v_mov_b64_e32 v[174:175], v[194:195]
	v_pk_fma_f32 v[160:161], v[80:81], v[170:171], v[144:145] op_sel_hi:[1,0,1]
	v_pk_fma_f32 v[158:159], v[78:79], v[170:171], v[142:143] op_sel_hi:[1,0,1]
	v_pk_fma_f32 v[156:157], v[76:77], v[170:171], v[140:141] op_sel_hi:[1,0,1]
	v_pk_fma_f32 v[154:155], v[74:75], v[170:171], v[138:139] op_sel_hi:[1,0,1]
	v_pk_fma_f32 v[152:153], v[72:73], v[170:171], v[136:137] op_sel_hi:[1,0,1]
	v_pk_fma_f32 v[150:151], v[70:71], v[170:171], v[134:135] op_sel_hi:[1,0,1]
	v_pk_fma_f32 v[148:149], v[68:69], v[170:171], v[132:133] op_sel_hi:[1,0,1]
	s_and_b64 vcc, exec, s[42:43]
	v_pk_fma_f32 v[146:147], v[66:67], v[170:171], v[130:131] op_sel_hi:[1,0,1]
	s_cbranch_vccnz .LBB0_616
	v_add_co_u32_e32 v170, vcc, 0x6000, v174
	s_nop 1
	v_addc_co_u32_e32 v171, vcc, 0, v175, vcc
	v_mbcnt_lo_u32_b32 v228, -1, 0
	v_mbcnt_hi_u32_b32 v228, -1, v228
	v_and_b32_e32 v229, 15, v228
	v_lshrrev_b32_e32 v228, 4, v228
	v_mul_u32_u24_e32 v230, 0x110, v229
	v_lshl_add_u32 v222, v228, 4, v230
	v_add_u32_e32 v222, m0, v222
	v_mul_u32_u24_e32 v230, 0x110, v228
	v_lshl_add_u32 v224, v229, 4, v230
	v_add_u32_e32 v224, m0, v224
	v_sub_u32_e32 v236, v228, v229
	v_mul_i32_i24_e32 v236, 0x1f0, v236
	v_ashrrev_i32_e32 v237, 31, v236
	ds_write_b128 v222, v[158:161]
	ds_write_b128 v222, v[154:157] offset:64
	ds_write_b128 v222, v[150:153] offset:128
	ds_write_b128 v222, v[146:149] offset:192
	v_lshl_add_u64 v[236:237], v[170:171], 0, v[236:237]
	ds_read_b128 v[228:231], v224
	ds_read_b128 v[232:235], v224 offset:1088
	s_waitcnt lgkmcnt(1)
	global_store_dwordx4 v[236:237], v[228:231], off
	s_waitcnt lgkmcnt(0)
	global_store_dwordx4 v[236:237], v[232:235], off offset:2048
	v_add_co_u32_e32 v236, vcc, 0x1000, v236
	s_nop 1
	v_addc_co_u32_e32 v237, vcc, 0, v237, vcc
	ds_read_b128 v[228:231], v224 offset:2176
	ds_read_b128 v[232:235], v224 offset:3264
	s_waitcnt lgkmcnt(1)
	global_store_dwordx4 v[236:237], v[228:231], off
	s_waitcnt lgkmcnt(0)
	global_store_dwordx4 v[236:237], v[232:235], off offset:2048
	s_nop 1
.LBB0_616:
	v_mbcnt_lo_u32_b32 v232, -1, 0
	v_mbcnt_hi_u32_b32 v232, -1, v232
	v_and_b32_e32 v233, 15, v232
	v_lshrrev_b32_e32 v234, 4, v232
	v_mul_u32_u24_e32 v222, 0x90, v233
	v_lshl_add_u32 v222, v234, 3, v222
	v_add_u32_e32 v222, m0, v222
	v_bfe_u32 v235, v232, 3, 1
	v_lshlrev_b32_e32 v235, 3, v235
	v_lshl_add_u32 v235, v234, 1, v235
	v_and_b32_e32 v232, 7, v232
	v_mul_u32_u24_e32 v224, 0x90, v235
	v_lshl_add_u32 v224, v232, 4, v224
	v_add_u32_e32 v224, m0, v224
	v_sub_u32_e32 v235, v235, v233
	v_mul_i32_i24_e32 v236, 0x100, v235
	v_lshl_add_u32 v236, v232, 4, v236
	v_lshlrev_b32_e32 v234, 3, v234
	v_sub_u32_e32 v236, v236, v234
	v_ashrrev_i32_e32 v237, 31, v236
	v_cvt_pk_bf16_f32 v228, v158, v159
	v_cvt_pk_bf16_f32 v229, v160, v161
	v_add_co_u32_e32 v160, vcc, 0x3000, v172
	s_nop 1
	v_addc_co_u32_e32 v161, vcc, 0, v173, vcc
	v_lshl_add_u64 v[236:237], v[160:161], 0, v[236:237]
	v_cvt_pk_bf16_f32 v230, v154, v155
	v_cvt_pk_bf16_f32 v231, v156, v157
	ds_write_b64 v222, v[228:229] offset:36864
	ds_write_b64 v222, v[230:231] offset:36896
	v_cvt_pk_bf16_f32 v232, v150, v151
	v_cvt_pk_bf16_f32 v233, v152, v153
	s_nop 0
	v_cvt_pk_bf16_f32 v234, v146, v147
	v_cvt_pk_bf16_f32 v235, v148, v149
	ds_write_b64 v222, v[232:233] offset:36928
	ds_write_b64 v222, v[234:235] offset:36960
	ds_read_b128 v[228:231], v224 offset:36864
	ds_read_b128 v[232:235], v224 offset:37008
	s_waitcnt lgkmcnt(1)
	global_store_dwordx4 v[236:237], v[228:231], off
	s_waitcnt lgkmcnt(0)
	global_store_dwordx4 v[236:237], v[232:235], off offset:256
	v_mov_b64_e32 v[170:171], v[192:193]
	v_mov_b64_e32 v[172:173], v[194:195]
	v_pk_fma_f32 v[160:161], v[64:65], v[168:169], v[144:145] op_sel_hi:[1,0,1]
	v_pk_fma_f32 v[158:159], v[62:63], v[168:169], v[142:143] op_sel_hi:[1,0,1]
	v_pk_fma_f32 v[148:149], v[60:61], v[168:169], v[140:141] op_sel_hi:[1,0,1]
	v_pk_fma_f32 v[146:147], v[58:59], v[168:169], v[138:139] op_sel_hi:[1,0,1]
	v_pk_fma_f32 v[152:153], v[56:57], v[168:169], v[136:137] op_sel_hi:[1,0,1]
	v_pk_fma_f32 v[150:151], v[54:55], v[168:169], v[134:135] op_sel_hi:[1,0,1]
	v_pk_fma_f32 v[156:157], v[52:53], v[168:169], v[132:133] op_sel_hi:[1,0,1]
	s_and_b64 vcc, exec, s[42:43]
	v_pk_fma_f32 v[154:155], v[50:51], v[168:169], v[130:131] op_sel_hi:[1,0,1]
	s_cbranch_vccnz .LBB0_618
	v_add_co_u32_e32 v168, vcc, 0x10000, v172
	s_nop 1
	v_addc_co_u32_e32 v169, vcc, 0, v173, vcc
	v_mbcnt_lo_u32_b32 v228, -1, 0
	v_mbcnt_hi_u32_b32 v228, -1, v228
	v_and_b32_e32 v229, 15, v228
	v_lshrrev_b32_e32 v228, 4, v228
	v_mul_u32_u24_e32 v230, 0x110, v229
	v_lshl_add_u32 v222, v228, 4, v230
	v_add_u32_e32 v222, m0, v222
	v_mul_u32_u24_e32 v230, 0x110, v228
	v_lshl_add_u32 v224, v229, 4, v230
	v_add_u32_e32 v224, m0, v224
	v_sub_u32_e32 v236, v228, v229
	v_mul_i32_i24_e32 v236, 0x1f0, v236
	v_ashrrev_i32_e32 v237, 31, v236
	ds_write_b128 v222, v[158:161]
	ds_write_b128 v222, v[146:149] offset:64
	ds_write_b128 v222, v[150:153] offset:128
	ds_write_b128 v222, v[154:157] offset:192
	v_lshl_add_u64 v[236:237], v[168:169], 0, v[236:237]
	ds_read_b128 v[228:231], v224
	ds_read_b128 v[232:235], v224 offset:1088
	s_waitcnt lgkmcnt(1)
	global_store_dwordx4 v[236:237], v[228:231], off
	s_waitcnt lgkmcnt(0)
	global_store_dwordx4 v[236:237], v[232:235], off offset:2048
	v_add_co_u32_e32 v236, vcc, 0x1000, v236
	s_nop 1
	v_addc_co_u32_e32 v237, vcc, 0, v237, vcc
	ds_read_b128 v[228:231], v224 offset:2176
	ds_read_b128 v[232:235], v224 offset:3264
	s_waitcnt lgkmcnt(1)
	global_store_dwordx4 v[236:237], v[228:231], off
	s_waitcnt lgkmcnt(0)
	global_store_dwordx4 v[236:237], v[232:235], off offset:2048
	s_nop 1
.LBB0_618:
	v_mbcnt_lo_u32_b32 v232, -1, 0
	v_mbcnt_hi_u32_b32 v232, -1, v232
	v_and_b32_e32 v233, 15, v232
	v_lshrrev_b32_e32 v234, 4, v232
	v_mul_u32_u24_e32 v222, 0x90, v233
	v_lshl_add_u32 v222, v234, 3, v222
	v_add_u32_e32 v222, m0, v222
	v_bfe_u32 v235, v232, 3, 1
	v_lshlrev_b32_e32 v235, 3, v235
	v_lshl_add_u32 v235, v234, 1, v235
	v_and_b32_e32 v232, 7, v232
	v_mul_u32_u24_e32 v224, 0x90, v235
	v_lshl_add_u32 v224, v232, 4, v224
	v_add_u32_e32 v224, m0, v224
	v_sub_u32_e32 v235, v235, v233
	v_mul_i32_i24_e32 v236, 0x100, v235
	v_lshl_add_u32 v236, v232, 4, v236
	v_lshlrev_b32_e32 v234, 3, v234
	v_sub_u32_e32 v236, v236, v234
	v_ashrrev_i32_e32 v237, 31, v236
	v_cvt_pk_bf16_f32 v228, v158, v159
	v_cvt_pk_bf16_f32 v229, v160, v161
	v_add_co_u32_e32 v160, vcc, 0x8000, v170
	v_mov_b64_e32 v[168:169], v[192:193]
	s_nop 0
	v_addc_co_u32_e32 v161, vcc, 0, v171, vcc
	v_lshl_add_u64 v[236:237], v[160:161], 0, v[236:237]
	v_cvt_pk_bf16_f32 v230, v146, v147
	v_cvt_pk_bf16_f32 v231, v148, v149
	ds_write_b64 v222, v[228:229] offset:36864
	ds_write_b64 v222, v[230:231] offset:36896
	v_cvt_pk_bf16_f32 v232, v150, v151
	v_cvt_pk_bf16_f32 v233, v152, v153
	s_nop 0
	v_cvt_pk_bf16_f32 v234, v154, v155
	v_cvt_pk_bf16_f32 v235, v156, v157
	ds_write_b64 v222, v[232:233] offset:36928
	ds_write_b64 v222, v[234:235] offset:36960
	ds_read_b128 v[228:231], v224 offset:36864
	ds_read_b128 v[232:235], v224 offset:37008
	s_waitcnt lgkmcnt(1)
	global_store_dwordx4 v[236:237], v[228:231], off
	s_waitcnt lgkmcnt(0)
	global_store_dwordx4 v[236:237], v[232:235], off offset:256
	v_mov_b64_e32 v[170:171], v[194:195]
	v_pk_fma_f32 v[160:161], v[48:49], v[166:167], v[144:145] op_sel_hi:[1,0,1]
	v_pk_fma_f32 v[158:159], v[46:47], v[166:167], v[142:143] op_sel_hi:[1,0,1]
	v_pk_fma_f32 v[156:157], v[44:45], v[166:167], v[140:141] op_sel_hi:[1,0,1]
	v_pk_fma_f32 v[154:155], v[42:43], v[166:167], v[138:139] op_sel_hi:[1,0,1]
	v_pk_fma_f32 v[152:153], v[40:41], v[166:167], v[136:137] op_sel_hi:[1,0,1]
	v_pk_fma_f32 v[150:151], v[38:39], v[166:167], v[134:135] op_sel_hi:[1,0,1]
	v_pk_fma_f32 v[148:149], v[36:37], v[166:167], v[132:133] op_sel_hi:[1,0,1]
	s_and_b64 vcc, exec, s[42:43]
	v_pk_fma_f32 v[146:147], v[34:35], v[166:167], v[130:131] op_sel_hi:[1,0,1]
	s_cbranch_vccnz .LBB0_620
	v_add_co_u32_e32 v166, vcc, 0x12000, v170
	s_nop 1
	v_addc_co_u32_e32 v167, vcc, 0, v171, vcc
	v_mbcnt_lo_u32_b32 v228, -1, 0
	v_mbcnt_hi_u32_b32 v228, -1, v228
	v_and_b32_e32 v229, 15, v228
	v_lshrrev_b32_e32 v228, 4, v228
	v_mul_u32_u24_e32 v230, 0x110, v229
	v_lshl_add_u32 v222, v228, 4, v230
	v_add_u32_e32 v222, m0, v222
	v_mul_u32_u24_e32 v230, 0x110, v228
	v_lshl_add_u32 v224, v229, 4, v230
	v_add_u32_e32 v224, m0, v224
	v_sub_u32_e32 v236, v228, v229
	v_mul_i32_i24_e32 v236, 0x1f0, v236
	v_ashrrev_i32_e32 v237, 31, v236
	ds_write_b128 v222, v[158:161]
	ds_write_b128 v222, v[154:157] offset:64
	ds_write_b128 v222, v[150:153] offset:128
	ds_write_b128 v222, v[146:149] offset:192
	v_lshl_add_u64 v[236:237], v[166:167], 0, v[236:237]
	ds_read_b128 v[228:231], v224
	ds_read_b128 v[232:235], v224 offset:1088
	s_waitcnt lgkmcnt(1)
	global_store_dwordx4 v[236:237], v[228:231], off
	s_waitcnt lgkmcnt(0)
	global_store_dwordx4 v[236:237], v[232:235], off offset:2048
	v_add_co_u32_e32 v236, vcc, 0x1000, v236
	s_nop 1
	v_addc_co_u32_e32 v237, vcc, 0, v237, vcc
	ds_read_b128 v[228:231], v224 offset:2176
	ds_read_b128 v[232:235], v224 offset:3264
	s_waitcnt lgkmcnt(1)
	global_store_dwordx4 v[236:237], v[228:231], off
	s_waitcnt lgkmcnt(0)
	global_store_dwordx4 v[236:237], v[232:235], off offset:2048
	s_nop 1
.LBB0_620:
	v_mbcnt_lo_u32_b32 v232, -1, 0
	v_mbcnt_hi_u32_b32 v232, -1, v232
	v_and_b32_e32 v233, 15, v232
	v_lshrrev_b32_e32 v234, 4, v232
	v_mul_u32_u24_e32 v222, 0x90, v233
	v_lshl_add_u32 v222, v234, 3, v222
	v_add_u32_e32 v222, m0, v222
	v_bfe_u32 v235, v232, 3, 1
	v_lshlrev_b32_e32 v235, 3, v235
	v_lshl_add_u32 v235, v234, 1, v235
	v_and_b32_e32 v232, 7, v232
	v_mul_u32_u24_e32 v224, 0x90, v235
	v_lshl_add_u32 v224, v232, 4, v224
	v_add_u32_e32 v224, m0, v224
	v_sub_u32_e32 v235, v235, v233
	v_mul_i32_i24_e32 v236, 0x100, v235
	v_lshl_add_u32 v236, v232, 4, v236
	v_lshlrev_b32_e32 v234, 3, v234
	v_sub_u32_e32 v236, v236, v234
	v_ashrrev_i32_e32 v237, 31, v236
	v_cvt_pk_bf16_f32 v228, v158, v159
	v_cvt_pk_bf16_f32 v229, v160, v161
	v_add_co_u32_e32 v160, vcc, 0x9000, v168
	s_nop 1
	v_addc_co_u32_e32 v161, vcc, 0, v169, vcc
	v_lshl_add_u64 v[236:237], v[160:161], 0, v[236:237]
	v_cvt_pk_bf16_f32 v230, v154, v155
	v_cvt_pk_bf16_f32 v231, v156, v157
	ds_write_b64 v222, v[228:229] offset:36864
	ds_write_b64 v222, v[230:231] offset:36896
	v_cvt_pk_bf16_f32 v232, v150, v151
	v_cvt_pk_bf16_f32 v233, v152, v153
	s_nop 0
	v_cvt_pk_bf16_f32 v234, v146, v147
	v_cvt_pk_bf16_f32 v235, v148, v149
	ds_write_b64 v222, v[232:233] offset:36928
	ds_write_b64 v222, v[234:235] offset:36960
	ds_read_b128 v[228:231], v224 offset:36864
	ds_read_b128 v[232:235], v224 offset:37008
	s_waitcnt lgkmcnt(1)
	global_store_dwordx4 v[236:237], v[228:231], off
	s_waitcnt lgkmcnt(0)
	global_store_dwordx4 v[236:237], v[232:235], off offset:256
	v_mov_b64_e32 v[168:169], v[194:195]
	v_mov_b64_e32 v[166:167], v[192:193]
	v_pk_fma_f32 v[160:161], v[32:33], v[164:165], v[144:145] op_sel_hi:[1,0,1]
	v_pk_fma_f32 v[158:159], v[30:31], v[164:165], v[142:143] op_sel_hi:[1,0,1]
	v_pk_fma_f32 v[148:149], v[28:29], v[164:165], v[140:141] op_sel_hi:[1,0,1]
	v_pk_fma_f32 v[146:147], v[26:27], v[164:165], v[138:139] op_sel_hi:[1,0,1]
	v_pk_fma_f32 v[152:153], v[24:25], v[164:165], v[136:137] op_sel_hi:[1,0,1]
	v_pk_fma_f32 v[150:151], v[22:23], v[164:165], v[134:135] op_sel_hi:[1,0,1]
	v_pk_fma_f32 v[156:157], v[20:21], v[164:165], v[132:133] op_sel_hi:[1,0,1]
	s_and_b64 vcc, exec, s[42:43]
	v_pk_fma_f32 v[154:155], v[18:19], v[164:165], v[130:131] op_sel_hi:[1,0,1]
	s_cbranch_vccnz .LBB0_622
	v_add_co_u32_e32 v164, vcc, 0x14000, v168
	s_nop 1
	v_addc_co_u32_e32 v165, vcc, 0, v169, vcc
	v_mbcnt_lo_u32_b32 v228, -1, 0
	v_mbcnt_hi_u32_b32 v228, -1, v228
	v_and_b32_e32 v229, 15, v228
	v_lshrrev_b32_e32 v228, 4, v228
	v_mul_u32_u24_e32 v230, 0x110, v229
	v_lshl_add_u32 v222, v228, 4, v230
	v_add_u32_e32 v222, m0, v222
	v_mul_u32_u24_e32 v230, 0x110, v228
	v_lshl_add_u32 v224, v229, 4, v230
	v_add_u32_e32 v224, m0, v224
	v_sub_u32_e32 v236, v228, v229
	v_mul_i32_i24_e32 v236, 0x1f0, v236
	v_ashrrev_i32_e32 v237, 31, v236
	ds_write_b128 v222, v[158:161]
	ds_write_b128 v222, v[146:149] offset:64
	ds_write_b128 v222, v[150:153] offset:128
	ds_write_b128 v222, v[154:157] offset:192
	v_lshl_add_u64 v[236:237], v[164:165], 0, v[236:237]
	ds_read_b128 v[228:231], v224
	ds_read_b128 v[232:235], v224 offset:1088
	s_waitcnt lgkmcnt(1)
	global_store_dwordx4 v[236:237], v[228:231], off
	s_waitcnt lgkmcnt(0)
	global_store_dwordx4 v[236:237], v[232:235], off offset:2048
	v_add_co_u32_e32 v236, vcc, 0x1000, v236
	s_nop 1
	v_addc_co_u32_e32 v237, vcc, 0, v237, vcc
	ds_read_b128 v[228:231], v224 offset:2176
	ds_read_b128 v[232:235], v224 offset:3264
	s_waitcnt lgkmcnt(1)
	global_store_dwordx4 v[236:237], v[228:231], off
	s_waitcnt lgkmcnt(0)
	global_store_dwordx4 v[236:237], v[232:235], off offset:2048
	s_nop 1
.LBB0_622:
	v_mbcnt_lo_u32_b32 v232, -1, 0
	v_mbcnt_hi_u32_b32 v232, -1, v232
	v_and_b32_e32 v233, 15, v232
	v_lshrrev_b32_e32 v234, 4, v232
	v_mul_u32_u24_e32 v222, 0x90, v233
	v_lshl_add_u32 v222, v234, 3, v222
	v_add_u32_e32 v222, m0, v222
	v_bfe_u32 v235, v232, 3, 1
	v_lshlrev_b32_e32 v235, 3, v235
	v_lshl_add_u32 v235, v234, 1, v235
	v_and_b32_e32 v232, 7, v232
	v_mul_u32_u24_e32 v224, 0x90, v235
	v_lshl_add_u32 v224, v232, 4, v224
	v_add_u32_e32 v224, m0, v224
	v_sub_u32_e32 v235, v235, v233
	v_mul_i32_i24_e32 v236, 0x100, v235
	v_lshl_add_u32 v236, v232, 4, v236
	v_lshlrev_b32_e32 v234, 3, v234
	v_sub_u32_e32 v236, v236, v234
	v_ashrrev_i32_e32 v237, 31, v236
	v_cvt_pk_bf16_f32 v228, v158, v159
	v_cvt_pk_bf16_f32 v229, v160, v161
	v_add_co_u32_e32 v160, vcc, 0xa000, v166
	v_pk_fma_f32 v[144:145], v[16:17], v[162:163], v[144:145] op_sel_hi:[1,0,1]
	s_nop 0
	v_addc_co_u32_e32 v161, vcc, 0, v167, vcc
	v_lshl_add_u64 v[236:237], v[160:161], 0, v[236:237]
	v_cvt_pk_bf16_f32 v230, v146, v147
	v_cvt_pk_bf16_f32 v231, v148, v149
	ds_write_b64 v222, v[228:229] offset:36864
	ds_write_b64 v222, v[230:231] offset:36896
	v_cvt_pk_bf16_f32 v232, v150, v151
	v_cvt_pk_bf16_f32 v233, v152, v153
	s_nop 0
	v_cvt_pk_bf16_f32 v234, v154, v155
	v_cvt_pk_bf16_f32 v235, v156, v157
	ds_write_b64 v222, v[232:233] offset:36928
	ds_write_b64 v222, v[234:235] offset:36960
	ds_read_b128 v[228:231], v224 offset:36864
	ds_read_b128 v[232:235], v224 offset:37008
	s_waitcnt lgkmcnt(1)
	global_store_dwordx4 v[236:237], v[228:231], off
	s_waitcnt lgkmcnt(0)
	global_store_dwordx4 v[236:237], v[232:235], off offset:256
	v_mov_b64_e32 v[148:149], v[194:195]
	v_mov_b64_e32 v[146:147], v[192:193]
	v_pk_fma_f32 v[142:143], v[14:15], v[162:163], v[142:143] op_sel_hi:[1,0,1]
	v_pk_fma_f32 v[140:141], v[12:13], v[162:163], v[140:141] op_sel_hi:[1,0,1]
	v_pk_fma_f32 v[138:139], v[10:11], v[162:163], v[138:139] op_sel_hi:[1,0,1]
	v_pk_fma_f32 v[136:137], v[8:9], v[162:163], v[136:137] op_sel_hi:[1,0,1]
	v_pk_fma_f32 v[134:135], v[6:7], v[162:163], v[134:135] op_sel_hi:[1,0,1]
	v_pk_fma_f32 v[132:133], v[4:5], v[162:163], v[132:133] op_sel_hi:[1,0,1]
	s_and_b64 vcc, exec, s[42:43]
	v_pk_fma_f32 v[130:131], v[2:3], v[162:163], v[130:131] op_sel_hi:[1,0,1]
	s_cbranch_vccnz .LBB0_624
	v_add_co_u32_e32 v148, vcc, 0x16000, v148
	s_nop 1
	v_addc_co_u32_e32 v149, vcc, 0, v149, vcc
	v_mbcnt_lo_u32_b32 v228, -1, 0
	v_mbcnt_hi_u32_b32 v228, -1, v228
	v_and_b32_e32 v229, 15, v228
	v_lshrrev_b32_e32 v228, 4, v228
	v_mul_u32_u24_e32 v230, 0x110, v229
	v_lshl_add_u32 v222, v228, 4, v230
	v_add_u32_e32 v222, m0, v222
	v_mul_u32_u24_e32 v230, 0x110, v228
	v_lshl_add_u32 v224, v229, 4, v230
	v_add_u32_e32 v224, m0, v224
	v_sub_u32_e32 v236, v228, v229
	v_mul_i32_i24_e32 v236, 0x1f0, v236
	v_ashrrev_i32_e32 v237, 31, v236
	ds_write_b128 v222, v[142:145]
	ds_write_b128 v222, v[138:141] offset:64
	ds_write_b128 v222, v[134:137] offset:128
	ds_write_b128 v222, v[130:133] offset:192
	v_lshl_add_u64 v[236:237], v[148:149], 0, v[236:237]
	ds_read_b128 v[228:231], v224
	ds_read_b128 v[232:235], v224 offset:1088
	s_waitcnt lgkmcnt(1)
	global_store_dwordx4 v[236:237], v[228:231], off
	s_waitcnt lgkmcnt(0)
	global_store_dwordx4 v[236:237], v[232:235], off offset:2048
	v_add_co_u32_e32 v236, vcc, 0x1000, v236
	s_nop 1
	v_addc_co_u32_e32 v237, vcc, 0, v237, vcc
	ds_read_b128 v[228:231], v224 offset:2176
	ds_read_b128 v[232:235], v224 offset:3264
	s_waitcnt lgkmcnt(1)
	global_store_dwordx4 v[236:237], v[228:231], off
	s_waitcnt lgkmcnt(0)
	global_store_dwordx4 v[236:237], v[232:235], off offset:2048
	s_nop 1
.LBB0_624:
	v_mbcnt_lo_u32_b32 v232, -1, 0
	v_mbcnt_hi_u32_b32 v232, -1, v232
	v_and_b32_e32 v233, 15, v232
	v_lshrrev_b32_e32 v234, 4, v232
	v_mul_u32_u24_e32 v222, 0x90, v233
	v_lshl_add_u32 v222, v234, 3, v222
	v_add_u32_e32 v222, m0, v222
	v_bfe_u32 v235, v232, 3, 1
	v_lshlrev_b32_e32 v235, 3, v235
	v_lshl_add_u32 v235, v234, 1, v235
	v_and_b32_e32 v232, 7, v232
	v_mul_u32_u24_e32 v224, 0x90, v235
	v_lshl_add_u32 v224, v232, 4, v224
	v_add_u32_e32 v224, m0, v224
	v_sub_u32_e32 v235, v235, v233
	v_mul_i32_i24_e32 v236, 0x100, v235
	v_lshl_add_u32 v236, v232, 4, v236
	v_lshlrev_b32_e32 v234, 3, v234
	v_sub_u32_e32 v236, v236, v234
	v_ashrrev_i32_e32 v237, 31, v236
	v_cvt_pk_bf16_f32 v228, v142, v143
	v_cvt_pk_bf16_f32 v229, v144, v145
	v_add_co_u32_e32 v144, vcc, 0xb000, v146
	s_nop 1
	v_addc_co_u32_e32 v145, vcc, 0, v147, vcc
	v_lshl_add_u64 v[236:237], v[144:145], 0, v[236:237]
	v_cvt_pk_bf16_f32 v230, v138, v139
	v_cvt_pk_bf16_f32 v231, v140, v141
	ds_write_b64 v222, v[228:229] offset:36864
	ds_write_b64 v222, v[230:231] offset:36896
	v_cvt_pk_bf16_f32 v232, v134, v135
	v_cvt_pk_bf16_f32 v233, v136, v137
	s_nop 0
	v_cvt_pk_bf16_f32 v234, v130, v131
	v_cvt_pk_bf16_f32 v235, v132, v133
	ds_write_b64 v222, v[232:233] offset:36928
	ds_write_b64 v222, v[234:235] offset:36960
	ds_read_b128 v[228:231], v224 offset:36864
	ds_read_b128 v[232:235], v224 offset:37008
	s_waitcnt lgkmcnt(1)
	global_store_dwordx4 v[236:237], v[228:231], off
	s_waitcnt lgkmcnt(0)
	global_store_dwordx4 v[236:237], v[232:235], off offset:256
	s_mov_b64 s[56:57], 0

.LBB0_628:
	s_and_b64 vcc, exec, s[42:43]
	s_cbranch_vccnz .LBB0_630
	v_mbcnt_lo_u32_b32 v228, -1, 0
	v_mbcnt_hi_u32_b32 v228, -1, v228
	v_and_b32_e32 v229, 15, v228
	v_lshrrev_b32_e32 v228, 4, v228
	v_mul_u32_u24_e32 v230, 0x110, v229
	v_lshl_add_u32 v222, v228, 4, v230
	v_add_u32_e32 v222, m0, v222
	v_mul_u32_u24_e32 v230, 0x110, v228
	v_lshl_add_u32 v224, v229, 4, v230
	v_add_u32_e32 v224, m0, v224
	v_sub_u32_e32 v236, v228, v229
	v_mul_i32_i24_e32 v236, 0x1f0, v236
	v_ashrrev_i32_e32 v237, 31, v236
	ds_write_b128 v222, v[170:173]
	ds_write_b128 v222, v[174:177] offset:64
	ds_write_b128 v222, v[162:165] offset:128
	ds_write_b128 v222, v[166:169] offset:192
	v_lshl_add_u64 v[236:237], v[212:213], 0, v[236:237]
	ds_read_b128 v[228:231], v224
	ds_read_b128 v[232:235], v224 offset:1088
	s_waitcnt lgkmcnt(1)
	global_store_dwordx4 v[236:237], v[228:231], off
	s_waitcnt lgkmcnt(0)
	global_store_dwordx4 v[236:237], v[232:235], off offset:2048
	v_add_co_u32_e32 v236, vcc, 0x1000, v236
	s_nop 1
	v_addc_co_u32_e32 v237, vcc, 0, v237, vcc
	ds_read_b128 v[228:231], v224 offset:2176
	ds_read_b128 v[232:235], v224 offset:3264
	s_waitcnt lgkmcnt(1)
	global_store_dwordx4 v[236:237], v[228:231], off
	s_waitcnt lgkmcnt(0)
	global_store_dwordx4 v[236:237], v[232:235], off offset:2048
	s_nop 1
.LBB0_630:
	v_mbcnt_lo_u32_b32 v232, -1, 0
	v_mbcnt_hi_u32_b32 v232, -1, v232
	v_and_b32_e32 v233, 15, v232
	v_lshrrev_b32_e32 v234, 4, v232
	v_mul_u32_u24_e32 v222, 0x90, v233
	v_lshl_add_u32 v222, v234, 3, v222
	v_add_u32_e32 v222, m0, v222
	v_bfe_u32 v235, v232, 3, 1
	v_lshlrev_b32_e32 v235, 3, v235
	v_lshl_add_u32 v235, v234, 1, v235
	v_and_b32_e32 v232, 7, v232
	v_mul_u32_u24_e32 v224, 0x90, v235
	v_lshl_add_u32 v224, v232, 4, v224
	v_add_u32_e32 v224, m0, v224
	v_sub_u32_e32 v235, v235, v233
	v_mul_i32_i24_e32 v236, 0x100, v235
	v_lshl_add_u32 v236, v232, 4, v236
	v_lshlrev_b32_e32 v234, 3, v234
	v_sub_u32_e32 v236, v236, v234
	v_ashrrev_i32_e32 v237, 31, v236
	v_cvt_pk_bf16_f32 v228, v170, v171
	v_cvt_pk_bf16_f32 v229, v172, v173
	v_lshl_add_u64 v[236:237], v[210:211], 0, v[236:237]
	v_cvt_pk_bf16_f32 v230, v174, v175
	v_cvt_pk_bf16_f32 v231, v176, v177
	ds_write_b64 v222, v[228:229] offset:36864
	ds_write_b64 v222, v[230:231] offset:36896
	v_cvt_pk_bf16_f32 v232, v162, v163
	v_cvt_pk_bf16_f32 v233, v164, v165
	s_nop 0
	v_cvt_pk_bf16_f32 v234, v166, v167
	v_cvt_pk_bf16_f32 v235, v168, v169
	ds_write_b64 v222, v[232:233] offset:36928
	ds_write_b64 v222, v[234:235] offset:36960
	ds_read_b128 v[228:231], v224 offset:36864
	ds_read_b128 v[232:235], v224 offset:37008
	s_waitcnt lgkmcnt(1)
	global_store_dwordx4 v[236:237], v[228:231], off
	s_waitcnt lgkmcnt(0)
	global_store_dwordx4 v[236:237], v[232:235], off offset:256
	v_pk_fma_f32 v[162:163], v[112:113], v[208:209], v[160:161] op_sel_hi:[1,0,1]
	v_pk_fma_f32 v[164:165], v[110:111], v[208:209], v[158:159] op_sel_hi:[1,0,1]
	v_mul_f32_e32 v171, v163, v163
	v_mul_f32_e32 v170, v165, v165
	v_pk_fma_f32 v[166:167], v[108:109], v[208:209], v[156:157] op_sel_hi:[1,0,1]
	v_pk_fma_f32 v[168:169], v[106:107], v[208:209], v[154:155] op_sel_hi:[1,0,1]
	v_fmac_f32_e32 v170, v164, v164
	v_fmac_f32_e32 v171, v162, v162
	v_add_f32_e32 v170, v170, v171
	v_mul_f32_e32 v171, v169, v169
	v_mul_f32_e32 v172, v167, v167
	v_fmac_f32_e32 v171, v168, v168
	v_fmac_f32_e32 v172, v166, v166
	v_pk_fma_f32 v[174:175], v[104:105], v[208:209], v[152:153] op_sel_hi:[1,0,1]
	v_pk_fma_f32 v[176:177], v[102:103], v[208:209], v[150:151] op_sel_hi:[1,0,1]
	v_add_f32_e32 v171, v171, v172
	v_add_f32_e32 v170, v170, v171
	v_mul_f32_e32 v171, v177, v177
	v_mul_f32_e32 v172, v175, v175
	v_fmac_f32_e32 v171, v176, v176
	v_fmac_f32_e32 v172, v174, v174
	v_pk_fma_f32 v[212:213], v[100:101], v[208:209], v[148:149] op_sel_hi:[1,0,1]
	v_pk_fma_f32 v[228:229], v[98:99], v[208:209], v[146:147] op_sel_hi:[1,0,1]
	v_add_f32_e32 v171, v171, v172
	v_add_f32_e32 v170, v170, v171
	v_mul_f32_e32 v171, v229, v229
	v_mul_f32_e32 v172, v213, v213
	v_fmac_f32_e32 v171, v228, v228
	v_fmac_f32_e32 v172, v212, v212
	v_add_f32_e32 v171, v171, v172
	v_add_f32_e32 v170, v170, v171
	v_mov_b32_e32 v171, v170
	s_nop 1
	v_permlane16_swap_b32_e32 v170, v171
	v_add_f32_e32 v170, v170, v171
	v_mov_b32_e32 v171, v170
	s_nop 1
	v_permlane32_swap_b32_e32 v170, v171
	v_add_f32_e32 v170, v170, v171
	v_fmamk_f32 v170, v170, 0x3c800000, v223
	v_rsq_f32_e32 v222, v170
	v_add_u32_e32 v205, 16, v216
	v_and_b32_e32 v207, 63, v205
	v_mov_b64_e32 v[210:211], v[194:195]
	v_pk_mul_f32 v[164:165], v[164:165], v[222:223] op_sel_hi:[1,0]
	v_pk_mul_f32 v[162:163], v[162:163], v[222:223] op_sel_hi:[1,0]
	v_pk_mul_f32 v[170:171], v[130:131], v[164:165]
	v_pk_mul_f32 v[172:173], v[132:133], v[162:163]
	v_pk_mul_f32 v[162:163], v[168:169], v[222:223] op_sel_hi:[1,0]
	v_pk_mul_f32 v[164:165], v[166:167], v[222:223] op_sel_hi:[1,0]
	v_pk_mul_f32 v[166:167], v[134:135], v[162:163]
	v_pk_mul_f32 v[168:169], v[136:137], v[164:165]
	v_pk_mul_f32 v[162:163], v[176:177], v[222:223] op_sel_hi:[1,0]
	v_pk_mul_f32 v[164:165], v[174:175], v[222:223] op_sel_hi:[1,0]
	v_pk_mul_f32 v[174:175], v[228:229], v[222:223] op_sel_hi:[1,0]
	v_pk_mul_f32 v[176:177], v[212:213], v[222:223] op_sel_hi:[1,0]
	v_cvt_f32_ubyte0_e32 v212, v207
	v_mov_b64_e32 v[208:209], v[192:193]
	v_pk_mul_f32 v[164:165], v[140:141], v[164:165]
	v_pk_mul_f32 v[162:163], v[138:139], v[162:163]
	v_pk_mul_f32 v[176:177], v[144:145], v[176:177]
	v_pk_mul_f32 v[174:175], v[142:143], v[174:175]
	s_and_b64 vcc, exec, s[44:45]
	v_mul_f32_e32 v245, v220, v212
	v_mul_f32_e32 v243, v219, v212
	v_mul_f32_e32 v241, v218, v212
	v_mul_f32_e32 v213, v197, v212
	s_cbranch_vccnz .LBB0_632
	v_ashrrev_i32_e32 v205, 6, v205
	v_cvt_f32_i32_e32 v205, v205
	v_mul_f32_e32 v207, v220, v205
	v_mul_f32_e32 v222, v219, v205
	v_floor_f32_e32 v207, v207
	v_floor_f32_e32 v222, v222
	v_fma_f32 v207, v220, v205, -v207
	v_sin_f32_e32 v228, v207
	v_cos_f32_e32 v230, v207
	v_fma_f32 v207, v219, v205, -v222
	v_sin_f32_e32 v229, v207
	v_cos_f32_e32 v231, v207
	v_mul_f32_e32 v207, v218, v205
	v_floor_f32_e32 v207, v207
	v_pk_mul_f32 v[232:233], v[228:229], v[166:167]
	v_pk_mul_f32 v[166:167], v[230:231], v[166:167]
	v_mul_f32_e32 v224, v197, v205
	v_fma_f32 v207, v218, v205, -v207
	v_floor_f32_e32 v224, v224
	v_pk_fma_f32 v[230:231], v[230:231], v[170:171], v[232:233] neg_lo:[0,0,1] neg_hi:[0,0,1]
	v_pk_fma_f32 v[166:167], v[228:229], v[170:171], v[166:167]
	v_floor_f32_e32 v170, v245
	v_cos_f32_e32 v222, v207
	v_sin_f32_e32 v207, v207
	v_fma_f32 v205, v197, v205, -v224
	v_fma_f32 v171, v220, v212, -v170
	v_sin_f32_e32 v247, v205
	v_cos_f32_e32 v246, v205
	v_sin_f32_e32 v170, v171
	v_cos_f32_e32 v228, v171
	v_floor_f32_e32 v171, v243
	v_fma_f32 v205, v219, v212, -v171
	v_sin_f32_e32 v171, v205
	v_cos_f32_e32 v229, v205
	v_floor_f32_e32 v205, v241
	v_mul_f32_e32 v234, v222, v172
	v_mul_f32_e32 v236, v207, v168
	v_mul_f32_e32 v250, v222, v168
	v_mov_b32_e32 v168, v173
	v_fma_f32 v205, v218, v212, -v205
	v_floor_f32_e32 v222, v213
	v_mul_f32_e32 v248, v207, v172
	v_pk_mul_f32 v[172:173], v[246:247], v[168:169]
	v_cos_f32_e32 v207, v205
	v_sin_f32_e32 v205, v205
	v_fma_f32 v222, v197, v212, -v222
	v_mov_b32_e32 v235, v172
	v_mov_b32_e32 v237, v173
	v_mov_b32_e32 v172, v247
	v_mov_b32_e32 v173, v246
	v_sin_f32_e32 v247, v222
	v_cos_f32_e32 v246, v222
	v_pk_mul_f32 v[168:169], v[172:173], v[168:169]
	v_pk_add_f32 v[172:173], v[234:235], v[236:237] neg_lo:[0,1] neg_hi:[0,1]
	v_mov_b32_e32 v249, v168
	v_mov_b32_e32 v251, v169
	v_pk_add_f32 v[168:169], v[248:249], v[250:251]
	v_mul_f32_e32 v236, v205, v176
	v_mul_f32_e32 v250, v207, v176
	v_mov_b32_e32 v176, v165
	v_mul_f32_e32 v234, v207, v164
	v_mul_f32_e32 v248, v205, v164
	v_pk_mul_f32 v[164:165], v[246:247], v[176:177]
	v_pk_mul_f32 v[232:233], v[170:171], v[174:175]
	v_mov_b32_e32 v235, v164
	v_mov_b32_e32 v237, v165
	v_mov_b32_e32 v164, v247
	v_mov_b32_e32 v165, v246
	v_pk_mul_f32 v[164:165], v[164:165], v[176:177]
	v_pk_mul_f32 v[174:175], v[228:229], v[174:175]
	v_mov_b32_e32 v249, v164
	v_mov_b32_e32 v251, v165
	v_pk_fma_f32 v[228:229], v[228:229], v[162:163], v[232:233] neg_lo:[0,0,1] neg_hi:[0,0,1]
	v_pk_add_f32 v[164:165], v[234:235], v[236:237] neg_lo:[0,1] neg_hi:[0,1]
	v_pk_fma_f32 v[174:175], v[170:171], v[162:163], v[174:175]
	v_pk_add_f32 v[176:177], v[248:249], v[250:251]
	v_mov_b32_e32 v170, v230
	v_mov_b32_e32 v171, v231
	v_mov_b32_e32 v162, v228
	v_mov_b32_e32 v163, v229
.LBB0_632:
	s_and_b64 vcc, exec, s[42:43]
	s_cbranch_vccnz .LBB0_634
	v_add_co_u32_e32 v210, vcc, 0x2000, v210
	s_nop 1
	v_addc_co_u32_e32 v211, vcc, 0, v211, vcc
	v_mbcnt_lo_u32_b32 v228, -1, 0
	v_mbcnt_hi_u32_b32 v228, -1, v228
	v_and_b32_e32 v229, 15, v228
	v_lshrrev_b32_e32 v228, 4, v228
	v_mul_u32_u24_e32 v230, 0x110, v229
	v_lshl_add_u32 v222, v228, 4, v230
	v_add_u32_e32 v222, m0, v222
	v_mul_u32_u24_e32 v230, 0x110, v228
	v_lshl_add_u32 v224, v229, 4, v230
	v_add_u32_e32 v224, m0, v224
	v_sub_u32_e32 v236, v228, v229
	v_mul_i32_i24_e32 v236, 0x1f0, v236
	v_ashrrev_i32_e32 v237, 31, v236
	ds_write_b128 v222, v[170:173]
	ds_write_b128 v222, v[166:169] offset:64
	ds_write_b128 v222, v[162:165] offset:128
	ds_write_b128 v222, v[174:177] offset:192
	v_lshl_add_u64 v[236:237], v[210:211], 0, v[236:237]
	ds_read_b128 v[228:231], v224
	ds_read_b128 v[232:235], v224 offset:1088
	s_waitcnt lgkmcnt(1)
	global_store_dwordx4 v[236:237], v[228:231], off
	s_waitcnt lgkmcnt(0)
	global_store_dwordx4 v[236:237], v[232:235], off offset:2048
	v_add_co_u32_e32 v236, vcc, 0x1000, v236
	s_nop 1
	v_addc_co_u32_e32 v237, vcc, 0, v237, vcc
	ds_read_b128 v[228:231], v224 offset:2176
	ds_read_b128 v[232:235], v224 offset:3264
	s_waitcnt lgkmcnt(1)
	global_store_dwordx4 v[236:237], v[228:231], off
	s_waitcnt lgkmcnt(0)
	global_store_dwordx4 v[236:237], v[232:235], off offset:2048
	s_nop 1
.LBB0_634:
	v_mbcnt_lo_u32_b32 v232, -1, 0
	v_mbcnt_hi_u32_b32 v232, -1, v232
	v_and_b32_e32 v233, 15, v232
	v_lshrrev_b32_e32 v234, 4, v232
	v_mul_u32_u24_e32 v222, 0x90, v233
	v_lshl_add_u32 v222, v234, 3, v222
	v_add_u32_e32 v222, m0, v222
	v_bfe_u32 v235, v232, 3, 1
	v_lshlrev_b32_e32 v235, 3, v235
	v_lshl_add_u32 v235, v234, 1, v235
	v_and_b32_e32 v232, 7, v232
	v_mul_u32_u24_e32 v224, 0x90, v235
	v_lshl_add_u32 v224, v232, 4, v224
	v_add_u32_e32 v224, m0, v224
	v_sub_u32_e32 v235, v235, v233
	v_mul_i32_i24_e32 v236, 0x100, v235
	v_lshl_add_u32 v236, v232, 4, v236
	v_lshlrev_b32_e32 v234, 3, v234
	v_sub_u32_e32 v236, v236, v234
	v_ashrrev_i32_e32 v237, 31, v236
	v_cvt_pk_bf16_f32 v228, v170, v171
	v_cvt_pk_bf16_f32 v229, v172, v173
	v_add_co_u32_e32 v172, vcc, 0x1000, v208
	v_xor_b32_e32 v203, 32, v203
	s_nop 0
	v_addc_co_u32_e32 v173, vcc, 0, v209, vcc
	v_lshl_add_u64 v[236:237], v[172:173], 0, v[236:237]
	v_cvt_pk_bf16_f32 v230, v166, v167
	v_cvt_pk_bf16_f32 v231, v168, v169
	ds_write_b64 v222, v[228:229] offset:36864
	ds_write_b64 v222, v[230:231] offset:36896
	v_cvt_pk_bf16_f32 v232, v162, v163
	v_cvt_pk_bf16_f32 v233, v164, v165
	s_nop 0
	v_cvt_pk_bf16_f32 v234, v174, v175
	v_cvt_pk_bf16_f32 v235, v176, v177
	ds_write_b64 v222, v[232:233] offset:36928
	ds_write_b64 v222, v[234:235] offset:36960
	ds_read_b128 v[228:231], v224 offset:36864
	ds_read_b128 v[232:235], v224 offset:37008
	s_waitcnt lgkmcnt(1)
	global_store_dwordx4 v[236:237], v[228:231], off
	s_waitcnt lgkmcnt(0)
	global_store_dwordx4 v[236:237], v[232:235], off offset:256
	v_pk_fma_f32 v[162:163], v[96:97], v[206:207], v[160:161] op_sel_hi:[1,0,1]
	v_pk_fma_f32 v[164:165], v[94:95], v[206:207], v[158:159] op_sel_hi:[1,0,1]
	v_mul_f32_e32 v171, v163, v163
	v_mul_f32_e32 v170, v165, v165
	v_pk_fma_f32 v[166:167], v[92:93], v[206:207], v[156:157] op_sel_hi:[1,0,1]
	v_pk_fma_f32 v[168:169], v[90:91], v[206:207], v[154:155] op_sel_hi:[1,0,1]
	v_fmac_f32_e32 v170, v164, v164
	v_fmac_f32_e32 v171, v162, v162
	v_add_f32_e32 v170, v170, v171
	v_mul_f32_e32 v171, v169, v169
	v_mul_f32_e32 v172, v167, v167
	v_fmac_f32_e32 v171, v168, v168
	v_fmac_f32_e32 v172, v166, v166
	v_pk_fma_f32 v[174:175], v[88:89], v[206:207], v[152:153] op_sel_hi:[1,0,1]
	v_pk_fma_f32 v[176:177], v[86:87], v[206:207], v[150:151] op_sel_hi:[1,0,1]
	v_add_f32_e32 v171, v171, v172
	v_add_f32_e32 v170, v170, v171
	v_mul_f32_e32 v171, v177, v177
	v_mul_f32_e32 v172, v175, v175
	v_fmac_f32_e32 v171, v176, v176
	v_fmac_f32_e32 v172, v174, v174
	v_pk_fma_f32 v[210:211], v[84:85], v[206:207], v[148:149] op_sel_hi:[1,0,1]
	v_pk_fma_f32 v[228:229], v[82:83], v[206:207], v[146:147] op_sel_hi:[1,0,1]
	v_add_f32_e32 v171, v171, v172
	v_add_f32_e32 v170, v170, v171
	v_mul_f32_e32 v171, v229, v229
	v_mul_f32_e32 v172, v211, v211
	v_fmac_f32_e32 v171, v228, v228
	v_fmac_f32_e32 v172, v210, v210
	v_add_f32_e32 v171, v171, v172
	v_add_f32_e32 v170, v170, v171
	v_mov_b32_e32 v171, v170
	s_nop 1
	v_permlane16_swap_b32_e32 v170, v171
	v_add_f32_e32 v170, v170, v171
	v_mov_b32_e32 v171, v170
	s_nop 1
	v_permlane32_swap_b32_e32 v170, v171
	v_add_f32_e32 v170, v170, v171
	v_fmamk_f32 v170, v170, 0x3c800000, v223
	v_rsq_f32_e32 v222, v170
	v_mov_b64_e32 v[208:209], v[194:195]
	v_mov_b64_e32 v[206:207], v[192:193]
	s_and_b64 vcc, exec, s[44:45]
	v_pk_mul_f32 v[164:165], v[164:165], v[222:223] op_sel_hi:[1,0]
	v_pk_mul_f32 v[162:163], v[162:163], v[222:223] op_sel_hi:[1,0]
	v_pk_mul_f32 v[170:171], v[130:131], v[164:165]
	v_pk_mul_f32 v[172:173], v[132:133], v[162:163]
	v_pk_mul_f32 v[162:163], v[168:169], v[222:223] op_sel_hi:[1,0]
	v_pk_mul_f32 v[164:165], v[166:167], v[222:223] op_sel_hi:[1,0]
	v_pk_mul_f32 v[166:167], v[134:135], v[162:163]
	v_pk_mul_f32 v[168:169], v[136:137], v[164:165]
	v_pk_mul_f32 v[162:163], v[176:177], v[222:223] op_sel_hi:[1,0]
	v_pk_mul_f32 v[164:165], v[174:175], v[222:223] op_sel_hi:[1,0]
	v_pk_mul_f32 v[174:175], v[228:229], v[222:223] op_sel_hi:[1,0]
	v_pk_mul_f32 v[176:177], v[210:211], v[222:223] op_sel_hi:[1,0]
	v_cvt_f32_ubyte0_e32 v210, v203
	v_pk_mul_f32 v[164:165], v[140:141], v[164:165]
	v_pk_mul_f32 v[162:163], v[138:139], v[162:163]
	v_pk_mul_f32 v[176:177], v[144:145], v[176:177]
	v_pk_mul_f32 v[174:175], v[142:143], v[174:175]
	v_mul_f32_e32 v247, v220, v210
	v_mul_f32_e32 v246, v219, v210
	v_mul_f32_e32 v242, v218, v210
	v_mul_f32_e32 v211, v197, v210
	s_cbranch_vccnz .LBB0_636
	v_add_u32_e32 v203, 32, v216
	v_ashrrev_i32_e32 v203, 6, v203
	v_cvt_f32_i32_e32 v203, v203
	v_mul_f32_e32 v205, v220, v203
	v_mul_f32_e32 v222, v219, v203
	v_floor_f32_e32 v205, v205
	v_floor_f32_e32 v222, v222
	v_fma_f32 v205, v220, v203, -v205
	v_sin_f32_e32 v228, v205
	v_cos_f32_e32 v230, v205
	v_fma_f32 v205, v219, v203, -v222
	v_sin_f32_e32 v229, v205
	v_cos_f32_e32 v231, v205
	v_mul_f32_e32 v205, v218, v203
	v_floor_f32_e32 v205, v205
	v_pk_mul_f32 v[232:233], v[228:229], v[166:167]
	v_pk_mul_f32 v[166:167], v[230:231], v[166:167]
	v_mul_f32_e32 v224, v197, v203
	v_fma_f32 v205, v218, v203, -v205
	v_floor_f32_e32 v224, v224
	v_pk_fma_f32 v[230:231], v[230:231], v[170:171], v[232:233] neg_lo:[0,0,1] neg_hi:[0,0,1]
	v_pk_fma_f32 v[166:167], v[228:229], v[170:171], v[166:167]
	v_floor_f32_e32 v170, v247
	v_cos_f32_e32 v222, v205
	v_sin_f32_e32 v205, v205
	v_fma_f32 v203, v197, v203, -v224
	v_fma_f32 v171, v220, v210, -v170
	v_sin_f32_e32 v249, v203
	v_cos_f32_e32 v248, v203
	v_sin_f32_e32 v170, v171
	v_cos_f32_e32 v228, v171
	v_floor_f32_e32 v171, v246
	v_fma_f32 v203, v219, v210, -v171
	v_sin_f32_e32 v171, v203
	v_cos_f32_e32 v229, v203
	v_floor_f32_e32 v203, v242
	v_mul_f32_e32 v234, v222, v172
	v_mul_f32_e32 v236, v205, v168
	v_mul_f32_e32 v252, v222, v168
	v_mov_b32_e32 v168, v173
	v_fma_f32 v203, v218, v210, -v203
	v_floor_f32_e32 v222, v211
	v_mul_f32_e32 v250, v205, v172
	v_pk_mul_f32 v[172:173], v[248:249], v[168:169]
	v_cos_f32_e32 v205, v203
	v_sin_f32_e32 v203, v203
	v_fma_f32 v222, v197, v210, -v222
	v_mov_b32_e32 v235, v172
	v_mov_b32_e32 v237, v173
	v_mov_b32_e32 v172, v249
	v_mov_b32_e32 v173, v248
	v_sin_f32_e32 v249, v222
	v_cos_f32_e32 v248, v222
	v_pk_mul_f32 v[168:169], v[172:173], v[168:169]
	v_pk_add_f32 v[172:173], v[234:235], v[236:237] neg_lo:[0,1] neg_hi:[0,1]
	v_mov_b32_e32 v251, v168
	v_mov_b32_e32 v253, v169
	v_pk_add_f32 v[168:169], v[250:251], v[252:253]
	v_mul_f32_e32 v236, v203, v176
	v_mul_f32_e32 v252, v205, v176
	v_mov_b32_e32 v176, v165
	v_mul_f32_e32 v234, v205, v164
	v_mul_f32_e32 v250, v203, v164
	v_pk_mul_f32 v[164:165], v[248:249], v[176:177]
	v_pk_mul_f32 v[232:233], v[170:171], v[174:175]
	v_mov_b32_e32 v235, v164
	v_mov_b32_e32 v237, v165
	v_mov_b32_e32 v164, v249
	v_mov_b32_e32 v165, v248
	v_pk_mul_f32 v[164:165], v[164:165], v[176:177]
	v_pk_mul_f32 v[174:175], v[228:229], v[174:175]
	v_mov_b32_e32 v251, v164
	v_mov_b32_e32 v253, v165
	v_pk_fma_f32 v[228:229], v[228:229], v[162:163], v[232:233] neg_lo:[0,0,1] neg_hi:[0,0,1]
	v_pk_add_f32 v[164:165], v[234:235], v[236:237] neg_lo:[0,1] neg_hi:[0,1]
	v_pk_fma_f32 v[174:175], v[170:171], v[162:163], v[174:175]
	v_pk_add_f32 v[176:177], v[250:251], v[252:253]
	v_mov_b32_e32 v170, v230
	v_mov_b32_e32 v171, v231
	v_mov_b32_e32 v162, v228
	v_mov_b32_e32 v163, v229
.LBB0_636:
	s_and_b64 vcc, exec, s[42:43]
	s_cbranch_vccnz .LBB0_638
	v_add_co_u32_e32 v208, vcc, 0x4000, v208
	s_nop 1
	v_addc_co_u32_e32 v209, vcc, 0, v209, vcc
	v_mbcnt_lo_u32_b32 v228, -1, 0
	v_mbcnt_hi_u32_b32 v228, -1, v228
	v_and_b32_e32 v229, 15, v228
	v_lshrrev_b32_e32 v228, 4, v228
	v_mul_u32_u24_e32 v230, 0x110, v229
	v_lshl_add_u32 v222, v228, 4, v230
	v_add_u32_e32 v222, m0, v222
	v_mul_u32_u24_e32 v230, 0x110, v228
	v_lshl_add_u32 v224, v229, 4, v230
	v_add_u32_e32 v224, m0, v224
	v_sub_u32_e32 v236, v228, v229
	v_mul_i32_i24_e32 v236, 0x1f0, v236
	v_ashrrev_i32_e32 v237, 31, v236
	ds_write_b128 v222, v[170:173]
	ds_write_b128 v222, v[166:169] offset:64
	ds_write_b128 v222, v[162:165] offset:128
	ds_write_b128 v222, v[174:177] offset:192
	v_lshl_add_u64 v[236:237], v[208:209], 0, v[236:237]
	ds_read_b128 v[228:231], v224
	ds_read_b128 v[232:235], v224 offset:1088
	s_waitcnt lgkmcnt(1)
	global_store_dwordx4 v[236:237], v[228:231], off
	s_waitcnt lgkmcnt(0)
	global_store_dwordx4 v[236:237], v[232:235], off offset:2048
	v_add_co_u32_e32 v236, vcc, 0x1000, v236
	s_nop 1
	v_addc_co_u32_e32 v237, vcc, 0, v237, vcc
	ds_read_b128 v[228:231], v224 offset:2176
	ds_read_b128 v[232:235], v224 offset:3264
	s_waitcnt lgkmcnt(1)
	global_store_dwordx4 v[236:237], v[228:231], off
	s_waitcnt lgkmcnt(0)
	global_store_dwordx4 v[236:237], v[232:235], off offset:2048
	s_nop 1
.LBB0_638:
	v_mbcnt_lo_u32_b32 v232, -1, 0
	v_mbcnt_hi_u32_b32 v232, -1, v232
	v_and_b32_e32 v233, 15, v232
	v_lshrrev_b32_e32 v234, 4, v232
	v_mul_u32_u24_e32 v222, 0x90, v233
	v_lshl_add_u32 v222, v234, 3, v222
	v_add_u32_e32 v222, m0, v222
	v_bfe_u32 v235, v232, 3, 1
	v_lshlrev_b32_e32 v235, 3, v235
	v_lshl_add_u32 v235, v234, 1, v235
	v_and_b32_e32 v232, 7, v232
	v_mul_u32_u24_e32 v224, 0x90, v235
	v_lshl_add_u32 v224, v232, 4, v224
	v_add_u32_e32 v224, m0, v224
	v_sub_u32_e32 v235, v235, v233
	v_mul_i32_i24_e32 v236, 0x100, v235
	v_lshl_add_u32 v236, v232, 4, v236
	v_lshlrev_b32_e32 v234, 3, v234
	v_sub_u32_e32 v236, v236, v234
	v_ashrrev_i32_e32 v237, 31, v236
	v_cvt_pk_bf16_f32 v228, v170, v171
	v_cvt_pk_bf16_f32 v229, v172, v173
	v_add_co_u32_e32 v172, vcc, 0x2000, v206
	v_pk_fma_f32 v[208:209], v[68:69], v[204:205], v[148:149] op_sel_hi:[1,0,1]
	s_nop 0
	v_addc_co_u32_e32 v173, vcc, 0, v207, vcc
	v_lshl_add_u64 v[236:237], v[172:173], 0, v[236:237]
	v_cvt_pk_bf16_f32 v230, v166, v167
	v_cvt_pk_bf16_f32 v231, v168, v169
	ds_write_b64 v222, v[228:229] offset:36864
	ds_write_b64 v222, v[230:231] offset:36896
	v_cvt_pk_bf16_f32 v232, v162, v163
	v_cvt_pk_bf16_f32 v233, v164, v165
	s_nop 0
	v_cvt_pk_bf16_f32 v234, v174, v175
	v_cvt_pk_bf16_f32 v235, v176, v177
	ds_write_b64 v222, v[232:233] offset:36928
	ds_write_b64 v222, v[234:235] offset:36960
	ds_read_b128 v[228:231], v224 offset:36864
	ds_read_b128 v[232:235], v224 offset:37008
	s_waitcnt lgkmcnt(1)
	global_store_dwordx4 v[236:237], v[228:231], off
	s_waitcnt lgkmcnt(0)
	global_store_dwordx4 v[236:237], v[232:235], off offset:256
	v_pk_fma_f32 v[162:163], v[80:81], v[204:205], v[160:161] op_sel_hi:[1,0,1]
	v_pk_fma_f32 v[164:165], v[78:79], v[204:205], v[158:159] op_sel_hi:[1,0,1]
	v_mul_f32_e32 v171, v163, v163
	v_mul_f32_e32 v170, v165, v165
	v_pk_fma_f32 v[166:167], v[76:77], v[204:205], v[156:157] op_sel_hi:[1,0,1]
	v_pk_fma_f32 v[168:169], v[74:75], v[204:205], v[154:155] op_sel_hi:[1,0,1]
	v_fmac_f32_e32 v170, v164, v164
	v_fmac_f32_e32 v171, v162, v162
	v_add_f32_e32 v170, v170, v171
	v_mul_f32_e32 v171, v169, v169
	v_mul_f32_e32 v172, v167, v167
	v_fmac_f32_e32 v171, v168, v168
	v_fmac_f32_e32 v172, v166, v166
	v_pk_fma_f32 v[174:175], v[72:73], v[204:205], v[152:153] op_sel_hi:[1,0,1]
	v_pk_fma_f32 v[176:177], v[70:71], v[204:205], v[150:151] op_sel_hi:[1,0,1]
	v_add_f32_e32 v171, v171, v172
	v_add_f32_e32 v170, v170, v171
	v_mul_f32_e32 v171, v177, v177
	v_mul_f32_e32 v172, v175, v175
	v_fmac_f32_e32 v171, v176, v176
	v_fmac_f32_e32 v172, v174, v174
	v_pk_fma_f32 v[228:229], v[66:67], v[204:205], v[146:147] op_sel_hi:[1,0,1]
	v_add_f32_e32 v171, v171, v172
	v_add_f32_e32 v170, v170, v171
	v_mul_f32_e32 v171, v229, v229
	v_mul_f32_e32 v172, v209, v209
	v_fmac_f32_e32 v171, v228, v228
	v_fmac_f32_e32 v172, v208, v208
	v_add_f32_e32 v171, v171, v172
	v_add_f32_e32 v170, v170, v171
	v_mov_b32_e32 v171, v170
	s_nop 1
	v_permlane16_swap_b32_e32 v170, v171
	v_add_f32_e32 v170, v170, v171
	v_mov_b32_e32 v171, v170
	s_nop 1
	v_permlane32_swap_b32_e32 v170, v171
	v_add_f32_e32 v170, v170, v171
	v_fmamk_f32 v170, v170, 0x3c800000, v223
	v_rsq_f32_e32 v222, v170
	v_add_u32_e32 v203, 48, v216
	v_and_b32_e32 v224, 63, v203
	v_mov_b64_e32 v[206:207], v[194:195]
	v_pk_mul_f32 v[164:165], v[164:165], v[222:223] op_sel_hi:[1,0]
	v_pk_mul_f32 v[162:163], v[162:163], v[222:223] op_sel_hi:[1,0]
	v_pk_mul_f32 v[170:171], v[130:131], v[164:165]
	v_pk_mul_f32 v[172:173], v[132:133], v[162:163]
	v_pk_mul_f32 v[162:163], v[168:169], v[222:223] op_sel_hi:[1,0]
	v_pk_mul_f32 v[164:165], v[166:167], v[222:223] op_sel_hi:[1,0]
	v_pk_mul_f32 v[166:167], v[134:135], v[162:163]
	v_pk_mul_f32 v[168:169], v[136:137], v[164:165]
	v_pk_mul_f32 v[162:163], v[176:177], v[222:223] op_sel_hi:[1,0]
	v_pk_mul_f32 v[164:165], v[174:175], v[222:223] op_sel_hi:[1,0]
	v_pk_mul_f32 v[174:175], v[228:229], v[222:223] op_sel_hi:[1,0]
	v_pk_mul_f32 v[176:177], v[208:209], v[222:223] op_sel_hi:[1,0]
	v_cvt_f32_ubyte0_e32 v208, v224
	v_mov_b64_e32 v[204:205], v[192:193]
	v_pk_mul_f32 v[164:165], v[140:141], v[164:165]
	v_pk_mul_f32 v[162:163], v[138:139], v[162:163]
	v_pk_mul_f32 v[176:177], v[144:145], v[176:177]
	v_pk_mul_f32 v[174:175], v[142:143], v[174:175]
	s_and_b64 vcc, exec, s[44:45]
	v_mul_f32_e32 v249, v220, v208
	v_mul_f32_e32 v248, v219, v208
	v_mul_f32_e32 v244, v218, v208
	v_mul_f32_e32 v209, v197, v208
	s_cbranch_vccnz .LBB0_640
	v_ashrrev_i32_e32 v203, 6, v203
	v_cvt_f32_i32_e32 v203, v203
	v_mul_f32_e32 v222, v220, v203
	v_mul_f32_e32 v224, v219, v203
	v_floor_f32_e32 v222, v222
	v_floor_f32_e32 v224, v224
	v_fma_f32 v222, v220, v203, -v222
	v_sin_f32_e32 v228, v222
	v_cos_f32_e32 v230, v222
	v_fma_f32 v222, v219, v203, -v224
	v_sin_f32_e32 v229, v222
	v_cos_f32_e32 v231, v222
	v_mul_f32_e32 v222, v218, v203
	v_floor_f32_e32 v222, v222
	v_mul_f32_e32 v225, v197, v203
	v_fma_f32 v222, v218, v203, -v222
	v_floor_f32_e32 v225, v225
	v_cos_f32_e32 v224, v222
	v_sin_f32_e32 v222, v222
	v_fma_f32 v203, v197, v203, -v225
	v_sin_f32_e32 v251, v203
	v_cos_f32_e32 v250, v203
	v_mul_f32_e32 v234, v224, v172
	v_mul_f32_e32 v236, v222, v168
	v_mul_f32_e32 v224, v224, v168
	v_mov_b32_e32 v168, v173
	v_mul_f32_e32 v252, v222, v172
	v_pk_mul_f32 v[172:173], v[250:251], v[168:169]
	v_pk_mul_f32 v[232:233], v[228:229], v[166:167]
	v_pk_mul_f32 v[166:167], v[230:231], v[166:167]
	v_mov_b32_e32 v235, v172
	v_mov_b32_e32 v237, v173
	v_mov_b32_e32 v172, v251
	v_mov_b32_e32 v173, v250
	v_pk_mul_f32 v[168:169], v[172:173], v[168:169]
	v_pk_fma_f32 v[230:231], v[230:231], v[170:171], v[232:233] neg_lo:[0,0,1] neg_hi:[0,0,1]
	v_pk_fma_f32 v[166:167], v[228:229], v[170:171], v[166:167]
	v_floor_f32_e32 v170, v249
	v_mov_b32_e32 v253, v168
	v_mov_b32_e32 v225, v169
	v_fma_f32 v171, v220, v208, -v170
	v_pk_add_f32 v[168:169], v[252:253], v[224:225]
	v_sin_f32_e32 v170, v171
	v_cos_f32_e32 v224, v171
	v_floor_f32_e32 v171, v248
	v_fma_f32 v203, v219, v208, -v171
	v_sin_f32_e32 v171, v203
	v_cos_f32_e32 v225, v203
	v_floor_f32_e32 v203, v244
	v_fma_f32 v203, v218, v208, -v203
	v_floor_f32_e32 v233, v209
	v_cos_f32_e32 v222, v203
	v_sin_f32_e32 v203, v203
	v_fma_f32 v233, v197, v208, -v233
	v_pk_add_f32 v[172:173], v[234:235], v[236:237] neg_lo:[0,1] neg_hi:[0,1]
	v_sin_f32_e32 v237, v233
	v_cos_f32_e32 v236, v233
	v_mul_f32_e32 v234, v203, v176
	v_mul_f32_e32 v252, v222, v176
	v_mov_b32_e32 v176, v165
	v_mul_f32_e32 v232, v222, v164
	v_mul_f32_e32 v250, v203, v164
	v_pk_mul_f32 v[164:165], v[236:237], v[176:177]
	v_pk_mul_f32 v[228:229], v[170:171], v[174:175]
	v_mov_b32_e32 v233, v164
	v_mov_b32_e32 v235, v165
	v_mov_b32_e32 v164, v237
	v_mov_b32_e32 v165, v236
	v_pk_mul_f32 v[164:165], v[164:165], v[176:177]
	v_pk_mul_f32 v[174:175], v[224:225], v[174:175]
	v_mov_b32_e32 v251, v164
	v_mov_b32_e32 v253, v165
	v_pk_fma_f32 v[224:225], v[224:225], v[162:163], v[228:229] neg_lo:[0,0,1] neg_hi:[0,0,1]
	v_pk_add_f32 v[164:165], v[232:233], v[234:235] neg_lo:[0,1] neg_hi:[0,1]
	v_pk_fma_f32 v[174:175], v[170:171], v[162:163], v[174:175]
	v_pk_add_f32 v[176:177], v[250:251], v[252:253]
	v_mov_b32_e32 v170, v230
	v_mov_b32_e32 v171, v231
	v_mov_b32_e32 v162, v224
	v_mov_b32_e32 v163, v225
.LBB0_640:
	s_and_b64 vcc, exec, s[42:43]
	s_cbranch_vccnz .LBB0_642
	v_add_co_u32_e32 v206, vcc, 0x6000, v206
	s_nop 1
	v_addc_co_u32_e32 v207, vcc, 0, v207, vcc
	v_mbcnt_lo_u32_b32 v228, -1, 0
	v_mbcnt_hi_u32_b32 v228, -1, v228
	v_and_b32_e32 v229, 15, v228
	v_lshrrev_b32_e32 v228, 4, v228
	v_mul_u32_u24_e32 v230, 0x110, v229
	v_lshl_add_u32 v222, v228, 4, v230
	v_add_u32_e32 v222, m0, v222
	v_mul_u32_u24_e32 v230, 0x110, v228
	v_lshl_add_u32 v224, v229, 4, v230
	v_add_u32_e32 v224, m0, v224
	v_sub_u32_e32 v236, v228, v229
	v_mul_i32_i24_e32 v236, 0x1f0, v236
	v_ashrrev_i32_e32 v237, 31, v236
	ds_write_b128 v222, v[170:173]
	ds_write_b128 v222, v[166:169] offset:64
	ds_write_b128 v222, v[162:165] offset:128
	ds_write_b128 v222, v[174:177] offset:192
	v_lshl_add_u64 v[236:237], v[206:207], 0, v[236:237]
	ds_read_b128 v[228:231], v224
	ds_read_b128 v[232:235], v224 offset:1088
	s_waitcnt lgkmcnt(1)
	global_store_dwordx4 v[236:237], v[228:231], off
	s_waitcnt lgkmcnt(0)
	global_store_dwordx4 v[236:237], v[232:235], off offset:2048
	v_add_co_u32_e32 v236, vcc, 0x1000, v236
	s_nop 1
	v_addc_co_u32_e32 v237, vcc, 0, v237, vcc
	ds_read_b128 v[228:231], v224 offset:2176
	ds_read_b128 v[232:235], v224 offset:3264
	s_waitcnt lgkmcnt(1)
	global_store_dwordx4 v[236:237], v[228:231], off
	s_waitcnt lgkmcnt(0)
	global_store_dwordx4 v[236:237], v[232:235], off offset:2048
	s_nop 1
.LBB0_642:
	v_mbcnt_lo_u32_b32 v232, -1, 0
	v_mbcnt_hi_u32_b32 v232, -1, v232
	v_and_b32_e32 v233, 15, v232
	v_lshrrev_b32_e32 v234, 4, v232
	v_mul_u32_u24_e32 v222, 0x90, v233
	v_lshl_add_u32 v222, v234, 3, v222
	v_add_u32_e32 v222, m0, v222
	v_bfe_u32 v235, v232, 3, 1
	v_lshlrev_b32_e32 v235, 3, v235
	v_lshl_add_u32 v235, v234, 1, v235
	v_and_b32_e32 v232, 7, v232
	v_mul_u32_u24_e32 v224, 0x90, v235
	v_lshl_add_u32 v224, v232, 4, v224
	v_add_u32_e32 v224, m0, v224
	v_sub_u32_e32 v235, v235, v233
	v_mul_i32_i24_e32 v236, 0x100, v235
	v_lshl_add_u32 v236, v232, 4, v236
	v_lshlrev_b32_e32 v234, 3, v234
	v_sub_u32_e32 v236, v236, v234
	v_ashrrev_i32_e32 v237, 31, v236
	v_cvt_pk_bf16_f32 v228, v170, v171
	v_cvt_pk_bf16_f32 v229, v172, v173
	v_add_co_u32_e32 v172, vcc, 0x3000, v204
	s_nop 1
	v_addc_co_u32_e32 v173, vcc, 0, v205, vcc
	v_lshl_add_u64 v[236:237], v[172:173], 0, v[236:237]
	v_cvt_pk_bf16_f32 v230, v166, v167
	v_cvt_pk_bf16_f32 v231, v168, v169
	ds_write_b64 v222, v[228:229] offset:36864
	ds_write_b64 v222, v[230:231] offset:36896
	v_cvt_pk_bf16_f32 v232, v162, v163
	v_cvt_pk_bf16_f32 v233, v164, v165
	s_nop 0
	v_cvt_pk_bf16_f32 v234, v174, v175
	v_cvt_pk_bf16_f32 v235, v176, v177
	ds_write_b64 v222, v[232:233] offset:36928
	ds_write_b64 v222, v[234:235] offset:36960
	ds_read_b128 v[228:231], v224 offset:36864
	ds_read_b128 v[232:235], v224 offset:37008
	s_waitcnt lgkmcnt(1)
	global_store_dwordx4 v[236:237], v[228:231], off
	s_waitcnt lgkmcnt(0)
	global_store_dwordx4 v[236:237], v[232:235], off offset:256
	v_pk_fma_f32 v[162:163], v[64:65], v[202:203], v[160:161] op_sel_hi:[1,0,1]
	v_pk_fma_f32 v[164:165], v[62:63], v[202:203], v[158:159] op_sel_hi:[1,0,1]
	v_mul_f32_e32 v171, v163, v163
	v_mul_f32_e32 v170, v165, v165
	v_pk_fma_f32 v[166:167], v[60:61], v[202:203], v[156:157] op_sel_hi:[1,0,1]
	v_pk_fma_f32 v[168:169], v[58:59], v[202:203], v[154:155] op_sel_hi:[1,0,1]
	v_fmac_f32_e32 v170, v164, v164
	v_fmac_f32_e32 v171, v162, v162
	v_add_f32_e32 v170, v170, v171
	v_mul_f32_e32 v171, v169, v169
	v_mul_f32_e32 v172, v167, v167
	v_fmac_f32_e32 v171, v168, v168
	v_fmac_f32_e32 v172, v166, v166
	v_pk_fma_f32 v[174:175], v[56:57], v[202:203], v[152:153] op_sel_hi:[1,0,1]
	v_pk_fma_f32 v[176:177], v[54:55], v[202:203], v[150:151] op_sel_hi:[1,0,1]
	v_add_f32_e32 v171, v171, v172
	v_add_f32_e32 v170, v170, v171
	v_mul_f32_e32 v171, v177, v177
	v_mul_f32_e32 v172, v175, v175
	v_fmac_f32_e32 v171, v176, v176
	v_fmac_f32_e32 v172, v174, v174
	v_pk_fma_f32 v[206:207], v[52:53], v[202:203], v[148:149] op_sel_hi:[1,0,1]
	v_pk_fma_f32 v[224:225], v[50:51], v[202:203], v[146:147] op_sel_hi:[1,0,1]
	v_add_f32_e32 v171, v171, v172
	v_add_f32_e32 v170, v171, v170
	v_mul_f32_e32 v171, v225, v225
	v_mul_f32_e32 v172, v207, v207
	v_fmac_f32_e32 v171, v224, v224
	v_fmac_f32_e32 v172, v206, v206
	v_add_f32_e32 v171, v171, v172
	v_add_f32_e32 v170, v171, v170
	v_mov_b32_e32 v171, v170
	s_nop 1
	v_permlane16_swap_b32_e32 v170, v171
	v_add_f32_e32 v170, v170, v171
	v_mov_b32_e32 v171, v170
	s_nop 1
	v_permlane32_swap_b32_e32 v170, v171
	v_add_f32_e32 v170, v170, v171
	v_fmamk_f32 v170, v170, 0x3c800000, v223
	v_rsq_f32_e32 v222, v170
	v_mov_b64_e32 v[202:203], v[192:193]
	v_mov_b64_e32 v[204:205], v[194:195]
	s_and_b64 vcc, exec, s[44:45]
	v_pk_mul_f32 v[164:165], v[164:165], v[222:223] op_sel_hi:[1,0]
	v_pk_mul_f32 v[162:163], v[162:163], v[222:223] op_sel_hi:[1,0]
	v_pk_mul_f32 v[170:171], v[130:131], v[164:165]
	v_pk_mul_f32 v[172:173], v[132:133], v[162:163]
	v_pk_mul_f32 v[162:163], v[168:169], v[222:223] op_sel_hi:[1,0]
	v_pk_mul_f32 v[164:165], v[166:167], v[222:223] op_sel_hi:[1,0]
	v_pk_mul_f32 v[166:167], v[134:135], v[162:163]
	v_pk_mul_f32 v[168:169], v[136:137], v[164:165]
	v_pk_mul_f32 v[162:163], v[176:177], v[222:223] op_sel_hi:[1,0]
	v_pk_mul_f32 v[164:165], v[174:175], v[222:223] op_sel_hi:[1,0]
	v_pk_mul_f32 v[174:175], v[224:225], v[222:223] op_sel_hi:[1,0]
	v_pk_mul_f32 v[176:177], v[206:207], v[222:223] op_sel_hi:[1,0]
	v_pk_mul_f32 v[164:165], v[140:141], v[164:165]
	v_pk_mul_f32 v[162:163], v[138:139], v[162:163]
	v_pk_mul_f32 v[176:177], v[144:145], v[176:177]
	v_pk_mul_f32 v[174:175], v[142:143], v[174:175]
	s_cbranch_vccnz .LBB0_644
	v_add_u32_e32 v206, 0x80, v216
	v_ashrrev_i32_e32 v206, 6, v206
	v_cvt_f32_i32_e32 v222, v206
	v_mul_f32_e32 v206, v220, v222
	v_mul_f32_e32 v207, v219, v222
	v_floor_f32_e32 v206, v206
	v_floor_f32_e32 v207, v207
	v_fma_f32 v224, v220, v222, -v206
	v_fma_f32 v225, v219, v222, -v207
	v_sin_f32_e32 v206, v224
	v_cos_f32_e32 v224, v224
	v_sin_f32_e32 v207, v225
	v_cos_f32_e32 v225, v225
	v_mul_f32_e32 v228, v218, v222
	v_floor_f32_e32 v228, v228
	v_fma_f32 v228, v218, v222, -v228
	v_cos_f32_e32 v231, v228
	v_sin_f32_e32 v233, v228
	v_pk_mul_f32 v[228:229], v[206:207], v[166:167]
	v_pk_mul_f32 v[166:167], v[224:225], v[166:167]
	v_mul_f32_e32 v234, v197, v222
	v_floor_f32_e32 v234, v234
	v_pk_fma_f32 v[224:225], v[224:225], v[170:171], v[228:229] neg_lo:[0,0,1] neg_hi:[0,0,1]
	v_pk_fma_f32 v[166:167], v[206:207], v[170:171], v[166:167]
	v_floor_f32_e32 v170, v201
	v_fma_f32 v222, v197, v222, -v234
	v_fma_f32 v171, v220, v199, -v170
	v_sin_f32_e32 v235, v222
	v_cos_f32_e32 v234, v222
	v_sin_f32_e32 v170, v171
	v_cos_f32_e32 v206, v171
	v_floor_f32_e32 v171, v239
	v_fma_f32 v201, v219, v199, -v171
	v_sin_f32_e32 v171, v201
	v_cos_f32_e32 v207, v201
	v_floor_f32_e32 v201, v221
	v_mul_f32_e32 v232, v233, v168
	v_mul_f32_e32 v250, v231, v168
	v_mov_b32_e32 v168, v173
	v_fma_f32 v201, v218, v199, -v201
	v_floor_f32_e32 v222, v240
	v_mul_f32_e32 v230, v231, v172
	v_mul_f32_e32 v236, v233, v172
	v_pk_mul_f32 v[172:173], v[234:235], v[168:169]
	v_cos_f32_e32 v221, v201
	v_sin_f32_e32 v201, v201
	v_fma_f32 v199, v197, v199, -v222
	v_mov_b32_e32 v231, v172
	v_mov_b32_e32 v233, v173
	v_mov_b32_e32 v172, v235
	v_mov_b32_e32 v173, v234
	v_sin_f32_e32 v235, v199
	v_cos_f32_e32 v234, v199
	v_pk_mul_f32 v[168:169], v[172:173], v[168:169]
	v_pk_add_f32 v[172:173], v[230:231], v[232:233] neg_lo:[0,1] neg_hi:[0,1]
	v_mov_b32_e32 v237, v168
	v_mov_b32_e32 v251, v169
	v_mul_f32_e32 v232, v201, v176
	v_mul_f32_e32 v238, v221, v176
	v_mov_b32_e32 v176, v165
	v_pk_add_f32 v[168:169], v[236:237], v[250:251]
	v_mul_f32_e32 v230, v221, v164
	v_mul_f32_e32 v236, v201, v164
	v_pk_mul_f32 v[164:165], v[234:235], v[176:177]
	v_pk_mul_f32 v[228:229], v[170:171], v[174:175]
	v_mov_b32_e32 v231, v164
	v_mov_b32_e32 v233, v165
	v_mov_b32_e32 v164, v235
	v_mov_b32_e32 v165, v234
	v_pk_mul_f32 v[164:165], v[164:165], v[176:177]
	v_pk_mul_f32 v[174:175], v[206:207], v[174:175]
	v_mov_b32_e32 v237, v164
	v_mov_b32_e32 v239, v165
	v_pk_fma_f32 v[206:207], v[206:207], v[162:163], v[228:229] neg_lo:[0,0,1] neg_hi:[0,0,1]
	v_pk_add_f32 v[164:165], v[230:231], v[232:233] neg_lo:[0,1] neg_hi:[0,1]
	v_pk_fma_f32 v[174:175], v[170:171], v[162:163], v[174:175]
	v_pk_add_f32 v[176:177], v[236:237], v[238:239]
	v_mov_b32_e32 v170, v224
	v_mov_b32_e32 v171, v225
	v_mov_b32_e32 v162, v206
	v_mov_b32_e32 v163, v207
.LBB0_644:
	s_and_b64 vcc, exec, s[42:43]
	s_cbranch_vccnz .LBB0_646
	v_add_co_u32_e32 v204, vcc, 0x10000, v204
	s_nop 1
	v_addc_co_u32_e32 v205, vcc, 0, v205, vcc
	v_mbcnt_lo_u32_b32 v228, -1, 0
	v_mbcnt_hi_u32_b32 v228, -1, v228
	v_and_b32_e32 v229, 15, v228
	v_lshrrev_b32_e32 v228, 4, v228
	v_mul_u32_u24_e32 v230, 0x110, v229
	v_lshl_add_u32 v222, v228, 4, v230
	v_add_u32_e32 v222, m0, v222
	v_mul_u32_u24_e32 v230, 0x110, v228
	v_lshl_add_u32 v224, v229, 4, v230
	v_add_u32_e32 v224, m0, v224
	v_sub_u32_e32 v236, v228, v229
	v_mul_i32_i24_e32 v236, 0x1f0, v236
	v_ashrrev_i32_e32 v237, 31, v236
	ds_write_b128 v222, v[170:173]
	ds_write_b128 v222, v[166:169] offset:64
	ds_write_b128 v222, v[162:165] offset:128
	ds_write_b128 v222, v[174:177] offset:192
	v_lshl_add_u64 v[236:237], v[204:205], 0, v[236:237]
	ds_read_b128 v[228:231], v224
	ds_read_b128 v[232:235], v224 offset:1088
	s_waitcnt lgkmcnt(1)
	global_store_dwordx4 v[236:237], v[228:231], off
	s_waitcnt lgkmcnt(0)
	global_store_dwordx4 v[236:237], v[232:235], off offset:2048
	v_add_co_u32_e32 v236, vcc, 0x1000, v236
	s_nop 1
	v_addc_co_u32_e32 v237, vcc, 0, v237, vcc
	ds_read_b128 v[228:231], v224 offset:2176
	ds_read_b128 v[232:235], v224 offset:3264
	s_waitcnt lgkmcnt(1)
	global_store_dwordx4 v[236:237], v[228:231], off
	s_waitcnt lgkmcnt(0)
	global_store_dwordx4 v[236:237], v[232:235], off offset:2048
	s_nop 1
.LBB0_646:
	v_mbcnt_lo_u32_b32 v232, -1, 0
	v_mbcnt_hi_u32_b32 v232, -1, v232
	v_and_b32_e32 v233, 15, v232
	v_lshrrev_b32_e32 v234, 4, v232
	v_mul_u32_u24_e32 v222, 0x90, v233
	v_lshl_add_u32 v222, v234, 3, v222
	v_add_u32_e32 v222, m0, v222
	v_bfe_u32 v235, v232, 3, 1
	v_lshlrev_b32_e32 v235, 3, v235
	v_lshl_add_u32 v235, v234, 1, v235
	v_and_b32_e32 v232, 7, v232
	v_mul_u32_u24_e32 v224, 0x90, v235
	v_lshl_add_u32 v224, v232, 4, v224
	v_add_u32_e32 v224, m0, v224
	v_sub_u32_e32 v235, v235, v233
	v_mul_i32_i24_e32 v236, 0x100, v235
	v_lshl_add_u32 v236, v232, 4, v236
	v_lshlrev_b32_e32 v234, 3, v234
	v_sub_u32_e32 v236, v236, v234
	v_ashrrev_i32_e32 v237, 31, v236
	v_cvt_pk_bf16_f32 v228, v170, v171
	v_cvt_pk_bf16_f32 v229, v172, v173
	v_add_co_u32_e32 v172, vcc, 0x8000, v202
	v_pk_fma_f32 v[204:205], v[36:37], v[200:201], v[148:149] op_sel_hi:[1,0,1]
	s_nop 0
	v_addc_co_u32_e32 v173, vcc, 0, v203, vcc
	v_lshl_add_u64 v[236:237], v[172:173], 0, v[236:237]
	v_cvt_pk_bf16_f32 v230, v166, v167
	v_cvt_pk_bf16_f32 v231, v168, v169
	ds_write_b64 v222, v[228:229] offset:36864
	ds_write_b64 v222, v[230:231] offset:36896
	v_cvt_pk_bf16_f32 v232, v162, v163
	v_cvt_pk_bf16_f32 v233, v164, v165
	s_nop 0
	v_cvt_pk_bf16_f32 v234, v174, v175
	v_cvt_pk_bf16_f32 v235, v176, v177
	ds_write_b64 v222, v[232:233] offset:36928
	ds_write_b64 v222, v[234:235] offset:36960
	ds_read_b128 v[228:231], v224 offset:36864
	ds_read_b128 v[232:235], v224 offset:37008
	s_waitcnt lgkmcnt(1)
	global_store_dwordx4 v[236:237], v[228:231], off
	s_waitcnt lgkmcnt(0)
	global_store_dwordx4 v[236:237], v[232:235], off offset:256
	v_pk_fma_f32 v[162:163], v[48:49], v[200:201], v[160:161] op_sel_hi:[1,0,1]
	v_pk_fma_f32 v[164:165], v[46:47], v[200:201], v[158:159] op_sel_hi:[1,0,1]
	v_mul_f32_e32 v171, v163, v163
	v_mul_f32_e32 v170, v165, v165
	v_pk_fma_f32 v[166:167], v[44:45], v[200:201], v[156:157] op_sel_hi:[1,0,1]
	v_pk_fma_f32 v[168:169], v[42:43], v[200:201], v[154:155] op_sel_hi:[1,0,1]
	v_fmac_f32_e32 v170, v164, v164
	v_fmac_f32_e32 v171, v162, v162
	v_add_f32_e32 v170, v170, v171
	v_mul_f32_e32 v171, v169, v169
	v_mul_f32_e32 v172, v167, v167
	v_fmac_f32_e32 v171, v168, v168
	v_fmac_f32_e32 v172, v166, v166
	v_pk_fma_f32 v[174:175], v[40:41], v[200:201], v[152:153] op_sel_hi:[1,0,1]
	v_pk_fma_f32 v[176:177], v[38:39], v[200:201], v[150:151] op_sel_hi:[1,0,1]
	v_add_f32_e32 v171, v171, v172
	v_add_f32_e32 v170, v170, v171
	v_mul_f32_e32 v171, v177, v177
	v_mul_f32_e32 v172, v175, v175
	v_fmac_f32_e32 v171, v176, v176
	v_fmac_f32_e32 v172, v174, v174
	v_pk_fma_f32 v[206:207], v[34:35], v[200:201], v[146:147] op_sel_hi:[1,0,1]
	v_add_f32_e32 v171, v171, v172
	v_add_f32_e32 v170, v171, v170
	v_mul_f32_e32 v171, v207, v207
	v_mul_f32_e32 v172, v205, v205
	v_fmac_f32_e32 v171, v206, v206
	v_fmac_f32_e32 v172, v204, v204
	v_add_f32_e32 v171, v171, v172
	v_add_f32_e32 v170, v171, v170
	v_mov_b32_e32 v171, v170
	s_nop 1
	v_permlane16_swap_b32_e32 v170, v171
	v_add_f32_e32 v170, v170, v171
	v_mov_b32_e32 v171, v170
	s_nop 1
	v_permlane32_swap_b32_e32 v170, v171
	v_add_f32_e32 v170, v170, v171
	v_fmamk_f32 v170, v170, 0x3c800000, v223
	v_rsq_f32_e32 v222, v170
	v_mov_b64_e32 v[202:203], v[194:195]
	v_mov_b64_e32 v[200:201], v[192:193]
	s_and_b64 vcc, exec, s[44:45]
	v_pk_mul_f32 v[164:165], v[164:165], v[222:223] op_sel_hi:[1,0]
	v_pk_mul_f32 v[162:163], v[162:163], v[222:223] op_sel_hi:[1,0]
	v_pk_mul_f32 v[170:171], v[130:131], v[164:165]
	v_pk_mul_f32 v[172:173], v[132:133], v[162:163]
	v_pk_mul_f32 v[162:163], v[168:169], v[222:223] op_sel_hi:[1,0]
	v_pk_mul_f32 v[164:165], v[166:167], v[222:223] op_sel_hi:[1,0]
	v_pk_mul_f32 v[166:167], v[134:135], v[162:163]
	v_pk_mul_f32 v[168:169], v[136:137], v[164:165]
	v_pk_mul_f32 v[162:163], v[176:177], v[222:223] op_sel_hi:[1,0]
	v_pk_mul_f32 v[164:165], v[174:175], v[222:223] op_sel_hi:[1,0]
	v_pk_mul_f32 v[174:175], v[206:207], v[222:223] op_sel_hi:[1,0]
	v_pk_mul_f32 v[176:177], v[204:205], v[222:223] op_sel_hi:[1,0]
	v_pk_mul_f32 v[164:165], v[140:141], v[164:165]
	v_pk_mul_f32 v[162:163], v[138:139], v[162:163]
	v_pk_mul_f32 v[176:177], v[144:145], v[176:177]
	v_pk_mul_f32 v[174:175], v[142:143], v[174:175]
	v_mov_b32_e32 v238, 0xd00000
	v_mov_b32_e32 v239, 0xd05000
	s_cbranch_vccnz .LBB0_648
	v_add_u32_e32 v199, 0x90, v216
	v_ashrrev_i32_e32 v199, 6, v199
	v_cvt_f32_i32_e32 v199, v199
	v_floor_f32_e32 v213, v213
	v_mul_f32_e32 v204, v220, v199
	v_mul_f32_e32 v205, v219, v199
	v_floor_f32_e32 v204, v204
	v_floor_f32_e32 v205, v205
	v_fma_f32 v206, v220, v199, -v204
	v_fma_f32 v207, v219, v199, -v205
	v_sin_f32_e32 v204, v206
	v_cos_f32_e32 v206, v206
	v_sin_f32_e32 v205, v207
	v_cos_f32_e32 v207, v207
	v_mul_f32_e32 v221, v218, v199
	v_floor_f32_e32 v221, v221
	v_pk_mul_f32 v[224:225], v[204:205], v[166:167]
	v_pk_mul_f32 v[166:167], v[206:207], v[166:167]
	v_mul_f32_e32 v229, v197, v199
	v_fma_f32 v221, v218, v199, -v221
	v_floor_f32_e32 v229, v229
	v_pk_fma_f32 v[206:207], v[206:207], v[170:171], v[224:225] neg_lo:[0,0,1] neg_hi:[0,0,1]
	v_pk_fma_f32 v[166:167], v[204:205], v[170:171], v[166:167]
	v_floor_f32_e32 v170, v245
	v_cos_f32_e32 v222, v221
	v_sin_f32_e32 v221, v221
	v_fma_f32 v199, v197, v199, -v229
	v_fma_f32 v171, v220, v212, -v170
	v_sin_f32_e32 v233, v199
	v_cos_f32_e32 v232, v199
	v_sin_f32_e32 v170, v171
	v_cos_f32_e32 v204, v171
	v_floor_f32_e32 v171, v243
	v_fma_f32 v199, v219, v212, -v171
	v_sin_f32_e32 v171, v199
	v_cos_f32_e32 v205, v199
	v_floor_f32_e32 v199, v241
	v_mul_f32_e32 v230, v221, v168
	v_mul_f32_e32 v236, v222, v168
	v_mov_b32_e32 v168, v173
	v_fma_f32 v199, v218, v212, -v199
	v_mul_f32_e32 v228, v222, v172
	v_mul_f32_e32 v234, v221, v172
	v_pk_mul_f32 v[172:173], v[232:233], v[168:169]
	v_cos_f32_e32 v221, v199
	v_sin_f32_e32 v199, v199
	v_fma_f32 v212, v197, v212, -v213
	v_mov_b32_e32 v229, v172
	v_mov_b32_e32 v231, v173
	v_mov_b32_e32 v172, v233
	v_mov_b32_e32 v173, v232
	v_sin_f32_e32 v213, v212
	v_cos_f32_e32 v212, v212
	v_pk_mul_f32 v[168:169], v[172:173], v[168:169]
	v_pk_add_f32 v[172:173], v[228:229], v[230:231] neg_lo:[0,1] neg_hi:[0,1]
	v_mov_b32_e32 v235, v168
	v_mov_b32_e32 v237, v169
	v_pk_add_f32 v[168:169], v[234:235], v[236:237]
	v_mul_f32_e32 v230, v199, v176
	v_mul_f32_e32 v234, v221, v176
	v_mov_b32_e32 v176, v165
	v_mul_f32_e32 v228, v221, v164
	v_mul_f32_e32 v232, v199, v164
	v_pk_mul_f32 v[164:165], v[212:213], v[176:177]
	v_pk_mul_f32 v[224:225], v[170:171], v[174:175]
	v_mov_b32_e32 v229, v164
	v_mov_b32_e32 v231, v165
	v_mov_b32_e32 v164, v213
	v_mov_b32_e32 v165, v212
	v_pk_mul_f32 v[164:165], v[164:165], v[176:177]
	v_pk_mul_f32 v[174:175], v[204:205], v[174:175]
	v_mov_b32_e32 v233, v164
	v_mov_b32_e32 v235, v165
	v_pk_fma_f32 v[204:205], v[204:205], v[162:163], v[224:225] neg_lo:[0,0,1] neg_hi:[0,0,1]
	v_pk_add_f32 v[164:165], v[228:229], v[230:231] neg_lo:[0,1] neg_hi:[0,1]
	v_pk_fma_f32 v[174:175], v[170:171], v[162:163], v[174:175]
	v_pk_add_f32 v[176:177], v[232:233], v[234:235]
	v_mov_b32_e32 v170, v206
	v_mov_b32_e32 v171, v207
	v_mov_b32_e32 v162, v204
	v_mov_b32_e32 v163, v205
.LBB0_648:
	s_and_b64 vcc, exec, s[42:43]
	s_cbranch_vccnz .LBB0_650
	v_add_co_u32_e32 v202, vcc, 0x12000, v202
	s_nop 1
	v_addc_co_u32_e32 v203, vcc, 0, v203, vcc
	v_mbcnt_lo_u32_b32 v228, -1, 0
	v_mbcnt_hi_u32_b32 v228, -1, v228
	v_and_b32_e32 v229, 15, v228
	v_lshrrev_b32_e32 v228, 4, v228
	v_mul_u32_u24_e32 v230, 0x110, v229
	v_lshl_add_u32 v222, v228, 4, v230
	v_add_u32_e32 v222, m0, v222
	v_mul_u32_u24_e32 v230, 0x110, v228
	v_lshl_add_u32 v224, v229, 4, v230
	v_add_u32_e32 v224, m0, v224
	v_sub_u32_e32 v236, v228, v229
	v_mul_i32_i24_e32 v236, 0x1f0, v236
	v_ashrrev_i32_e32 v237, 31, v236
	ds_write_b128 v222, v[170:173]
	ds_write_b128 v222, v[166:169] offset:64
	ds_write_b128 v222, v[162:165] offset:128
	ds_write_b128 v222, v[174:177] offset:192
	v_lshl_add_u64 v[236:237], v[202:203], 0, v[236:237]
	ds_read_b128 v[228:231], v224
	ds_read_b128 v[232:235], v224 offset:1088
	s_waitcnt lgkmcnt(1)
	global_store_dwordx4 v[236:237], v[228:231], off
	s_waitcnt lgkmcnt(0)
	global_store_dwordx4 v[236:237], v[232:235], off offset:2048
	v_add_co_u32_e32 v236, vcc, 0x1000, v236
	s_nop 1
	v_addc_co_u32_e32 v237, vcc, 0, v237, vcc
	ds_read_b128 v[228:231], v224 offset:2176
	ds_read_b128 v[232:235], v224 offset:3264
	s_waitcnt lgkmcnt(1)
	global_store_dwordx4 v[236:237], v[228:231], off
	s_waitcnt lgkmcnt(0)
	global_store_dwordx4 v[236:237], v[232:235], off offset:2048
	s_nop 1
.LBB0_650:
	v_mbcnt_lo_u32_b32 v232, -1, 0
	v_mbcnt_hi_u32_b32 v232, -1, v232
	v_and_b32_e32 v233, 15, v232
	v_lshrrev_b32_e32 v234, 4, v232
	v_mul_u32_u24_e32 v222, 0x90, v233
	v_lshl_add_u32 v222, v234, 3, v222
	v_add_u32_e32 v222, m0, v222
	v_bfe_u32 v235, v232, 3, 1
	v_lshlrev_b32_e32 v235, 3, v235
	v_lshl_add_u32 v235, v234, 1, v235
	v_and_b32_e32 v232, 7, v232
	v_mul_u32_u24_e32 v224, 0x90, v235
	v_lshl_add_u32 v224, v232, 4, v224
	v_add_u32_e32 v224, m0, v224
	v_sub_u32_e32 v235, v235, v233
	v_mul_i32_i24_e32 v236, 0x100, v235
	v_lshl_add_u32 v236, v232, 4, v236
	v_lshlrev_b32_e32 v234, 3, v234
	v_sub_u32_e32 v236, v236, v234
	v_ashrrev_i32_e32 v237, 31, v236
	v_cvt_pk_bf16_f32 v228, v170, v171
	v_cvt_pk_bf16_f32 v229, v172, v173
	v_add_co_u32_e32 v172, vcc, 0x9000, v200
	s_nop 1
	v_addc_co_u32_e32 v173, vcc, 0, v201, vcc
	v_lshl_add_u64 v[236:237], v[172:173], 0, v[236:237]
	v_cvt_pk_bf16_f32 v230, v166, v167
	v_cvt_pk_bf16_f32 v231, v168, v169
	ds_write_b64 v222, v[228:229] offset:36864
	ds_write_b64 v222, v[230:231] offset:36896
	v_cvt_pk_bf16_f32 v232, v162, v163
	v_cvt_pk_bf16_f32 v233, v164, v165
	s_nop 0
	v_cvt_pk_bf16_f32 v234, v174, v175
	v_cvt_pk_bf16_f32 v235, v176, v177
	ds_write_b64 v222, v[232:233] offset:36928
	ds_write_b64 v222, v[234:235] offset:36960
	ds_read_b128 v[228:231], v224 offset:36864
	ds_read_b128 v[232:235], v224 offset:37008
	s_waitcnt lgkmcnt(1)
	global_store_dwordx4 v[236:237], v[228:231], off
	s_waitcnt lgkmcnt(0)
	global_store_dwordx4 v[236:237], v[232:235], off offset:256
	v_pk_fma_f32 v[162:163], v[32:33], v[198:199], v[160:161] op_sel_hi:[1,0,1]
	v_pk_fma_f32 v[164:165], v[30:31], v[198:199], v[158:159] op_sel_hi:[1,0,1]
	v_mul_f32_e32 v171, v163, v163
	v_mul_f32_e32 v170, v165, v165
	v_pk_fma_f32 v[166:167], v[28:29], v[198:199], v[156:157] op_sel_hi:[1,0,1]
	v_pk_fma_f32 v[168:169], v[26:27], v[198:199], v[154:155] op_sel_hi:[1,0,1]
	v_fmac_f32_e32 v170, v164, v164
	v_fmac_f32_e32 v171, v162, v162
	v_add_f32_e32 v170, v170, v171
	v_mul_f32_e32 v171, v169, v169
	v_mul_f32_e32 v172, v167, v167
	v_fmac_f32_e32 v171, v168, v168
	v_fmac_f32_e32 v172, v166, v166
	v_pk_fma_f32 v[202:203], v[24:25], v[198:199], v[152:153] op_sel_hi:[1,0,1]
	v_pk_fma_f32 v[204:205], v[22:23], v[198:199], v[150:151] op_sel_hi:[1,0,1]
	v_add_f32_e32 v171, v171, v172
	v_add_f32_e32 v170, v170, v171
	v_mul_f32_e32 v171, v205, v205
	v_mul_f32_e32 v172, v203, v203
	v_fmac_f32_e32 v171, v204, v204
	v_fmac_f32_e32 v172, v202, v202
	v_pk_fma_f32 v[206:207], v[20:21], v[198:199], v[148:149] op_sel_hi:[1,0,1]
	v_pk_fma_f32 v[212:213], v[18:19], v[198:199], v[146:147] op_sel_hi:[1,0,1]
	v_add_f32_e32 v171, v171, v172
	v_add_f32_e32 v170, v171, v170
	v_mul_f32_e32 v171, v213, v213
	v_mul_f32_e32 v172, v207, v207
	v_fmac_f32_e32 v171, v212, v212
	v_fmac_f32_e32 v172, v206, v206
	v_add_f32_e32 v171, v171, v172
	v_add_f32_e32 v170, v171, v170
	v_mov_b32_e32 v171, v170
	s_nop 1
	v_permlane16_swap_b32_e32 v170, v171
	v_add_f32_e32 v170, v170, v171
	v_mov_b32_e32 v171, v170
	s_nop 1
	v_permlane32_swap_b32_e32 v170, v171
	v_add_f32_e32 v170, v170, v171
	v_fmamk_f32 v170, v170, 0x3c800000, v223
	v_rsq_f32_e32 v222, v170
	v_mov_b64_e32 v[200:201], v[194:195]
	v_mov_b64_e32 v[198:199], v[192:193]
	s_and_b64 vcc, exec, s[44:45]
	v_pk_mul_f32 v[164:165], v[164:165], v[222:223] op_sel_hi:[1,0]
	v_pk_mul_f32 v[162:163], v[162:163], v[222:223] op_sel_hi:[1,0]
	v_pk_mul_f32 v[174:175], v[130:131], v[164:165]
	v_pk_mul_f32 v[176:177], v[132:133], v[162:163]
	v_pk_mul_f32 v[162:163], v[168:169], v[222:223] op_sel_hi:[1,0]
	v_pk_mul_f32 v[164:165], v[166:167], v[222:223] op_sel_hi:[1,0]
	v_pk_mul_f32 v[170:171], v[134:135], v[162:163]
	v_pk_mul_f32 v[172:173], v[136:137], v[164:165]
	v_pk_mul_f32 v[162:163], v[204:205], v[222:223] op_sel_hi:[1,0]
	v_pk_mul_f32 v[164:165], v[202:203], v[222:223] op_sel_hi:[1,0]
	v_pk_mul_f32 v[166:167], v[138:139], v[162:163]
	v_pk_mul_f32 v[168:169], v[140:141], v[164:165]
	v_pk_mul_f32 v[162:163], v[212:213], v[222:223] op_sel_hi:[1,0]
	v_pk_mul_f32 v[164:165], v[206:207], v[222:223] op_sel_hi:[1,0]
	v_pk_mul_f32 v[162:163], v[142:143], v[162:163]
	v_pk_mul_f32 v[164:165], v[144:145], v[164:165]
	s_cbranch_vccnz .LBB0_652
	v_add_u32_e32 v202, 0xa0, v216
	v_ashrrev_i32_e32 v202, 6, v202
	v_cvt_f32_i32_e32 v213, v202
	v_floor_f32_e32 v211, v211
	v_mul_f32_e32 v202, v220, v213
	v_mul_f32_e32 v203, v219, v213
	v_floor_f32_e32 v202, v202
	v_floor_f32_e32 v203, v203
	v_mul_f32_e32 v206, v218, v213
	v_fma_f32 v204, v220, v213, -v202
	v_fma_f32 v205, v219, v213, -v203
	v_floor_f32_e32 v206, v206
	v_mul_f32_e32 v225, v197, v213
	v_sin_f32_e32 v202, v204
	v_cos_f32_e32 v204, v204
	v_sin_f32_e32 v203, v205
	v_cos_f32_e32 v205, v205
	v_fma_f32 v206, v218, v213, -v206
	v_floor_f32_e32 v225, v225
	v_cos_f32_e32 v221, v206
	v_sin_f32_e32 v222, v206
	v_fma_f32 v213, v197, v213, -v225
	v_sin_f32_e32 v229, v213
	v_cos_f32_e32 v228, v213
	v_pk_mul_f32 v[206:207], v[202:203], v[170:171]
	v_pk_mul_f32 v[170:171], v[204:205], v[170:171]
	v_mul_f32_e32 v224, v222, v172
	v_mul_f32_e32 v232, v221, v172
	v_mov_b32_e32 v172, v177
	v_pk_fma_f32 v[204:205], v[204:205], v[174:175], v[206:207] neg_lo:[0,0,1] neg_hi:[0,0,1]
	v_pk_fma_f32 v[170:171], v[202:203], v[174:175], v[170:171]
	v_floor_f32_e32 v174, v247
	v_mul_f32_e32 v212, v221, v176
	v_mul_f32_e32 v230, v222, v176
	v_pk_mul_f32 v[176:177], v[228:229], v[172:173]
	v_fma_f32 v175, v220, v210, -v174
	v_floor_f32_e32 v206, v242
	v_mov_b32_e32 v213, v176
	v_mov_b32_e32 v225, v177
	v_mov_b32_e32 v176, v229
	v_mov_b32_e32 v177, v228
	v_sin_f32_e32 v174, v175
	v_cos_f32_e32 v202, v175
	v_floor_f32_e32 v175, v246
	v_fma_f32 v206, v218, v210, -v206
	v_pk_mul_f32 v[172:173], v[176:177], v[172:173]
	v_pk_add_f32 v[176:177], v[212:213], v[224:225] neg_lo:[0,1] neg_hi:[0,1]
	v_fma_f32 v203, v219, v210, -v175
	v_cos_f32_e32 v213, v206
	v_sin_f32_e32 v221, v206
	v_fma_f32 v210, v197, v210, -v211
	v_sin_f32_e32 v211, v210
	v_cos_f32_e32 v210, v210
	v_mov_b32_e32 v231, v172
	v_mov_b32_e32 v233, v173
	v_sin_f32_e32 v175, v203
	v_pk_add_f32 v[172:173], v[230:231], v[232:233]
	v_cos_f32_e32 v203, v203
	v_mul_f32_e32 v224, v221, v164
	v_mul_f32_e32 v230, v213, v164
	v_mov_b32_e32 v164, v169
	v_mul_f32_e32 v212, v213, v168
	v_mul_f32_e32 v228, v221, v168
	v_pk_mul_f32 v[168:169], v[210:211], v[164:165]
	v_pk_mul_f32 v[206:207], v[174:175], v[162:163]
	v_mov_b32_e32 v213, v168
	v_mov_b32_e32 v225, v169
	v_mov_b32_e32 v168, v211
	v_mov_b32_e32 v169, v210
	v_pk_mul_f32 v[164:165], v[168:169], v[164:165]
	v_pk_mul_f32 v[162:163], v[202:203], v[162:163]
	v_mov_b32_e32 v229, v164
	v_mov_b32_e32 v231, v165
	v_pk_fma_f32 v[202:203], v[202:203], v[166:167], v[206:207] neg_lo:[0,0,1] neg_hi:[0,0,1]
	v_pk_add_f32 v[168:169], v[212:213], v[224:225] neg_lo:[0,1] neg_hi:[0,1]
	v_pk_fma_f32 v[162:163], v[174:175], v[166:167], v[162:163]
	v_pk_add_f32 v[164:165], v[228:229], v[230:231]
	v_mov_b32_e32 v174, v204
	v_mov_b32_e32 v175, v205
	v_mov_b32_e32 v166, v202
	v_mov_b32_e32 v167, v203
.LBB0_652:
	s_and_b64 vcc, exec, s[42:43]
	v_mov_b32_e32 v225, v226
	s_cbranch_vccnz .LBB0_654
	v_add_co_u32_e32 v200, vcc, 0x14000, v200
	s_nop 1
	v_addc_co_u32_e32 v201, vcc, 0, v201, vcc
	v_mbcnt_lo_u32_b32 v228, -1, 0
	v_mbcnt_hi_u32_b32 v228, -1, v228
	v_and_b32_e32 v229, 15, v228
	v_lshrrev_b32_e32 v228, 4, v228
	v_mul_u32_u24_e32 v230, 0x110, v229
	v_lshl_add_u32 v222, v228, 4, v230
	v_add_u32_e32 v222, m0, v222
	v_mul_u32_u24_e32 v230, 0x110, v228
	v_lshl_add_u32 v224, v229, 4, v230
	v_add_u32_e32 v224, m0, v224
	v_sub_u32_e32 v236, v228, v229
	v_mul_i32_i24_e32 v236, 0x1f0, v236
	v_ashrrev_i32_e32 v237, 31, v236
	ds_write_b128 v222, v[174:177]
	ds_write_b128 v222, v[170:173] offset:64
	ds_write_b128 v222, v[166:169] offset:128
	ds_write_b128 v222, v[162:165] offset:192
	v_lshl_add_u64 v[236:237], v[200:201], 0, v[236:237]
	ds_read_b128 v[228:231], v224
	ds_read_b128 v[232:235], v224 offset:1088
	s_waitcnt lgkmcnt(1)
	global_store_dwordx4 v[236:237], v[228:231], off
	s_waitcnt lgkmcnt(0)
	global_store_dwordx4 v[236:237], v[232:235], off offset:2048
	v_add_co_u32_e32 v236, vcc, 0x1000, v236
	s_nop 1
	v_addc_co_u32_e32 v237, vcc, 0, v237, vcc
	ds_read_b128 v[228:231], v224 offset:2176
	ds_read_b128 v[232:235], v224 offset:3264
	s_waitcnt lgkmcnt(1)
	global_store_dwordx4 v[236:237], v[228:231], off
	s_waitcnt lgkmcnt(0)
	global_store_dwordx4 v[236:237], v[232:235], off offset:2048
	s_nop 1
.LBB0_654:
	v_mbcnt_lo_u32_b32 v232, -1, 0
	v_mbcnt_hi_u32_b32 v232, -1, v232
	v_and_b32_e32 v233, 15, v232
	v_lshrrev_b32_e32 v234, 4, v232
	v_mul_u32_u24_e32 v222, 0x90, v233
	v_lshl_add_u32 v222, v234, 3, v222
	v_add_u32_e32 v222, m0, v222
	v_bfe_u32 v235, v232, 3, 1
	v_lshlrev_b32_e32 v235, 3, v235
	v_lshl_add_u32 v235, v234, 1, v235
	v_and_b32_e32 v232, 7, v232
	v_mul_u32_u24_e32 v224, 0x90, v235
	v_lshl_add_u32 v224, v232, 4, v224
	v_add_u32_e32 v224, m0, v224
	v_sub_u32_e32 v235, v235, v233
	v_mul_i32_i24_e32 v236, 0x100, v235
	v_lshl_add_u32 v236, v232, 4, v236
	v_lshlrev_b32_e32 v234, 3, v234
	v_sub_u32_e32 v236, v236, v234
	v_ashrrev_i32_e32 v237, 31, v236
	v_cvt_pk_bf16_f32 v228, v174, v175
	v_cvt_pk_bf16_f32 v229, v176, v177
	v_add_co_u32_e32 v176, vcc, 0xa000, v198
	v_pk_fma_f32 v[160:161], v[16:17], v[196:197], v[160:161] op_sel_hi:[1,0,1]
	s_nop 0
	v_addc_co_u32_e32 v177, vcc, 0, v199, vcc
	v_pk_fma_f32 v[158:159], v[14:15], v[196:197], v[158:159] op_sel_hi:[1,0,1]
	v_lshl_add_u64 v[236:237], v[176:177], 0, v[236:237]
	v_cvt_pk_bf16_f32 v230, v170, v171
	v_cvt_pk_bf16_f32 v231, v172, v173
	ds_write_b64 v222, v[228:229] offset:36864
	ds_write_b64 v222, v[230:231] offset:36896
	v_cvt_pk_bf16_f32 v232, v166, v167
	v_cvt_pk_bf16_f32 v233, v168, v169
	v_pk_fma_f32 v[168:169], v[2:3], v[196:197], v[146:147] op_sel_hi:[1,0,1]
	v_mul_f32_e32 v146, v159, v159
	v_mul_f32_e32 v147, v161, v161
	v_pk_fma_f32 v[156:157], v[12:13], v[196:197], v[156:157] op_sel_hi:[1,0,1]
	v_pk_fma_f32 v[154:155], v[10:11], v[196:197], v[154:155] op_sel_hi:[1,0,1]
	v_fmac_f32_e32 v146, v158, v158
	v_fmac_f32_e32 v147, v160, v160
	s_nop 0
	v_pk_fma_f32 v[166:167], v[4:5], v[196:197], v[148:149] op_sel_hi:[1,0,1]
	v_add_f32_e32 v146, v146, v147
	v_mul_f32_e32 v147, v155, v155
	v_mul_f32_e32 v148, v157, v157
	v_fmac_f32_e32 v147, v154, v154
	v_fmac_f32_e32 v148, v156, v156
	v_pk_fma_f32 v[152:153], v[8:9], v[196:197], v[152:153] op_sel_hi:[1,0,1]
	v_pk_fma_f32 v[150:151], v[6:7], v[196:197], v[150:151] op_sel_hi:[1,0,1]
	v_add_f32_e32 v147, v147, v148
	v_add_f32_e32 v146, v146, v147
	v_mul_f32_e32 v147, v151, v151
	v_mul_f32_e32 v148, v153, v153
	v_fmac_f32_e32 v147, v150, v150
	v_fmac_f32_e32 v148, v152, v152
	v_add_f32_e32 v147, v147, v148
	v_add_f32_e32 v146, v147, v146
	v_mul_f32_e32 v147, v169, v169
	v_mul_f32_e32 v148, v167, v167
	v_fmac_f32_e32 v147, v168, v168
	v_fmac_f32_e32 v148, v166, v166
	v_add_f32_e32 v147, v147, v148
	v_add_f32_e32 v146, v147, v146
	v_mov_b32_e32 v147, v146
	s_nop 1
	v_permlane16_swap_b32_e32 v146, v147
	v_add_f32_e32 v146, v146, v147
	v_mov_b32_e32 v147, v146
	s_nop 1
	v_permlane32_swap_b32_e32 v146, v147
	v_add_f32_e32 v146, v146, v147
	v_fmamk_f32 v146, v146, 0x3c800000, v223
	v_rsq_f32_e32 v170, v146
	s_and_b64 vcc, exec, s[44:45]
	v_mov_b32_e32 v226, 0x260
	v_cvt_pk_bf16_f32 v234, v162, v163
	v_pk_mul_f32 v[146:147], v[158:159], v[170:171] op_sel_hi:[1,0]
	v_pk_mul_f32 v[148:149], v[160:161], v[170:171] op_sel_hi:[1,0]
	v_pk_mul_f32 v[146:147], v[130:131], v[146:147]
	v_pk_mul_f32 v[148:149], v[132:133], v[148:149]
	v_pk_mul_f32 v[130:131], v[154:155], v[170:171] op_sel_hi:[1,0]
	v_pk_mul_f32 v[132:133], v[156:157], v[170:171] op_sel_hi:[1,0]
	v_pk_mul_f32 v[134:135], v[134:135], v[130:131]
	v_pk_mul_f32 v[136:137], v[136:137], v[132:133]
	v_pk_mul_f32 v[130:131], v[150:151], v[170:171] op_sel_hi:[1,0]
	v_pk_mul_f32 v[132:133], v[152:153], v[170:171] op_sel_hi:[1,0]
	v_pk_mul_f32 v[130:131], v[138:139], v[130:131]
	v_pk_mul_f32 v[132:133], v[140:141], v[132:133]
	v_pk_mul_f32 v[138:139], v[168:169], v[170:171] op_sel_hi:[1,0]
	v_pk_mul_f32 v[140:141], v[166:167], v[170:171] op_sel_hi:[1,0]
	v_pk_mul_f32 v[138:139], v[142:143], v[138:139]
	v_pk_mul_f32 v[140:141], v[144:145], v[140:141]
	v_cvt_pk_bf16_f32 v235, v164, v165
	ds_write_b64 v222, v[232:233] offset:36928
	ds_write_b64 v222, v[234:235] offset:36960
	ds_read_b128 v[228:231], v224 offset:36864
	ds_read_b128 v[232:235], v224 offset:37008
	s_waitcnt lgkmcnt(1)
	global_store_dwordx4 v[236:237], v[228:231], off
	s_waitcnt lgkmcnt(0)
	global_store_dwordx4 v[236:237], v[232:235], off offset:256
	s_cbranch_vccnz .LBB0_656
	v_add_u32_e32 v142, 0xb0, v216
	v_ashrrev_i32_e32 v142, 6, v142
	v_cvt_f32_i32_e32 v153, v142
	v_mul_f32_e32 v142, v220, v153
	v_mul_f32_e32 v143, v219, v153
	v_mul_f32_e32 v150, v218, v153
	v_floor_f32_e32 v142, v142
	v_floor_f32_e32 v143, v143
	v_floor_f32_e32 v150, v150
	v_mul_f32_e32 v156, v197, v153
	v_fma_f32 v144, v220, v153, -v142
	v_fma_f32 v145, v219, v153, -v143
	v_fma_f32 v150, v218, v153, -v150
	v_floor_f32_e32 v156, v156
	v_sin_f32_e32 v142, v144
	v_sin_f32_e32 v143, v145
	v_cos_f32_e32 v155, v150
	v_sin_f32_e32 v158, v150
	v_fma_f32 v153, v197, v153, -v156
	v_cos_f32_e32 v144, v144
	v_cos_f32_e32 v145, v145
	v_sin_f32_e32 v157, v153
	v_cos_f32_e32 v156, v153
	v_pk_mul_f32 v[150:151], v[142:143], v[134:135]
	v_mul_f32_e32 v154, v158, v136
	v_mul_f32_e32 v160, v155, v136
	v_mov_b32_e32 v136, v149
	v_pk_mul_f32 v[134:135], v[144:145], v[134:135]
	v_mul_f32_e32 v152, v155, v148
	v_mul_f32_e32 v158, v158, v148
	v_pk_mul_f32 v[148:149], v[156:157], v[136:137]
	v_pk_fma_f32 v[144:145], v[144:145], v[146:147], v[150:151] neg_lo:[0,0,1] neg_hi:[0,0,1]
	v_floor_f32_e32 v150, v244
	v_mov_b32_e32 v153, v148
	v_mov_b32_e32 v155, v149
	v_mov_b32_e32 v148, v157
	v_mov_b32_e32 v149, v156
	v_pk_fma_f32 v[134:135], v[142:143], v[146:147], v[134:135]
	v_floor_f32_e32 v142, v249
	v_fma_f32 v150, v218, v208, -v150
	v_floor_f32_e32 v156, v209
	v_pk_mul_f32 v[136:137], v[148:149], v[136:137]
	v_pk_add_f32 v[148:149], v[152:153], v[154:155] neg_lo:[0,1] neg_hi:[0,1]
	v_fma_f32 v143, v220, v208, -v142
	v_cos_f32_e32 v153, v150
	v_sin_f32_e32 v155, v150
	v_fma_f32 v156, v197, v208, -v156
	v_sin_f32_e32 v142, v143
	v_cos_f32_e32 v146, v143
	v_floor_f32_e32 v143, v248
	v_sin_f32_e32 v157, v156
	v_cos_f32_e32 v156, v156
	v_fma_f32 v147, v219, v208, -v143
	v_mov_b32_e32 v159, v136
	v_mov_b32_e32 v161, v137
	v_sin_f32_e32 v143, v147
	v_pk_add_f32 v[136:137], v[158:159], v[160:161]
	v_cos_f32_e32 v147, v147
	v_mul_f32_e32 v154, v155, v140
	v_mul_f32_e32 v160, v153, v140
	v_mov_b32_e32 v140, v133
	v_mul_f32_e32 v152, v153, v132
	v_mul_f32_e32 v158, v155, v132
	v_pk_mul_f32 v[132:133], v[156:157], v[140:141]
	v_pk_mul_f32 v[150:151], v[142:143], v[138:139]
	v_mov_b32_e32 v153, v132
	v_mov_b32_e32 v155, v133
	v_mov_b32_e32 v132, v157
	v_mov_b32_e32 v133, v156
	v_pk_mul_f32 v[132:133], v[132:133], v[140:141]
	v_pk_mul_f32 v[138:139], v[146:147], v[138:139]
	v_mov_b32_e32 v159, v132
	v_mov_b32_e32 v161, v133
	v_pk_fma_f32 v[150:151], v[146:147], v[130:131], v[150:151] neg_lo:[0,0,1] neg_hi:[0,0,1]
	v_pk_add_f32 v[132:133], v[152:153], v[154:155] neg_lo:[0,1] neg_hi:[0,1]
	v_pk_fma_f32 v[138:139], v[142:143], v[130:131], v[138:139]
	v_pk_add_f32 v[140:141], v[158:159], v[160:161]
	v_mov_b32_e32 v146, v144
	v_mov_b32_e32 v147, v145
	v_mov_b32_e32 v130, v150
	v_mov_b32_e32 v131, v151
.LBB0_656:
	s_and_b64 vcc, exec, s[42:43]
	s_cbranch_vccnz .LBB0_658
	v_add_co_u32_e32 v142, vcc, 0x16000, v194
	s_nop 1
	v_addc_co_u32_e32 v143, vcc, 0, v195, vcc
	v_mbcnt_lo_u32_b32 v228, -1, 0
	v_mbcnt_hi_u32_b32 v228, -1, v228
	v_and_b32_e32 v229, 15, v228
	v_lshrrev_b32_e32 v228, 4, v228
	v_mul_u32_u24_e32 v230, 0x110, v229
	v_lshl_add_u32 v222, v228, 4, v230
	v_add_u32_e32 v222, m0, v222
	v_mul_u32_u24_e32 v230, 0x110, v228
	v_lshl_add_u32 v224, v229, 4, v230
	v_add_u32_e32 v224, m0, v224
	v_sub_u32_e32 v236, v228, v229
	v_mul_i32_i24_e32 v236, 0x1f0, v236
	v_ashrrev_i32_e32 v237, 31, v236
	ds_write_b128 v222, v[146:149]
	ds_write_b128 v222, v[134:137] offset:64
	ds_write_b128 v222, v[130:133] offset:128
	ds_write_b128 v222, v[138:141] offset:192
	v_lshl_add_u64 v[236:237], v[142:143], 0, v[236:237]
	ds_read_b128 v[228:231], v224
	ds_read_b128 v[232:235], v224 offset:1088
	s_waitcnt lgkmcnt(1)
	global_store_dwordx4 v[236:237], v[228:231], off
	s_waitcnt lgkmcnt(0)
	global_store_dwordx4 v[236:237], v[232:235], off offset:2048
	v_add_co_u32_e32 v236, vcc, 0x1000, v236
	s_nop 1
	v_addc_co_u32_e32 v237, vcc, 0, v237, vcc
	ds_read_b128 v[228:231], v224 offset:2176
	ds_read_b128 v[232:235], v224 offset:3264
	s_waitcnt lgkmcnt(1)
	global_store_dwordx4 v[236:237], v[228:231], off
	s_waitcnt lgkmcnt(0)
	global_store_dwordx4 v[236:237], v[232:235], off offset:2048
	s_nop 1
.LBB0_658:
	v_add_co_u32_e32 v144, vcc, 0xb000, v192
	v_mbcnt_lo_u32_b32 v232, -1, 0
	v_mbcnt_hi_u32_b32 v232, -1, v232
	v_and_b32_e32 v233, 15, v232
	v_lshrrev_b32_e32 v234, 4, v232
	v_mul_u32_u24_e32 v222, 0x90, v233
	v_lshl_add_u32 v222, v234, 3, v222
	v_add_u32_e32 v222, m0, v222
	v_bfe_u32 v235, v232, 3, 1
	v_lshlrev_b32_e32 v235, 3, v235
	v_lshl_add_u32 v235, v234, 1, v235
	v_and_b32_e32 v232, 7, v232
	v_mul_u32_u24_e32 v224, 0x90, v235
	v_lshl_add_u32 v224, v232, 4, v224
	v_add_u32_e32 v224, m0, v224
	v_sub_u32_e32 v235, v235, v233
	v_mul_i32_i24_e32 v236, 0x100, v235
	v_lshl_add_u32 v236, v232, 4, v236
	v_lshlrev_b32_e32 v234, 3, v234
	v_sub_u32_e32 v236, v236, v234
	v_ashrrev_i32_e32 v237, 31, v236
	v_cvt_pk_bf16_f32 v228, v146, v147
	v_cvt_pk_bf16_f32 v229, v148, v149
	s_nop 1
	v_addc_co_u32_e32 v145, vcc, 0, v193, vcc
	v_lshl_add_u64 v[236:237], v[144:145], 0, v[236:237]
	v_cvt_pk_bf16_f32 v230, v134, v135
	v_cvt_pk_bf16_f32 v231, v136, v137
	ds_write_b64 v222, v[228:229] offset:36864
	ds_write_b64 v222, v[230:231] offset:36896
	v_cvt_pk_bf16_f32 v232, v130, v131
	v_cvt_pk_bf16_f32 v233, v132, v133
	s_nop 0
	v_cvt_pk_bf16_f32 v234, v138, v139
	v_cvt_pk_bf16_f32 v235, v140, v141
	ds_write_b64 v222, v[232:233] offset:36928
	ds_write_b64 v222, v[234:235] offset:36960
	ds_read_b128 v[228:231], v224 offset:36864
	ds_read_b128 v[232:235], v224 offset:37008
	s_waitcnt lgkmcnt(1)
	global_store_dwordx4 v[236:237], v[228:231], off
	s_waitcnt lgkmcnt(0)
	global_store_dwordx4 v[236:237], v[232:235], off offset:256

.LBB0_662:
	v_pk_mul_f32 v[120:121], v[120:121], s[12:13] op_sel_hi:[1,0]
	v_pk_mul_f32 v[128:129], v[128:129], s[12:13] op_sel_hi:[1,0]
	v_pk_mul_f32 v[116:117], v[116:117], s[12:13] op_sel_hi:[1,0]
	v_pk_mul_f32 v[126:127], v[126:127], s[12:13] op_sel_hi:[1,0]
	v_mbcnt_lo_u32_b32 v232, -1, 0
	v_mbcnt_hi_u32_b32 v232, -1, v232
	v_and_b32_e32 v233, 15, v232
	v_lshrrev_b32_e32 v234, 4, v232
	v_mul_u32_u24_e32 v222, 0x90, v233
	v_lshl_add_u32 v222, v234, 3, v222
	v_add_u32_e32 v222, m0, v222
	v_bfe_u32 v235, v232, 3, 1
	v_lshlrev_b32_e32 v235, 3, v235
	v_lshl_add_u32 v235, v234, 1, v235
	v_and_b32_e32 v232, 7, v232
	v_mul_u32_u24_e32 v224, 0x90, v235
	v_lshl_add_u32 v224, v232, 4, v224
	v_add_u32_e32 v224, m0, v224
	v_sub_u32_e32 v235, v235, v233
	v_mul_i32_i24_e32 v236, 0x400, v235
	v_lshl_add_u32 v236, v232, 4, v236
	v_lshlrev_b32_e32 v234, 3, v234
	v_sub_u32_e32 v236, v236, v234
	v_ashrrev_i32_e32 v237, 31, v236
	v_cvt_pk_bf16_f32 v228, v128, v129
	v_cvt_pk_bf16_f32 v229, v120, v121
	v_lshl_add_u64 v[236:237], v[186:187], 0, v[236:237]
	v_cvt_pk_bf16_f32 v230, v126, v127
	v_cvt_pk_bf16_f32 v231, v116, v117
	v_pk_fma_f32 v[112:113], v[112:113], v[176:177], v[160:161] op_sel_hi:[1,0,1]
	v_pk_fma_f32 v[110:111], v[110:111], v[176:177], v[158:159] op_sel_hi:[1,0,1]
	ds_write_b64 v222, v[228:229] offset:36864
	ds_write_b64 v222, v[230:231] offset:36896
	v_pk_fma_f32 v[120:121], v[98:99], v[176:177], v[146:147] op_sel_hi:[1,0,1]
	v_mul_f32_e32 v98, v111, v111
	v_mul_f32_e32 v99, v113, v113
	v_pk_mul_f32 v[118:119], v[118:119], s[12:13] op_sel_hi:[1,0]
	v_pk_fma_f32 v[108:109], v[108:109], v[176:177], v[156:157] op_sel_hi:[1,0,1]
	v_pk_fma_f32 v[106:107], v[106:107], v[176:177], v[154:155] op_sel_hi:[1,0,1]
	v_fmac_f32_e32 v98, v110, v110
	v_fmac_f32_e32 v99, v112, v112
	v_pk_mul_f32 v[122:123], v[122:123], s[12:13] op_sel_hi:[1,0]
	v_add_f32_e32 v98, v98, v99
	v_cvt_pk_bf16_f32 v232, v122, v123
	v_cvt_pk_bf16_f32 v233, v118, v119
	v_pk_fma_f32 v[118:119], v[100:101], v[176:177], v[148:149] op_sel_hi:[1,0,1]
	v_mul_f32_e32 v99, v107, v107
	v_mul_f32_e32 v100, v109, v109
	v_pk_mul_f32 v[114:115], v[114:115], s[12:13] op_sel_hi:[1,0]
	v_pk_mul_f32 v[124:125], v[124:125], s[12:13] op_sel_hi:[1,0]
	s_nop 0
	v_cvt_pk_bf16_f32 v234, v124, v125
	v_cvt_pk_bf16_f32 v235, v114, v115
	v_fmac_f32_e32 v99, v106, v106
	v_fmac_f32_e32 v100, v108, v108
	ds_write_b64 v222, v[232:233] offset:36928
	ds_write_b64 v222, v[234:235] offset:36960
	ds_read_b128 v[228:231], v224 offset:36864
	ds_read_b128 v[232:235], v224 offset:37008
	s_waitcnt lgkmcnt(1)
	global_store_dwordx4 v[236:237], v[228:231], off
	s_waitcnt lgkmcnt(0)
	global_store_dwordx4 v[236:237], v[232:235], off offset:1024
	v_pk_fma_f32 v[116:117], v[104:105], v[176:177], v[152:153] op_sel_hi:[1,0,1]
	v_pk_fma_f32 v[102:103], v[102:103], v[176:177], v[150:151] op_sel_hi:[1,0,1]
	v_add_f32_e32 v99, v99, v100
	v_add_f32_e32 v98, v98, v99
	v_mul_f32_e32 v99, v103, v103
	v_mul_f32_e32 v100, v117, v117
	v_fmac_f32_e32 v99, v102, v102
	v_fmac_f32_e32 v100, v116, v116
	v_add_f32_e32 v99, v99, v100
	v_add_f32_e32 v98, v98, v99
	v_mul_f32_e32 v99, v121, v121
	v_mul_f32_e32 v100, v119, v119
	v_fmac_f32_e32 v99, v120, v120
	v_fmac_f32_e32 v100, v118, v118
	v_add_f32_e32 v99, v99, v100
	v_add_f32_e32 v98, v98, v99
	v_mov_b32_e32 v99, v98
	s_nop 1
	v_permlane16_swap_b32_e32 v98, v99
	v_add_f32_e32 v98, v98, v99
	v_mov_b32_e32 v99, v98
	s_nop 1
	v_permlane32_swap_b32_e32 v98, v99
	v_add_f32_e32 v98, v98, v99
	v_fmamk_f32 v98, v98, 0x3c800000, v223
	v_rsq_f32_e32 v122, v98
	v_mov_b64_e32 v[100:101], 0
	v_mov_b64_e32 v[98:99], v[162:163]
	v_add_u32_e32 v190, 16, v216
	v_and_b32_e32 v191, 63, v190
	v_pk_mul_f32 v[100:101], v[110:111], v[122:123] op_sel_hi:[1,0]
	v_pk_mul_f32 v[106:107], v[106:107], v[122:123] op_sel_hi:[1,0]
	v_pk_mul_f32 v[102:103], v[102:103], v[122:123] op_sel_hi:[1,0]
	v_pk_mul_f32 v[104:105], v[112:113], v[122:123] op_sel_hi:[1,0]
	v_pk_mul_f32 v[114:115], v[142:143], v[100:101]
	v_pk_mul_f32 v[100:101], v[108:109], v[122:123] op_sel_hi:[1,0]
	v_pk_mul_f32 v[110:111], v[138:139], v[106:107]
	v_pk_mul_f32 v[106:107], v[116:117], v[122:123] op_sel_hi:[1,0]
	v_pk_mul_f32 v[108:109], v[134:135], v[102:103]
	v_pk_mul_f32 v[112:113], v[120:121], v[122:123] op_sel_hi:[1,0]
	v_pk_mul_f32 v[102:103], v[118:119], v[122:123] op_sel_hi:[1,0]
	v_cvt_f32_ubyte0_e32 v116, v191
	v_pk_mul_f32 v[104:105], v[144:145], v[104:105]
	v_pk_mul_f32 v[100:101], v[140:141], v[100:101]
	v_pk_mul_f32 v[106:107], v[136:137], v[106:107]
	v_pk_mul_f32 v[102:103], v[132:133], v[102:103]
	v_pk_mul_f32 v[112:113], v[130:131], v[112:113]
	s_and_b64 vcc, exec, s[42:43]
	v_mul_f32_e32 v120, v0, v116
	v_mul_f32_e32 v119, v165, v116
	v_mul_f32_e32 v118, v167, v116
	v_mul_f32_e32 v117, v169, v116
	s_cbranch_vccnz .LBB0_664
	v_ashrrev_i32_e32 v121, 6, v190
	v_cvt_f32_i32_e32 v121, v121
	v_mul_f32_e32 v122, v0, v121
	v_mul_f32_e32 v123, v165, v121
	v_floor_f32_e32 v122, v122
	v_floor_f32_e32 v123, v123
	v_fma_f32 v124, v0, v121, -v122
	v_fma_f32 v125, v165, v121, -v123
	v_sin_f32_e32 v122, v124
	v_cos_f32_e32 v124, v124
	v_sin_f32_e32 v123, v125
	v_cos_f32_e32 v125, v125
	v_mul_f32_e32 v126, v167, v121
	v_floor_f32_e32 v126, v126
	v_mul_f32_e32 v187, v169, v121
	v_fma_f32 v126, v167, v121, -v126
	v_floor_f32_e32 v187, v187
	v_cos_f32_e32 v129, v126
	v_sin_f32_e32 v176, v126
	v_pk_mul_f32 v[126:127], v[122:123], v[110:111]
	v_pk_mul_f32 v[110:111], v[124:125], v[110:111]
	v_fma_f32 v121, v169, v121, -v187
	v_sin_f32_e32 v191, v121
	v_cos_f32_e32 v190, v121
	v_pk_fma_f32 v[124:125], v[124:125], v[114:115], v[126:127] neg_lo:[0,0,1] neg_hi:[0,0,1]
	v_pk_fma_f32 v[110:111], v[122:123], v[114:115], v[110:111]
	v_floor_f32_e32 v114, v120
	v_fma_f32 v115, v0, v116, -v114
	v_sin_f32_e32 v114, v115
	v_cos_f32_e32 v122, v115
	v_floor_f32_e32 v115, v119
	v_mul_f32_e32 v186, v176, v100
	v_mul_f32_e32 v194, v129, v100
	v_mov_b32_e32 v100, v105
	v_fma_f32 v121, v165, v116, -v115
	v_mul_f32_e32 v128, v129, v104
	v_mul_f32_e32 v192, v176, v104
	v_pk_mul_f32 v[104:105], v[190:191], v[100:101]
	v_sin_f32_e32 v115, v121
	v_cos_f32_e32 v123, v121
	v_floor_f32_e32 v121, v118
	v_mov_b32_e32 v129, v104
	v_mov_b32_e32 v187, v105
	v_mov_b32_e32 v104, v191
	v_mov_b32_e32 v105, v190
	v_fma_f32 v121, v167, v116, -v121
	v_floor_f32_e32 v176, v117
	v_pk_mul_f32 v[100:101], v[104:105], v[100:101]
	v_pk_add_f32 v[104:105], v[128:129], v[186:187] neg_lo:[0,1] neg_hi:[0,1]
	v_cos_f32_e32 v129, v121
	v_sin_f32_e32 v121, v121
	v_fma_f32 v176, v169, v116, -v176
	v_sin_f32_e32 v191, v176
	v_cos_f32_e32 v190, v176
	v_mov_b32_e32 v193, v100
	v_mov_b32_e32 v195, v101
	v_pk_add_f32 v[100:101], v[192:193], v[194:195]
	v_mul_f32_e32 v186, v121, v102
	v_mul_f32_e32 v194, v129, v102
	v_mov_b32_e32 v102, v107
	v_mul_f32_e32 v128, v129, v106
	v_mul_f32_e32 v192, v121, v106
	v_pk_mul_f32 v[106:107], v[190:191], v[102:103]
	v_pk_mul_f32 v[126:127], v[114:115], v[112:113]
	v_mov_b32_e32 v129, v106
	v_mov_b32_e32 v187, v107
	v_mov_b32_e32 v106, v191
	v_mov_b32_e32 v107, v190
	v_pk_mul_f32 v[102:103], v[106:107], v[102:103]
	v_pk_mul_f32 v[112:113], v[122:123], v[112:113]
	v_mov_b32_e32 v193, v102
	v_mov_b32_e32 v195, v103
	v_pk_fma_f32 v[122:123], v[122:123], v[108:109], v[126:127] neg_lo:[0,0,1] neg_hi:[0,0,1]
	v_pk_add_f32 v[106:107], v[128:129], v[186:187] neg_lo:[0,1] neg_hi:[0,1]
	v_pk_fma_f32 v[112:113], v[114:115], v[108:109], v[112:113]
	v_pk_add_f32 v[102:103], v[192:193], v[194:195]
	v_mov_b32_e32 v114, v124
	v_mov_b32_e32 v115, v125
	v_mov_b32_e32 v108, v122
	v_mov_b32_e32 v109, v123
.LBB0_664:
	s_movk_i32 s2, 0x4000
	v_add_co_u32_e32 v98, vcc, s2, v98
	v_pk_mul_f32 v[104:105], v[104:105], s[12:13] op_sel_hi:[1,0]
	v_pk_mul_f32 v[114:115], v[114:115], s[12:13] op_sel_hi:[1,0]
	v_pk_mul_f32 v[100:101], v[100:101], s[12:13] op_sel_hi:[1,0]
	v_addc_co_u32_e32 v99, vcc, 0, v99, vcc
	v_pk_mul_f32 v[110:111], v[110:111], s[12:13] op_sel_hi:[1,0]
	v_pk_mul_f32 v[106:107], v[106:107], s[12:13] op_sel_hi:[1,0]
	v_pk_mul_f32 v[108:109], v[108:109], s[12:13] op_sel_hi:[1,0]
	v_pk_mul_f32 v[102:103], v[102:103], s[12:13] op_sel_hi:[1,0]
	v_mbcnt_lo_u32_b32 v232, -1, 0
	v_mbcnt_hi_u32_b32 v232, -1, v232
	v_and_b32_e32 v233, 15, v232
	v_lshrrev_b32_e32 v234, 4, v232
	v_mul_u32_u24_e32 v222, 0x90, v233
	v_lshl_add_u32 v222, v234, 3, v222
	v_add_u32_e32 v222, m0, v222
	v_bfe_u32 v235, v232, 3, 1
	v_lshlrev_b32_e32 v235, 3, v235
	v_lshl_add_u32 v235, v234, 1, v235
	v_and_b32_e32 v232, 7, v232
	v_mul_u32_u24_e32 v224, 0x90, v235
	v_lshl_add_u32 v224, v232, 4, v224
	v_add_u32_e32 v224, m0, v224
	v_sub_u32_e32 v235, v235, v233
	v_mul_i32_i24_e32 v236, 0x400, v235
	v_lshl_add_u32 v236, v232, 4, v236
	v_lshlrev_b32_e32 v234, 3, v234
	v_sub_u32_e32 v236, v236, v234
	v_ashrrev_i32_e32 v237, 31, v236
	v_cvt_pk_bf16_f32 v228, v114, v115
	v_cvt_pk_bf16_f32 v229, v104, v105
	v_lshl_add_u64 v[236:237], v[98:99], 0, v[236:237]
	v_cvt_pk_bf16_f32 v230, v110, v111
	v_cvt_pk_bf16_f32 v231, v100, v101
	ds_write_b64 v222, v[228:229] offset:36864
	ds_write_b64 v222, v[230:231] offset:36896
	v_cvt_pk_bf16_f32 v232, v108, v109
	v_cvt_pk_bf16_f32 v233, v106, v107
	v_xor_b32_e32 v121, 32, v189
	v_pk_mul_f32 v[112:113], v[112:113], s[12:13] op_sel_hi:[1,0]
	s_nop 0
	v_cvt_pk_bf16_f32 v234, v112, v113
	v_cvt_pk_bf16_f32 v235, v102, v103
	ds_write_b64 v222, v[232:233] offset:36928
	ds_write_b64 v222, v[234:235] offset:36960
	ds_read_b128 v[228:231], v224 offset:36864
	ds_read_b128 v[232:235], v224 offset:37008
	s_waitcnt lgkmcnt(1)
	global_store_dwordx4 v[236:237], v[228:231], off
	s_waitcnt lgkmcnt(0)
	global_store_dwordx4 v[236:237], v[232:235], off offset:1024
	v_pk_fma_f32 v[96:97], v[96:97], v[174:175], v[160:161] op_sel_hi:[1,0,1]
	v_pk_fma_f32 v[94:95], v[94:95], v[174:175], v[158:159] op_sel_hi:[1,0,1]
	v_pk_fma_f32 v[104:105], v[82:83], v[174:175], v[146:147] op_sel_hi:[1,0,1]
	v_mul_f32_e32 v82, v95, v95
	v_mul_f32_e32 v83, v97, v97
	v_pk_fma_f32 v[92:93], v[92:93], v[174:175], v[156:157] op_sel_hi:[1,0,1]
	v_pk_fma_f32 v[90:91], v[90:91], v[174:175], v[154:155] op_sel_hi:[1,0,1]
	v_fmac_f32_e32 v82, v94, v94
	v_fmac_f32_e32 v83, v96, v96
	v_pk_fma_f32 v[102:103], v[84:85], v[174:175], v[148:149] op_sel_hi:[1,0,1]
	v_add_f32_e32 v82, v82, v83
	v_mul_f32_e32 v83, v91, v91
	v_mul_f32_e32 v84, v93, v93
	v_fmac_f32_e32 v83, v90, v90
	v_fmac_f32_e32 v84, v92, v92
	v_pk_fma_f32 v[88:89], v[88:89], v[174:175], v[152:153] op_sel_hi:[1,0,1]
	v_pk_fma_f32 v[100:101], v[86:87], v[174:175], v[150:151] op_sel_hi:[1,0,1]
	v_add_f32_e32 v83, v83, v84
	v_add_f32_e32 v82, v82, v83
	v_mul_f32_e32 v83, v101, v101
	v_mul_f32_e32 v84, v89, v89
	v_fmac_f32_e32 v83, v100, v100
	v_fmac_f32_e32 v84, v88, v88
	v_add_f32_e32 v83, v83, v84
	v_add_f32_e32 v82, v82, v83
	v_mul_f32_e32 v83, v105, v105
	v_mul_f32_e32 v84, v103, v103
	v_fmac_f32_e32 v83, v104, v104
	v_fmac_f32_e32 v84, v102, v102
	v_add_f32_e32 v83, v83, v84
	v_add_f32_e32 v82, v82, v83
	v_mov_b32_e32 v83, v82
	s_nop 1
	v_permlane16_swap_b32_e32 v82, v83
	v_add_f32_e32 v82, v82, v83
	v_mov_b32_e32 v83, v82
	s_nop 1
	v_permlane32_swap_b32_e32 v82, v83
	v_add_f32_e32 v82, v82, v83
	v_fmamk_f32 v82, v82, 0x3c800000, v223
	v_rsq_f32_e32 v106, v82
	v_mov_b64_e32 v[82:83], v[162:163]
	v_mov_b64_e32 v[84:85], 0
	v_pk_mul_f32 v[90:91], v[90:91], v[106:107] op_sel_hi:[1,0]
	v_pk_mul_f32 v[84:85], v[94:95], v[106:107] op_sel_hi:[1,0]
	v_pk_mul_f32 v[88:89], v[88:89], v[106:107] op_sel_hi:[1,0]
	v_pk_mul_f32 v[86:87], v[96:97], v[106:107] op_sel_hi:[1,0]
	v_pk_mul_f32 v[98:99], v[142:143], v[84:85]
	v_pk_mul_f32 v[84:85], v[92:93], v[106:107] op_sel_hi:[1,0]
	v_pk_mul_f32 v[94:95], v[138:139], v[90:91]
	v_pk_mul_f32 v[92:93], v[100:101], v[106:107] op_sel_hi:[1,0]
	v_pk_mul_f32 v[90:91], v[136:137], v[88:89]
	v_pk_mul_f32 v[96:97], v[104:105], v[106:107] op_sel_hi:[1,0]
	v_pk_mul_f32 v[88:89], v[102:103], v[106:107] op_sel_hi:[1,0]
	v_cvt_f32_ubyte0_e32 v100, v121
	v_pk_mul_f32 v[86:87], v[144:145], v[86:87]
	v_pk_mul_f32 v[84:85], v[140:141], v[84:85]
	v_pk_mul_f32 v[92:93], v[134:135], v[92:93]
	v_pk_mul_f32 v[88:89], v[132:133], v[88:89]
	v_pk_mul_f32 v[96:97], v[130:131], v[96:97]
	s_and_b64 vcc, exec, s[42:43]
	v_mul_f32_e32 v104, v0, v100
	v_mul_f32_e32 v103, v165, v100
	v_mul_f32_e32 v102, v167, v100
	v_mul_f32_e32 v101, v169, v100
	s_cbranch_vccnz .LBB0_666
	v_add_u32_e32 v105, 32, v216
	v_ashrrev_i32_e32 v105, 6, v105
	v_cvt_f32_i32_e32 v105, v105
	v_mul_f32_e32 v106, v0, v105
	v_mul_f32_e32 v107, v165, v105
	v_floor_f32_e32 v106, v106
	v_floor_f32_e32 v107, v107
	v_fma_f32 v108, v0, v105, -v106
	v_fma_f32 v109, v165, v105, -v107
	v_sin_f32_e32 v106, v108
	v_cos_f32_e32 v108, v108
	v_sin_f32_e32 v107, v109
	v_cos_f32_e32 v109, v109
	v_mul_f32_e32 v110, v167, v105
	v_floor_f32_e32 v110, v110
	v_mul_f32_e32 v121, v169, v105
	v_fma_f32 v110, v167, v105, -v110
	v_floor_f32_e32 v121, v121
	v_cos_f32_e32 v113, v110
	v_sin_f32_e32 v115, v110
	v_fma_f32 v105, v169, v105, -v121
	v_pk_mul_f32 v[110:111], v[106:107], v[94:95]
	v_pk_mul_f32 v[94:95], v[108:109], v[94:95]
	v_sin_f32_e32 v123, v105
	v_cos_f32_e32 v122, v105
	v_pk_fma_f32 v[108:109], v[108:109], v[98:99], v[110:111] neg_lo:[0,0,1] neg_hi:[0,0,1]
	v_pk_fma_f32 v[94:95], v[106:107], v[98:99], v[94:95]
	v_floor_f32_e32 v98, v104
	v_fma_f32 v99, v0, v100, -v98
	v_mul_f32_e32 v114, v115, v84
	v_mul_f32_e32 v126, v113, v84
	v_mov_b32_e32 v84, v87
	v_sin_f32_e32 v98, v99
	v_cos_f32_e32 v106, v99
	v_floor_f32_e32 v99, v103
	v_mul_f32_e32 v112, v113, v86
	v_mul_f32_e32 v124, v115, v86
	v_pk_mul_f32 v[86:87], v[122:123], v[84:85]
	v_fma_f32 v105, v165, v100, -v99
	v_mov_b32_e32 v113, v86
	v_mov_b32_e32 v115, v87
	v_mov_b32_e32 v86, v123
	v_mov_b32_e32 v87, v122
	v_sin_f32_e32 v99, v105
	v_cos_f32_e32 v107, v105
	v_floor_f32_e32 v105, v102
	v_pk_mul_f32 v[84:85], v[86:87], v[84:85]
	v_pk_add_f32 v[86:87], v[112:113], v[114:115] neg_lo:[0,1] neg_hi:[0,1]
	v_fma_f32 v105, v167, v100, -v105
	v_floor_f32_e32 v115, v101
	v_cos_f32_e32 v113, v105
	v_sin_f32_e32 v105, v105
	v_fma_f32 v115, v169, v100, -v115
	v_sin_f32_e32 v123, v115
	v_cos_f32_e32 v122, v115
	v_mov_b32_e32 v125, v84
	v_mov_b32_e32 v127, v85
	v_pk_add_f32 v[84:85], v[124:125], v[126:127]
	v_mul_f32_e32 v114, v105, v88
	v_mul_f32_e32 v126, v113, v88
	v_mov_b32_e32 v88, v91
	v_mul_f32_e32 v112, v113, v90
	v_mul_f32_e32 v124, v105, v90
	v_pk_mul_f32 v[90:91], v[122:123], v[88:89]
	v_pk_mul_f32 v[110:111], v[98:99], v[96:97]
	v_mov_b32_e32 v113, v90
	v_mov_b32_e32 v115, v91
	v_mov_b32_e32 v90, v123
	v_mov_b32_e32 v91, v122
	v_pk_mul_f32 v[88:89], v[90:91], v[88:89]
	v_pk_mul_f32 v[96:97], v[106:107], v[96:97]
	v_mov_b32_e32 v125, v88
	v_mov_b32_e32 v127, v89
	v_pk_fma_f32 v[106:107], v[106:107], v[92:93], v[110:111] neg_lo:[0,0,1] neg_hi:[0,0,1]
	v_pk_add_f32 v[90:91], v[112:113], v[114:115] neg_lo:[0,1] neg_hi:[0,1]
	v_pk_fma_f32 v[96:97], v[98:99], v[92:93], v[96:97]
	v_pk_add_f32 v[88:89], v[124:125], v[126:127]
	v_mov_b32_e32 v98, v108
	v_mov_b32_e32 v99, v109
	v_mov_b32_e32 v92, v106
	v_mov_b32_e32 v93, v107
.LBB0_666:
	s_mov_b32 s2, 0x8000
	v_add_co_u32_e32 v82, vcc, s2, v82
	v_pk_mul_f32 v[86:87], v[86:87], s[12:13] op_sel_hi:[1,0]
	v_pk_mul_f32 v[98:99], v[98:99], s[12:13] op_sel_hi:[1,0]
	v_pk_mul_f32 v[84:85], v[84:85], s[12:13] op_sel_hi:[1,0]
	v_addc_co_u32_e32 v83, vcc, 0, v83, vcc
	v_pk_mul_f32 v[94:95], v[94:95], s[12:13] op_sel_hi:[1,0]
	v_pk_mul_f32 v[90:91], v[90:91], s[12:13] op_sel_hi:[1,0]
	v_pk_mul_f32 v[92:93], v[92:93], s[12:13] op_sel_hi:[1,0]
	v_pk_mul_f32 v[88:89], v[88:89], s[12:13] op_sel_hi:[1,0]
	v_mbcnt_lo_u32_b32 v232, -1, 0
	v_mbcnt_hi_u32_b32 v232, -1, v232
	v_and_b32_e32 v233, 15, v232
	v_lshrrev_b32_e32 v234, 4, v232
	v_mul_u32_u24_e32 v222, 0x90, v233
	v_lshl_add_u32 v222, v234, 3, v222
	v_add_u32_e32 v222, m0, v222
	v_bfe_u32 v235, v232, 3, 1
	v_lshlrev_b32_e32 v235, 3, v235
	v_lshl_add_u32 v235, v234, 1, v235
	v_and_b32_e32 v232, 7, v232
	v_mul_u32_u24_e32 v224, 0x90, v235
	v_lshl_add_u32 v224, v232, 4, v224
	v_add_u32_e32 v224, m0, v224
	v_sub_u32_e32 v235, v235, v233
	v_mul_i32_i24_e32 v236, 0x400, v235
	v_lshl_add_u32 v236, v232, 4, v236
	v_lshlrev_b32_e32 v234, 3, v234
	v_sub_u32_e32 v236, v236, v234
	v_ashrrev_i32_e32 v237, 31, v236
	v_cvt_pk_bf16_f32 v228, v98, v99
	v_cvt_pk_bf16_f32 v229, v86, v87
	v_lshl_add_u64 v[236:237], v[82:83], 0, v[236:237]
	v_cvt_pk_bf16_f32 v230, v94, v95
	v_cvt_pk_bf16_f32 v231, v84, v85
	ds_write_b64 v222, v[228:229] offset:36864
	ds_write_b64 v222, v[230:231] offset:36896
	v_cvt_pk_bf16_f32 v232, v92, v93
	v_cvt_pk_bf16_f32 v233, v90, v91
	v_pk_fma_f32 v[80:81], v[80:81], v[172:173], v[160:161] op_sel_hi:[1,0,1]
	v_pk_fma_f32 v[78:79], v[78:79], v[172:173], v[158:159] op_sel_hi:[1,0,1]
	v_pk_mul_f32 v[96:97], v[96:97], s[12:13] op_sel_hi:[1,0]
	s_nop 0
	v_cvt_pk_bf16_f32 v234, v96, v97
	v_cvt_pk_bf16_f32 v235, v88, v89
	v_pk_fma_f32 v[88:89], v[66:67], v[172:173], v[146:147] op_sel_hi:[1,0,1]
	v_mul_f32_e32 v66, v79, v79
	v_mul_f32_e32 v67, v81, v81
	v_pk_fma_f32 v[76:77], v[76:77], v[172:173], v[156:157] op_sel_hi:[1,0,1]
	v_pk_fma_f32 v[74:75], v[74:75], v[172:173], v[154:155] op_sel_hi:[1,0,1]
	v_fmac_f32_e32 v66, v78, v78
	v_fmac_f32_e32 v67, v80, v80
	v_pk_fma_f32 v[86:87], v[68:69], v[172:173], v[148:149] op_sel_hi:[1,0,1]
	v_add_f32_e32 v66, v66, v67
	v_mul_f32_e32 v67, v75, v75
	v_mul_f32_e32 v68, v77, v77
	v_fmac_f32_e32 v67, v74, v74
	v_fmac_f32_e32 v68, v76, v76
	ds_write_b64 v222, v[232:233] offset:36928
	ds_write_b64 v222, v[234:235] offset:36960
	ds_read_b128 v[228:231], v224 offset:36864
	ds_read_b128 v[232:235], v224 offset:37008
	s_waitcnt lgkmcnt(1)
	global_store_dwordx4 v[236:237], v[228:231], off
	s_waitcnt lgkmcnt(0)
	global_store_dwordx4 v[236:237], v[232:235], off offset:1024
	v_pk_fma_f32 v[84:85], v[72:73], v[172:173], v[152:153] op_sel_hi:[1,0,1]
	v_pk_fma_f32 v[70:71], v[70:71], v[172:173], v[150:151] op_sel_hi:[1,0,1]
	v_add_f32_e32 v67, v67, v68
	v_add_f32_e32 v66, v66, v67
	v_mul_f32_e32 v67, v71, v71
	v_mul_f32_e32 v68, v85, v85
	v_fmac_f32_e32 v67, v70, v70
	v_fmac_f32_e32 v68, v84, v84
	v_add_f32_e32 v67, v67, v68
	v_add_f32_e32 v66, v66, v67
	v_mul_f32_e32 v67, v89, v89
	v_mul_f32_e32 v68, v87, v87
	v_fmac_f32_e32 v67, v88, v88
	v_fmac_f32_e32 v68, v86, v86
	v_add_f32_e32 v67, v67, v68
	v_add_f32_e32 v66, v66, v67
	v_mov_b32_e32 v67, v66
	s_nop 1
	v_permlane16_swap_b32_e32 v66, v67
	v_add_f32_e32 v66, v66, v67
	v_mov_b32_e32 v67, v66
	s_nop 1
	v_permlane32_swap_b32_e32 v66, v67
	v_add_f32_e32 v66, v66, v67
	v_fmamk_f32 v66, v66, 0x3c800000, v223
	v_rsq_f32_e32 v90, v66
	v_mov_b64_e32 v[66:67], v[162:163]
	v_mov_b64_e32 v[68:69], 0
	v_add_u32_e32 v105, 48, v216
	v_and_b32_e32 v106, 63, v105
	v_pk_mul_f32 v[68:69], v[78:79], v[90:91] op_sel_hi:[1,0]
	v_pk_mul_f32 v[74:75], v[74:75], v[90:91] op_sel_hi:[1,0]
	v_pk_mul_f32 v[70:71], v[70:71], v[90:91] op_sel_hi:[1,0]
	v_pk_mul_f32 v[72:73], v[80:81], v[90:91] op_sel_hi:[1,0]
	v_pk_mul_f32 v[82:83], v[142:143], v[68:69]
	v_pk_mul_f32 v[68:69], v[76:77], v[90:91] op_sel_hi:[1,0]
	v_pk_mul_f32 v[78:79], v[138:139], v[74:75]
	v_pk_mul_f32 v[74:75], v[84:85], v[90:91] op_sel_hi:[1,0]
	v_pk_mul_f32 v[76:77], v[134:135], v[70:71]
	v_pk_mul_f32 v[80:81], v[88:89], v[90:91] op_sel_hi:[1,0]
	v_pk_mul_f32 v[70:71], v[86:87], v[90:91] op_sel_hi:[1,0]
	v_cvt_f32_ubyte0_e32 v84, v106
	v_pk_mul_f32 v[72:73], v[144:145], v[72:73]
	v_pk_mul_f32 v[68:69], v[140:141], v[68:69]
	v_pk_mul_f32 v[74:75], v[136:137], v[74:75]
	v_pk_mul_f32 v[70:71], v[132:133], v[70:71]
	v_pk_mul_f32 v[80:81], v[130:131], v[80:81]
	s_and_b64 vcc, exec, s[42:43]
	v_mul_f32_e32 v88, v0, v84
	v_mul_f32_e32 v87, v165, v84
	v_mul_f32_e32 v86, v167, v84
	v_mul_f32_e32 v85, v169, v84
	s_cbranch_vccnz .LBB0_668
	v_ashrrev_i32_e32 v89, 6, v105
	v_cvt_f32_i32_e32 v89, v89
	v_mul_f32_e32 v90, v0, v89
	v_mul_f32_e32 v91, v165, v89
	v_floor_f32_e32 v90, v90
	v_floor_f32_e32 v91, v91
	v_fma_f32 v92, v0, v89, -v90
	v_fma_f32 v93, v165, v89, -v91
	v_sin_f32_e32 v90, v92
	v_cos_f32_e32 v92, v92
	v_sin_f32_e32 v91, v93
	v_cos_f32_e32 v93, v93
	v_mul_f32_e32 v94, v167, v89
	v_floor_f32_e32 v94, v94
	v_mul_f32_e32 v105, v169, v89
	v_fma_f32 v94, v167, v89, -v94
	v_floor_f32_e32 v105, v105
	v_cos_f32_e32 v97, v94
	v_sin_f32_e32 v99, v94
	v_fma_f32 v89, v169, v89, -v105
	v_pk_mul_f32 v[94:95], v[90:91], v[78:79]
	v_pk_mul_f32 v[78:79], v[92:93], v[78:79]
	v_sin_f32_e32 v107, v89
	v_cos_f32_e32 v106, v89
	v_pk_fma_f32 v[92:93], v[92:93], v[82:83], v[94:95] neg_lo:[0,0,1] neg_hi:[0,0,1]
	v_pk_fma_f32 v[78:79], v[90:91], v[82:83], v[78:79]
	v_floor_f32_e32 v82, v88
	v_fma_f32 v83, v0, v84, -v82
	v_mul_f32_e32 v98, v99, v68
	v_mul_f32_e32 v110, v97, v68
	v_mov_b32_e32 v68, v73
	v_sin_f32_e32 v82, v83
	v_cos_f32_e32 v90, v83
	v_floor_f32_e32 v83, v87
	v_mul_f32_e32 v96, v97, v72
	v_mul_f32_e32 v108, v99, v72
	v_pk_mul_f32 v[72:73], v[106:107], v[68:69]
	v_fma_f32 v89, v165, v84, -v83
	v_mov_b32_e32 v97, v72
	v_mov_b32_e32 v99, v73
	v_mov_b32_e32 v72, v107
	v_mov_b32_e32 v73, v106
	v_sin_f32_e32 v83, v89
	v_cos_f32_e32 v91, v89
	v_floor_f32_e32 v89, v86
	v_pk_mul_f32 v[68:69], v[72:73], v[68:69]
	v_pk_add_f32 v[72:73], v[96:97], v[98:99] neg_lo:[0,1] neg_hi:[0,1]
	v_fma_f32 v89, v167, v84, -v89
	v_floor_f32_e32 v99, v85
	v_cos_f32_e32 v97, v89
	v_sin_f32_e32 v89, v89
	v_fma_f32 v99, v169, v84, -v99
	v_sin_f32_e32 v107, v99
	v_cos_f32_e32 v106, v99
	v_mov_b32_e32 v109, v68
	v_mov_b32_e32 v111, v69
	v_pk_add_f32 v[68:69], v[108:109], v[110:111]
	v_mul_f32_e32 v98, v89, v70
	v_mul_f32_e32 v110, v97, v70
	v_mov_b32_e32 v70, v75
	v_mul_f32_e32 v96, v97, v74
	v_mul_f32_e32 v108, v89, v74
	v_pk_mul_f32 v[74:75], v[106:107], v[70:71]
	v_pk_mul_f32 v[94:95], v[82:83], v[80:81]
	v_mov_b32_e32 v97, v74
	v_mov_b32_e32 v99, v75
	v_mov_b32_e32 v74, v107
	v_mov_b32_e32 v75, v106
	v_pk_mul_f32 v[70:71], v[74:75], v[70:71]
	v_pk_mul_f32 v[80:81], v[90:91], v[80:81]
	v_mov_b32_e32 v109, v70
	v_mov_b32_e32 v111, v71
	v_pk_fma_f32 v[90:91], v[90:91], v[76:77], v[94:95] neg_lo:[0,0,1] neg_hi:[0,0,1]
	v_pk_add_f32 v[74:75], v[96:97], v[98:99] neg_lo:[0,1] neg_hi:[0,1]
	v_pk_fma_f32 v[80:81], v[82:83], v[76:77], v[80:81]
	v_pk_add_f32 v[70:71], v[108:109], v[110:111]
	v_mov_b32_e32 v82, v92
	v_mov_b32_e32 v83, v93
	v_mov_b32_e32 v76, v90
	v_mov_b32_e32 v77, v91
.LBB0_668:
	s_mov_b32 s2, 0xc000
	v_add_co_u32_e32 v66, vcc, s2, v66
	v_pk_mul_f32 v[72:73], v[72:73], s[12:13] op_sel_hi:[1,0]
	v_pk_mul_f32 v[82:83], v[82:83], s[12:13] op_sel_hi:[1,0]
	v_pk_mul_f32 v[68:69], v[68:69], s[12:13] op_sel_hi:[1,0]
	v_addc_co_u32_e32 v67, vcc, 0, v67, vcc
	v_pk_mul_f32 v[78:79], v[78:79], s[12:13] op_sel_hi:[1,0]
	v_pk_mul_f32 v[74:75], v[74:75], s[12:13] op_sel_hi:[1,0]
	v_pk_mul_f32 v[76:77], v[76:77], s[12:13] op_sel_hi:[1,0]
	v_mbcnt_lo_u32_b32 v232, -1, 0
	v_mbcnt_hi_u32_b32 v232, -1, v232
	v_and_b32_e32 v233, 15, v232
	v_lshrrev_b32_e32 v234, 4, v232
	v_mul_u32_u24_e32 v222, 0x90, v233
	v_lshl_add_u32 v222, v234, 3, v222
	v_add_u32_e32 v222, m0, v222
	v_bfe_u32 v235, v232, 3, 1
	v_lshlrev_b32_e32 v235, 3, v235
	v_lshl_add_u32 v235, v234, 1, v235
	v_and_b32_e32 v232, 7, v232
	v_mul_u32_u24_e32 v224, 0x90, v235
	v_lshl_add_u32 v224, v232, 4, v224
	v_add_u32_e32 v224, m0, v224
	v_sub_u32_e32 v235, v235, v233
	v_mul_i32_i24_e32 v236, 0x400, v235
	v_lshl_add_u32 v236, v232, 4, v236
	v_lshlrev_b32_e32 v234, 3, v234
	v_sub_u32_e32 v236, v236, v234
	v_ashrrev_i32_e32 v237, 31, v236
	v_cvt_pk_bf16_f32 v228, v82, v83
	v_cvt_pk_bf16_f32 v229, v72, v73
	v_lshl_add_u64 v[236:237], v[66:67], 0, v[236:237]
	v_cvt_pk_bf16_f32 v230, v78, v79
	v_cvt_pk_bf16_f32 v231, v68, v69
	ds_write_b64 v222, v[228:229] offset:36864
	ds_write_b64 v222, v[230:231] offset:36896
	v_cvt_pk_bf16_f32 v232, v76, v77
	v_cvt_pk_bf16_f32 v233, v74, v75
	v_pk_mul_f32 v[70:71], v[70:71], s[12:13] op_sel_hi:[1,0]
	v_pk_mul_f32 v[80:81], v[80:81], s[12:13] op_sel_hi:[1,0]
	s_nop 0
	v_cvt_pk_bf16_f32 v234, v80, v81
	v_cvt_pk_bf16_f32 v235, v70, v71
	ds_write_b64 v222, v[232:233] offset:36928
	ds_write_b64 v222, v[234:235] offset:36960
	ds_read_b128 v[228:231], v224 offset:36864
	ds_read_b128 v[232:235], v224 offset:37008
	s_waitcnt lgkmcnt(1)
	global_store_dwordx4 v[236:237], v[228:231], off
	s_waitcnt lgkmcnt(0)
	global_store_dwordx4 v[236:237], v[232:235], off offset:1024
	v_pk_fma_f32 v[64:65], v[64:65], v[170:171], v[160:161] op_sel_hi:[1,0,1]
	v_pk_fma_f32 v[62:63], v[62:63], v[170:171], v[158:159] op_sel_hi:[1,0,1]
	v_pk_fma_f32 v[72:73], v[50:51], v[170:171], v[146:147] op_sel_hi:[1,0,1]
	v_mul_f32_e32 v50, v63, v63
	v_mul_f32_e32 v51, v65, v65
	v_pk_fma_f32 v[60:61], v[60:61], v[170:171], v[156:157] op_sel_hi:[1,0,1]
	v_pk_fma_f32 v[58:59], v[58:59], v[170:171], v[154:155] op_sel_hi:[1,0,1]
	v_fmac_f32_e32 v50, v62, v62
	v_fmac_f32_e32 v51, v64, v64
	v_pk_fma_f32 v[70:71], v[52:53], v[170:171], v[148:149] op_sel_hi:[1,0,1]
	v_add_f32_e32 v50, v50, v51
	v_mul_f32_e32 v51, v59, v59
	v_mul_f32_e32 v52, v61, v61
	v_fmac_f32_e32 v51, v58, v58
	v_fmac_f32_e32 v52, v60, v60
	v_pk_fma_f32 v[56:57], v[56:57], v[170:171], v[152:153] op_sel_hi:[1,0,1]
	v_pk_fma_f32 v[68:69], v[54:55], v[170:171], v[150:151] op_sel_hi:[1,0,1]
	v_add_f32_e32 v51, v51, v52
	v_add_f32_e32 v50, v50, v51
	v_mul_f32_e32 v51, v69, v69
	v_mul_f32_e32 v52, v57, v57
	v_fmac_f32_e32 v51, v68, v68
	v_fmac_f32_e32 v52, v56, v56
	v_add_f32_e32 v51, v51, v52
	v_add_f32_e32 v50, v51, v50
	v_mul_f32_e32 v51, v73, v73
	v_mul_f32_e32 v52, v71, v71
	v_fmac_f32_e32 v51, v72, v72
	v_fmac_f32_e32 v52, v70, v70
	v_add_f32_e32 v51, v51, v52
	v_add_f32_e32 v50, v51, v50
	v_mov_b32_e32 v51, v50
	s_nop 1
	v_permlane16_swap_b32_e32 v50, v51
	v_add_f32_e32 v50, v50, v51
	v_mov_b32_e32 v51, v50
	s_nop 1
	v_permlane32_swap_b32_e32 v50, v51
	v_add_f32_e32 v50, v50, v51
	v_fmamk_f32 v50, v50, 0x3c800000, v223
	v_rsq_f32_e32 v74, v50
	v_mov_b64_e32 v[50:51], v[162:163]
	v_mov_b64_e32 v[52:53], 0
	v_pk_mul_f32 v[58:59], v[58:59], v[74:75] op_sel_hi:[1,0]
	v_pk_mul_f32 v[52:53], v[62:63], v[74:75] op_sel_hi:[1,0]
	v_pk_mul_f32 v[56:57], v[56:57], v[74:75] op_sel_hi:[1,0]
	v_pk_mul_f32 v[54:55], v[64:65], v[74:75] op_sel_hi:[1,0]
	v_pk_mul_f32 v[66:67], v[142:143], v[52:53]
	v_pk_mul_f32 v[52:53], v[60:61], v[74:75] op_sel_hi:[1,0]
	v_pk_mul_f32 v[62:63], v[138:139], v[58:59]
	v_pk_mul_f32 v[60:61], v[68:69], v[74:75] op_sel_hi:[1,0]
	v_pk_mul_f32 v[58:59], v[136:137], v[56:57]
	v_pk_mul_f32 v[64:65], v[72:73], v[74:75] op_sel_hi:[1,0]
	v_pk_mul_f32 v[56:57], v[70:71], v[74:75] op_sel_hi:[1,0]
	v_pk_mul_f32 v[54:55], v[144:145], v[54:55]
	v_pk_mul_f32 v[52:53], v[140:141], v[52:53]
	v_pk_mul_f32 v[60:61], v[134:135], v[60:61]
	v_pk_mul_f32 v[56:57], v[132:133], v[56:57]
	s_and_b64 vcc, exec, s[42:43]
	v_pk_mul_f32 v[64:65], v[130:131], v[64:65]
	s_cbranch_vccnz .LBB0_670
	v_add_u32_e32 v68, 0x80, v216
	v_ashrrev_i32_e32 v68, 6, v68
	v_cvt_f32_i32_e32 v75, v68
	v_mul_f32_e32 v68, v0, v75
	v_mul_f32_e32 v69, v165, v75
	v_mul_f32_e32 v72, v167, v75
	v_floor_f32_e32 v68, v68
	v_floor_f32_e32 v69, v69
	v_floor_f32_e32 v72, v72
	v_mul_f32_e32 v78, v169, v75
	v_fma_f32 v70, v0, v75, -v68
	v_fma_f32 v71, v165, v75, -v69
	v_fma_f32 v72, v167, v75, -v72
	v_floor_f32_e32 v78, v78
	v_sin_f32_e32 v68, v70
	v_sin_f32_e32 v69, v71
	v_cos_f32_e32 v77, v72
	v_sin_f32_e32 v80, v72
	v_fma_f32 v75, v169, v75, -v78
	v_cos_f32_e32 v70, v70
	v_cos_f32_e32 v71, v71
	v_sin_f32_e32 v79, v75
	v_cos_f32_e32 v78, v75
	v_pk_mul_f32 v[72:73], v[68:69], v[62:63]
	v_mul_f32_e32 v76, v80, v52
	v_mul_f32_e32 v82, v77, v52
	v_mov_b32_e32 v52, v55
	v_pk_mul_f32 v[62:63], v[70:71], v[62:63]
	v_mul_f32_e32 v74, v77, v54
	v_mul_f32_e32 v80, v80, v54
	v_pk_mul_f32 v[54:55], v[78:79], v[52:53]
	v_pk_fma_f32 v[70:71], v[70:71], v[66:67], v[72:73] neg_lo:[0,0,1] neg_hi:[0,0,1]
	v_floor_f32_e32 v72, v175
	v_mov_b32_e32 v75, v54
	v_mov_b32_e32 v77, v55
	v_mov_b32_e32 v54, v79
	v_mov_b32_e32 v55, v78
	v_pk_fma_f32 v[62:63], v[68:69], v[66:67], v[62:63]
	v_floor_f32_e32 v66, v173
	v_fma_f32 v72, v167, v171, -v72
	v_floor_f32_e32 v78, v188
	v_pk_mul_f32 v[52:53], v[54:55], v[52:53]
	v_pk_add_f32 v[54:55], v[74:75], v[76:77] neg_lo:[0,1] neg_hi:[0,1]
	v_fma_f32 v67, v0, v171, -v66
	v_cos_f32_e32 v75, v72
	v_sin_f32_e32 v77, v72
	v_fma_f32 v78, v169, v171, -v78
	v_sin_f32_e32 v66, v67
	v_cos_f32_e32 v68, v67
	v_floor_f32_e32 v67, v177
	v_sin_f32_e32 v79, v78
	v_cos_f32_e32 v78, v78
	v_fma_f32 v69, v165, v171, -v67
	v_mov_b32_e32 v81, v52
	v_mov_b32_e32 v83, v53
	v_sin_f32_e32 v67, v69
	v_pk_add_f32 v[52:53], v[80:81], v[82:83]
	v_cos_f32_e32 v69, v69
	v_mul_f32_e32 v76, v77, v56
	v_mul_f32_e32 v82, v75, v56
	v_mov_b32_e32 v56, v59
	v_mul_f32_e32 v74, v75, v58
	v_mul_f32_e32 v80, v77, v58
	v_pk_mul_f32 v[58:59], v[78:79], v[56:57]
	v_pk_mul_f32 v[72:73], v[66:67], v[64:65]
	v_mov_b32_e32 v75, v58
	v_mov_b32_e32 v77, v59
	v_mov_b32_e32 v58, v79
	v_mov_b32_e32 v59, v78
	v_pk_mul_f32 v[56:57], v[58:59], v[56:57]
	v_pk_mul_f32 v[64:65], v[68:69], v[64:65]
	v_mov_b32_e32 v81, v56
	v_mov_b32_e32 v83, v57
	v_pk_fma_f32 v[68:69], v[68:69], v[60:61], v[72:73] neg_lo:[0,0,1] neg_hi:[0,0,1]
	v_pk_add_f32 v[58:59], v[74:75], v[76:77] neg_lo:[0,1] neg_hi:[0,1]
	v_pk_fma_f32 v[64:65], v[66:67], v[60:61], v[64:65]
	v_pk_add_f32 v[56:57], v[80:81], v[82:83]
	v_mov_b32_e32 v66, v70
	v_mov_b32_e32 v67, v71
	v_mov_b32_e32 v60, v68
	v_mov_b32_e32 v61, v69
.LBB0_670:
	s_mov_b32 s2, 0x20000
	v_add_co_u32_e32 v50, vcc, s2, v50
	v_pk_mul_f32 v[54:55], v[54:55], s[12:13] op_sel_hi:[1,0]
	v_pk_mul_f32 v[66:67], v[66:67], s[12:13] op_sel_hi:[1,0]
	v_pk_mul_f32 v[52:53], v[52:53], s[12:13] op_sel_hi:[1,0]
	v_addc_co_u32_e32 v51, vcc, 0, v51, vcc
	v_pk_mul_f32 v[62:63], v[62:63], s[12:13] op_sel_hi:[1,0]
	v_pk_mul_f32 v[58:59], v[58:59], s[12:13] op_sel_hi:[1,0]
	v_pk_mul_f32 v[60:61], v[60:61], s[12:13] op_sel_hi:[1,0]
	v_pk_mul_f32 v[56:57], v[56:57], s[12:13] op_sel_hi:[1,0]
	v_mbcnt_lo_u32_b32 v232, -1, 0
	v_mbcnt_hi_u32_b32 v232, -1, v232
	v_and_b32_e32 v233, 15, v232
	v_lshrrev_b32_e32 v234, 4, v232
	v_mul_u32_u24_e32 v222, 0x90, v233
	v_lshl_add_u32 v222, v234, 3, v222
	v_add_u32_e32 v222, m0, v222
	v_bfe_u32 v235, v232, 3, 1
	v_lshlrev_b32_e32 v235, 3, v235
	v_lshl_add_u32 v235, v234, 1, v235
	v_and_b32_e32 v232, 7, v232
	v_mul_u32_u24_e32 v224, 0x90, v235
	v_lshl_add_u32 v224, v232, 4, v224
	v_add_u32_e32 v224, m0, v224
	v_sub_u32_e32 v235, v235, v233
	v_mul_i32_i24_e32 v236, 0x400, v235
	v_lshl_add_u32 v236, v232, 4, v236
	v_lshlrev_b32_e32 v234, 3, v234
	v_sub_u32_e32 v236, v236, v234
	v_ashrrev_i32_e32 v237, 31, v236
	v_cvt_pk_bf16_f32 v228, v66, v67
	v_cvt_pk_bf16_f32 v229, v54, v55
	v_lshl_add_u64 v[236:237], v[50:51], 0, v[236:237]
	v_cvt_pk_bf16_f32 v230, v62, v63
	v_cvt_pk_bf16_f32 v231, v52, v53
	ds_write_b64 v222, v[228:229] offset:36864
	ds_write_b64 v222, v[230:231] offset:36896
	v_cvt_pk_bf16_f32 v232, v60, v61
	v_cvt_pk_bf16_f32 v233, v58, v59
	v_pk_fma_f32 v[48:49], v[48:49], v[168:169], v[160:161] op_sel_hi:[1,0,1]
	v_pk_fma_f32 v[46:47], v[46:47], v[168:169], v[158:159] op_sel_hi:[1,0,1]
	v_pk_mul_f32 v[64:65], v[64:65], s[12:13] op_sel_hi:[1,0]
	s_nop 0
	v_cvt_pk_bf16_f32 v234, v64, v65
	v_cvt_pk_bf16_f32 v235, v56, v57
	v_pk_fma_f32 v[56:57], v[34:35], v[168:169], v[146:147] op_sel_hi:[1,0,1]
	v_mul_f32_e32 v34, v47, v47
	v_mul_f32_e32 v35, v49, v49
	v_pk_fma_f32 v[44:45], v[44:45], v[168:169], v[156:157] op_sel_hi:[1,0,1]
	v_pk_fma_f32 v[42:43], v[42:43], v[168:169], v[154:155] op_sel_hi:[1,0,1]
	v_fmac_f32_e32 v34, v46, v46
	v_fmac_f32_e32 v35, v48, v48
	v_pk_fma_f32 v[54:55], v[36:37], v[168:169], v[148:149] op_sel_hi:[1,0,1]
	v_add_f32_e32 v34, v34, v35
	v_mul_f32_e32 v35, v43, v43
	v_mul_f32_e32 v36, v45, v45
	v_fmac_f32_e32 v35, v42, v42
	v_fmac_f32_e32 v36, v44, v44
	ds_write_b64 v222, v[232:233] offset:36928
	ds_write_b64 v222, v[234:235] offset:36960
	ds_read_b128 v[228:231], v224 offset:36864
	ds_read_b128 v[232:235], v224 offset:37008
	s_waitcnt lgkmcnt(1)
	global_store_dwordx4 v[236:237], v[228:231], off
	s_waitcnt lgkmcnt(0)
	global_store_dwordx4 v[236:237], v[232:235], off offset:1024
	v_pk_fma_f32 v[52:53], v[40:41], v[168:169], v[152:153] op_sel_hi:[1,0,1]
	v_pk_fma_f32 v[38:39], v[38:39], v[168:169], v[150:151] op_sel_hi:[1,0,1]
	v_add_f32_e32 v35, v35, v36
	v_add_f32_e32 v34, v34, v35
	v_mul_f32_e32 v35, v39, v39
	v_mul_f32_e32 v36, v53, v53
	v_fmac_f32_e32 v35, v38, v38
	v_fmac_f32_e32 v36, v52, v52
	v_add_f32_e32 v35, v35, v36
	v_add_f32_e32 v34, v35, v34
	v_mul_f32_e32 v35, v57, v57
	v_mul_f32_e32 v36, v55, v55
	v_fmac_f32_e32 v35, v56, v56
	v_fmac_f32_e32 v36, v54, v54
	v_add_f32_e32 v35, v35, v36
	v_add_f32_e32 v34, v35, v34
	v_mov_b32_e32 v35, v34
	s_nop 1
	v_permlane16_swap_b32_e32 v34, v35
	v_add_f32_e32 v34, v34, v35
	v_mov_b32_e32 v35, v34
	s_nop 1
	v_permlane32_swap_b32_e32 v34, v35
	v_add_f32_e32 v34, v34, v35
	v_fmamk_f32 v34, v34, 0x3c800000, v223
	v_rsq_f32_e32 v58, v34
	v_mov_b64_e32 v[36:37], 0
	v_mov_b64_e32 v[34:35], v[162:163]
	v_pk_mul_f32 v[42:43], v[42:43], v[58:59] op_sel_hi:[1,0]
	v_pk_mul_f32 v[36:37], v[46:47], v[58:59] op_sel_hi:[1,0]
	v_pk_mul_f32 v[38:39], v[38:39], v[58:59] op_sel_hi:[1,0]
	v_pk_mul_f32 v[40:41], v[48:49], v[58:59] op_sel_hi:[1,0]
	v_pk_mul_f32 v[50:51], v[142:143], v[36:37]
	v_pk_mul_f32 v[36:37], v[44:45], v[58:59] op_sel_hi:[1,0]
	v_pk_mul_f32 v[46:47], v[138:139], v[42:43]
	v_pk_mul_f32 v[42:43], v[52:53], v[58:59] op_sel_hi:[1,0]
	v_pk_mul_f32 v[44:45], v[134:135], v[38:39]
	v_pk_mul_f32 v[48:49], v[56:57], v[58:59] op_sel_hi:[1,0]
	v_pk_mul_f32 v[38:39], v[54:55], v[58:59] op_sel_hi:[1,0]
	v_pk_mul_f32 v[40:41], v[144:145], v[40:41]
	v_pk_mul_f32 v[36:37], v[140:141], v[36:37]
	v_pk_mul_f32 v[42:43], v[136:137], v[42:43]
	v_pk_mul_f32 v[38:39], v[132:133], v[38:39]
	s_and_b64 vcc, exec, s[42:43]
	v_pk_mul_f32 v[48:49], v[130:131], v[48:49]
	s_cbranch_vccnz .LBB0_672
	v_add_u32_e32 v52, 0x90, v216
	v_ashrrev_i32_e32 v52, 6, v52
	v_cvt_f32_i32_e32 v59, v52
	v_mul_f32_e32 v52, v0, v59
	v_mul_f32_e32 v53, v165, v59
	v_mul_f32_e32 v56, v167, v59
	v_floor_f32_e32 v52, v52
	v_floor_f32_e32 v53, v53
	v_floor_f32_e32 v56, v56
	v_mul_f32_e32 v62, v169, v59
	v_fma_f32 v54, v0, v59, -v52
	v_fma_f32 v55, v165, v59, -v53
	v_fma_f32 v56, v167, v59, -v56
	v_floor_f32_e32 v62, v62
	v_sin_f32_e32 v52, v54
	v_sin_f32_e32 v53, v55
	v_cos_f32_e32 v61, v56
	v_sin_f32_e32 v64, v56
	v_fma_f32 v59, v169, v59, -v62
	v_cos_f32_e32 v54, v54
	v_cos_f32_e32 v55, v55
	v_sin_f32_e32 v63, v59
	v_cos_f32_e32 v62, v59
	v_pk_mul_f32 v[56:57], v[52:53], v[46:47]
	v_mul_f32_e32 v60, v64, v36
	v_mul_f32_e32 v66, v61, v36
	v_mov_b32_e32 v36, v41
	v_pk_mul_f32 v[46:47], v[54:55], v[46:47]
	v_mul_f32_e32 v58, v61, v40
	v_mul_f32_e32 v64, v64, v40
	v_pk_mul_f32 v[40:41], v[62:63], v[36:37]
	v_pk_fma_f32 v[54:55], v[54:55], v[50:51], v[56:57] neg_lo:[0,0,1] neg_hi:[0,0,1]
	v_floor_f32_e32 v56, v118
	v_mov_b32_e32 v59, v40
	v_mov_b32_e32 v61, v41
	v_mov_b32_e32 v40, v63
	v_mov_b32_e32 v41, v62
	v_pk_fma_f32 v[46:47], v[52:53], v[50:51], v[46:47]
	v_floor_f32_e32 v50, v120
	v_fma_f32 v56, v167, v116, -v56
	v_floor_f32_e32 v62, v117
	v_pk_mul_f32 v[36:37], v[40:41], v[36:37]
	v_pk_add_f32 v[40:41], v[58:59], v[60:61] neg_lo:[0,1] neg_hi:[0,1]
	v_fma_f32 v51, v0, v116, -v50
	v_cos_f32_e32 v59, v56
	v_sin_f32_e32 v61, v56
	v_fma_f32 v62, v169, v116, -v62
	v_sin_f32_e32 v50, v51
	v_cos_f32_e32 v52, v51
	v_floor_f32_e32 v51, v119
	v_sin_f32_e32 v63, v62
	v_cos_f32_e32 v62, v62
	v_fma_f32 v53, v165, v116, -v51
	v_mov_b32_e32 v65, v36
	v_mov_b32_e32 v67, v37
	v_sin_f32_e32 v51, v53
	v_pk_add_f32 v[36:37], v[64:65], v[66:67]
	v_cos_f32_e32 v53, v53
	v_mul_f32_e32 v60, v61, v38
	v_mul_f32_e32 v66, v59, v38
	v_mov_b32_e32 v38, v43
	v_mul_f32_e32 v58, v59, v42
	v_mul_f32_e32 v64, v61, v42
	v_pk_mul_f32 v[42:43], v[62:63], v[38:39]
	v_pk_mul_f32 v[56:57], v[50:51], v[48:49]
	v_mov_b32_e32 v59, v42
	v_mov_b32_e32 v61, v43
	v_mov_b32_e32 v42, v63
	v_mov_b32_e32 v43, v62
	v_pk_mul_f32 v[38:39], v[42:43], v[38:39]
	v_pk_mul_f32 v[48:49], v[52:53], v[48:49]
	v_mov_b32_e32 v65, v38
	v_mov_b32_e32 v67, v39
	v_pk_fma_f32 v[52:53], v[52:53], v[44:45], v[56:57] neg_lo:[0,0,1] neg_hi:[0,0,1]
	v_pk_add_f32 v[42:43], v[58:59], v[60:61] neg_lo:[0,1] neg_hi:[0,1]
	v_pk_fma_f32 v[48:49], v[50:51], v[44:45], v[48:49]
	v_pk_add_f32 v[38:39], v[64:65], v[66:67]
	v_mov_b32_e32 v50, v54
	v_mov_b32_e32 v51, v55
	v_mov_b32_e32 v44, v52
	v_mov_b32_e32 v45, v53
.LBB0_672:
	s_mov_b32 s2, 0x24000
	v_add_co_u32_e32 v34, vcc, s2, v34
	v_pk_mul_f32 v[40:41], v[40:41], s[12:13] op_sel_hi:[1,0]
	v_pk_mul_f32 v[50:51], v[50:51], s[12:13] op_sel_hi:[1,0]
	v_pk_mul_f32 v[36:37], v[36:37], s[12:13] op_sel_hi:[1,0]
	v_addc_co_u32_e32 v35, vcc, 0, v35, vcc
	v_pk_mul_f32 v[46:47], v[46:47], s[12:13] op_sel_hi:[1,0]
	v_pk_mul_f32 v[42:43], v[42:43], s[12:13] op_sel_hi:[1,0]
	v_pk_mul_f32 v[44:45], v[44:45], s[12:13] op_sel_hi:[1,0]
	v_mbcnt_lo_u32_b32 v232, -1, 0
	v_mbcnt_hi_u32_b32 v232, -1, v232
	v_and_b32_e32 v233, 15, v232
	v_lshrrev_b32_e32 v234, 4, v232
	v_mul_u32_u24_e32 v222, 0x90, v233
	v_lshl_add_u32 v222, v234, 3, v222
	v_add_u32_e32 v222, m0, v222
	v_bfe_u32 v235, v232, 3, 1
	v_lshlrev_b32_e32 v235, 3, v235
	v_lshl_add_u32 v235, v234, 1, v235
	v_and_b32_e32 v232, 7, v232
	v_mul_u32_u24_e32 v224, 0x90, v235
	v_lshl_add_u32 v224, v232, 4, v224
	v_add_u32_e32 v224, m0, v224
	v_sub_u32_e32 v235, v235, v233
	v_mul_i32_i24_e32 v236, 0x400, v235
	v_lshl_add_u32 v236, v232, 4, v236
	v_lshlrev_b32_e32 v234, 3, v234
	v_sub_u32_e32 v236, v236, v234
	v_ashrrev_i32_e32 v237, 31, v236
	v_cvt_pk_bf16_f32 v228, v50, v51
	v_cvt_pk_bf16_f32 v229, v40, v41
	v_lshl_add_u64 v[236:237], v[34:35], 0, v[236:237]
	v_cvt_pk_bf16_f32 v230, v46, v47
	v_cvt_pk_bf16_f32 v231, v36, v37
	ds_write_b64 v222, v[228:229] offset:36864
	ds_write_b64 v222, v[230:231] offset:36896
	v_cvt_pk_bf16_f32 v232, v44, v45
	v_cvt_pk_bf16_f32 v233, v42, v43
	v_pk_mul_f32 v[38:39], v[38:39], s[12:13] op_sel_hi:[1,0]
	v_pk_mul_f32 v[48:49], v[48:49], s[12:13] op_sel_hi:[1,0]
	s_nop 0
	v_cvt_pk_bf16_f32 v234, v48, v49
	v_cvt_pk_bf16_f32 v235, v38, v39
	ds_write_b64 v222, v[232:233] offset:36928
	ds_write_b64 v222, v[234:235] offset:36960
	ds_read_b128 v[228:231], v224 offset:36864
	ds_read_b128 v[232:235], v224 offset:37008
	s_waitcnt lgkmcnt(1)
	global_store_dwordx4 v[236:237], v[228:231], off
	s_waitcnt lgkmcnt(0)
	global_store_dwordx4 v[236:237], v[232:235], off offset:1024
	v_pk_fma_f32 v[32:33], v[32:33], v[166:167], v[160:161] op_sel_hi:[1,0,1]
	v_pk_fma_f32 v[30:31], v[30:31], v[166:167], v[158:159] op_sel_hi:[1,0,1]
	v_pk_fma_f32 v[40:41], v[18:19], v[166:167], v[146:147] op_sel_hi:[1,0,1]
	v_mul_f32_e32 v18, v31, v31
	v_mul_f32_e32 v19, v33, v33
	v_pk_fma_f32 v[28:29], v[28:29], v[166:167], v[156:157] op_sel_hi:[1,0,1]
	v_pk_fma_f32 v[26:27], v[26:27], v[166:167], v[154:155] op_sel_hi:[1,0,1]
	v_fmac_f32_e32 v18, v30, v30
	v_fmac_f32_e32 v19, v32, v32
	v_pk_fma_f32 v[38:39], v[20:21], v[166:167], v[148:149] op_sel_hi:[1,0,1]
	v_add_f32_e32 v18, v18, v19
	v_mul_f32_e32 v19, v27, v27
	v_mul_f32_e32 v20, v29, v29
	v_fmac_f32_e32 v19, v26, v26
	v_fmac_f32_e32 v20, v28, v28
	v_pk_fma_f32 v[24:25], v[24:25], v[166:167], v[152:153] op_sel_hi:[1,0,1]
	v_pk_fma_f32 v[36:37], v[22:23], v[166:167], v[150:151] op_sel_hi:[1,0,1]
	v_add_f32_e32 v19, v19, v20
	v_add_f32_e32 v18, v18, v19
	v_mul_f32_e32 v19, v37, v37
	v_mul_f32_e32 v20, v25, v25
	v_fmac_f32_e32 v19, v36, v36
	v_fmac_f32_e32 v20, v24, v24
	v_add_f32_e32 v19, v19, v20
	v_add_f32_e32 v18, v19, v18
	v_mul_f32_e32 v19, v41, v41
	v_mul_f32_e32 v20, v39, v39
	v_fmac_f32_e32 v19, v40, v40
	v_fmac_f32_e32 v20, v38, v38
	v_add_f32_e32 v19, v19, v20
	v_add_f32_e32 v18, v19, v18
	v_mov_b32_e32 v19, v18
	s_nop 1
	v_permlane16_swap_b32_e32 v18, v19
	v_add_f32_e32 v18, v18, v19
	v_mov_b32_e32 v19, v18
	s_nop 1
	v_permlane32_swap_b32_e32 v18, v19
	v_add_f32_e32 v18, v18, v19
	v_fmamk_f32 v18, v18, 0x3c800000, v223
	v_rsq_f32_e32 v42, v18
	v_mov_b64_e32 v[18:19], v[162:163]
	v_mov_b64_e32 v[20:21], 0
	v_pk_mul_f32 v[26:27], v[26:27], v[42:43] op_sel_hi:[1,0]
	v_pk_mul_f32 v[20:21], v[30:31], v[42:43] op_sel_hi:[1,0]
	v_pk_mul_f32 v[24:25], v[24:25], v[42:43] op_sel_hi:[1,0]
	v_pk_mul_f32 v[22:23], v[32:33], v[42:43] op_sel_hi:[1,0]
	v_pk_mul_f32 v[34:35], v[142:143], v[20:21]
	v_pk_mul_f32 v[20:21], v[28:29], v[42:43] op_sel_hi:[1,0]
	v_pk_mul_f32 v[30:31], v[138:139], v[26:27]
	v_pk_mul_f32 v[28:29], v[36:37], v[42:43] op_sel_hi:[1,0]
	v_pk_mul_f32 v[26:27], v[136:137], v[24:25]
	v_pk_mul_f32 v[32:33], v[40:41], v[42:43] op_sel_hi:[1,0]
	v_pk_mul_f32 v[24:25], v[38:39], v[42:43] op_sel_hi:[1,0]
	v_pk_mul_f32 v[22:23], v[144:145], v[22:23]
	v_pk_mul_f32 v[20:21], v[140:141], v[20:21]
	v_pk_mul_f32 v[28:29], v[134:135], v[28:29]
	v_pk_mul_f32 v[24:25], v[132:133], v[24:25]
	s_and_b64 vcc, exec, s[42:43]
	v_pk_mul_f32 v[32:33], v[130:131], v[32:33]
	s_cbranch_vccnz .LBB0_674
	v_add_u32_e32 v36, 0xa0, v216
	v_ashrrev_i32_e32 v36, 6, v36
	v_cvt_f32_i32_e32 v43, v36
	v_mul_f32_e32 v36, v0, v43
	v_mul_f32_e32 v37, v165, v43
	v_mul_f32_e32 v40, v167, v43
	v_floor_f32_e32 v36, v36
	v_floor_f32_e32 v37, v37
	v_floor_f32_e32 v40, v40
	v_mul_f32_e32 v46, v169, v43
	v_fma_f32 v38, v0, v43, -v36
	v_fma_f32 v39, v165, v43, -v37
	v_fma_f32 v40, v167, v43, -v40
	v_floor_f32_e32 v46, v46
	v_sin_f32_e32 v36, v38
	v_sin_f32_e32 v37, v39
	v_cos_f32_e32 v45, v40
	v_sin_f32_e32 v48, v40
	v_fma_f32 v43, v169, v43, -v46
	v_cos_f32_e32 v38, v38
	v_cos_f32_e32 v39, v39
	v_sin_f32_e32 v47, v43
	v_cos_f32_e32 v46, v43
	v_pk_mul_f32 v[40:41], v[36:37], v[30:31]
	v_mul_f32_e32 v44, v48, v20
	v_mul_f32_e32 v50, v45, v20
	v_mov_b32_e32 v20, v23
	v_pk_mul_f32 v[30:31], v[38:39], v[30:31]
	v_mul_f32_e32 v42, v45, v22
	v_mul_f32_e32 v48, v48, v22
	v_pk_mul_f32 v[22:23], v[46:47], v[20:21]
	v_pk_fma_f32 v[38:39], v[38:39], v[34:35], v[40:41] neg_lo:[0,0,1] neg_hi:[0,0,1]
	v_floor_f32_e32 v40, v102
	v_mov_b32_e32 v43, v22
	v_mov_b32_e32 v45, v23
	v_mov_b32_e32 v22, v47
	v_mov_b32_e32 v23, v46
	v_pk_fma_f32 v[30:31], v[36:37], v[34:35], v[30:31]
	v_floor_f32_e32 v34, v104
	v_fma_f32 v40, v167, v100, -v40
	v_floor_f32_e32 v46, v101
	v_pk_mul_f32 v[20:21], v[22:23], v[20:21]
	v_pk_add_f32 v[22:23], v[42:43], v[44:45] neg_lo:[0,1] neg_hi:[0,1]
	v_fma_f32 v35, v0, v100, -v34
	v_cos_f32_e32 v43, v40
	v_sin_f32_e32 v45, v40
	v_fma_f32 v46, v169, v100, -v46
	v_sin_f32_e32 v34, v35
	v_cos_f32_e32 v36, v35
	v_floor_f32_e32 v35, v103
	v_sin_f32_e32 v47, v46
	v_cos_f32_e32 v46, v46
	v_fma_f32 v37, v165, v100, -v35
	v_mov_b32_e32 v49, v20
	v_mov_b32_e32 v51, v21
	v_sin_f32_e32 v35, v37
	v_pk_add_f32 v[20:21], v[48:49], v[50:51]
	v_cos_f32_e32 v37, v37
	v_mul_f32_e32 v44, v45, v24
	v_mul_f32_e32 v50, v43, v24
	v_mov_b32_e32 v24, v27
	v_mul_f32_e32 v42, v43, v26
	v_mul_f32_e32 v48, v45, v26
	v_pk_mul_f32 v[26:27], v[46:47], v[24:25]
	v_pk_mul_f32 v[40:41], v[34:35], v[32:33]
	v_mov_b32_e32 v43, v26
	v_mov_b32_e32 v45, v27
	v_mov_b32_e32 v26, v47
	v_mov_b32_e32 v27, v46
	v_pk_mul_f32 v[24:25], v[26:27], v[24:25]
	v_pk_mul_f32 v[32:33], v[36:37], v[32:33]
	v_mov_b32_e32 v49, v24
	v_mov_b32_e32 v51, v25
	v_pk_fma_f32 v[36:37], v[36:37], v[28:29], v[40:41] neg_lo:[0,0,1] neg_hi:[0,0,1]
	v_pk_add_f32 v[26:27], v[42:43], v[44:45] neg_lo:[0,1] neg_hi:[0,1]
	v_pk_fma_f32 v[32:33], v[34:35], v[28:29], v[32:33]
	v_pk_add_f32 v[24:25], v[48:49], v[50:51]
	v_mov_b32_e32 v34, v38
	v_mov_b32_e32 v35, v39
	v_mov_b32_e32 v28, v36
	v_mov_b32_e32 v29, v37
.LBB0_674:
	s_mov_b32 s2, 0x28000
	v_add_co_u32_e32 v18, vcc, s2, v18
	v_pk_mul_f32 v[22:23], v[22:23], s[12:13] op_sel_hi:[1,0]
	v_pk_mul_f32 v[34:35], v[34:35], s[12:13] op_sel_hi:[1,0]
	v_pk_mul_f32 v[20:21], v[20:21], s[12:13] op_sel_hi:[1,0]
	v_addc_co_u32_e32 v19, vcc, 0, v19, vcc
	v_pk_mul_f32 v[30:31], v[30:31], s[12:13] op_sel_hi:[1,0]
	v_pk_mul_f32 v[26:27], v[26:27], s[12:13] op_sel_hi:[1,0]
	v_pk_mul_f32 v[28:29], v[28:29], s[12:13] op_sel_hi:[1,0]
	v_pk_mul_f32 v[24:25], v[24:25], s[12:13] op_sel_hi:[1,0]
	v_mbcnt_lo_u32_b32 v232, -1, 0
	v_mbcnt_hi_u32_b32 v232, -1, v232
	v_and_b32_e32 v233, 15, v232
	v_lshrrev_b32_e32 v234, 4, v232
	v_mul_u32_u24_e32 v222, 0x90, v233
	v_lshl_add_u32 v222, v234, 3, v222
	v_add_u32_e32 v222, m0, v222
	v_bfe_u32 v235, v232, 3, 1
	v_lshlrev_b32_e32 v235, 3, v235
	v_lshl_add_u32 v235, v234, 1, v235
	v_and_b32_e32 v232, 7, v232
	v_mul_u32_u24_e32 v224, 0x90, v235
	v_lshl_add_u32 v224, v232, 4, v224
	v_add_u32_e32 v224, m0, v224
	v_sub_u32_e32 v235, v235, v233
	v_mul_i32_i24_e32 v236, 0x400, v235
	v_lshl_add_u32 v236, v232, 4, v236
	v_lshlrev_b32_e32 v234, 3, v234
	v_sub_u32_e32 v236, v236, v234
	v_ashrrev_i32_e32 v237, 31, v236
	v_cvt_pk_bf16_f32 v228, v34, v35
	v_cvt_pk_bf16_f32 v229, v22, v23
	v_lshl_add_u64 v[236:237], v[18:19], 0, v[236:237]
	v_cvt_pk_bf16_f32 v230, v30, v31
	v_cvt_pk_bf16_f32 v231, v20, v21
	ds_write_b64 v222, v[228:229] offset:36864
	ds_write_b64 v222, v[230:231] offset:36896
	v_cvt_pk_bf16_f32 v232, v28, v29
	v_cvt_pk_bf16_f32 v233, v26, v27
	v_pk_fma_f32 v[16:17], v[16:17], v[164:165], v[160:161] op_sel_hi:[1,0,1]
	v_pk_fma_f32 v[14:15], v[14:15], v[164:165], v[158:159] op_sel_hi:[1,0,1]
	v_pk_mul_f32 v[32:33], v[32:33], s[12:13] op_sel_hi:[1,0]
	s_nop 0
	v_cvt_pk_bf16_f32 v234, v32, v33
	v_cvt_pk_bf16_f32 v235, v24, v25
	v_pk_fma_f32 v[24:25], v[2:3], v[164:165], v[146:147] op_sel_hi:[1,0,1]
	v_mul_f32_e32 v2, v15, v15
	v_mul_f32_e32 v3, v17, v17
	v_pk_fma_f32 v[12:13], v[12:13], v[164:165], v[156:157] op_sel_hi:[1,0,1]
	v_pk_fma_f32 v[10:11], v[10:11], v[164:165], v[154:155] op_sel_hi:[1,0,1]
	v_fmac_f32_e32 v2, v14, v14
	v_fmac_f32_e32 v3, v16, v16
	v_pk_fma_f32 v[22:23], v[6:7], v[164:165], v[150:151] op_sel_hi:[1,0,1]
	v_add_f32_e32 v2, v2, v3
	v_mul_f32_e32 v3, v11, v11
	v_mul_f32_e32 v6, v13, v13
	v_fmac_f32_e32 v3, v10, v10
	v_fmac_f32_e32 v6, v12, v12
	v_pk_fma_f32 v[8:9], v[8:9], v[164:165], v[152:153] op_sel_hi:[1,0,1]
	v_add_f32_e32 v3, v3, v6
	v_add_f32_e32 v2, v2, v3
	v_mul_f32_e32 v3, v23, v23
	v_mul_f32_e32 v6, v9, v9
	v_fmac_f32_e32 v3, v22, v22
	v_fmac_f32_e32 v6, v8, v8
	v_pk_fma_f32 v[4:5], v[4:5], v[164:165], v[148:149] op_sel_hi:[1,0,1]
	v_add_f32_e32 v3, v3, v6
	v_add_f32_e32 v2, v3, v2
	v_mul_f32_e32 v3, v25, v25
	v_mul_f32_e32 v6, v5, v5
	v_fmac_f32_e32 v3, v24, v24
	v_fmac_f32_e32 v6, v4, v4
	v_add_f32_e32 v3, v3, v6
	v_add_f32_e32 v2, v3, v2
	v_mov_b32_e32 v3, v2
	s_nop 1
	v_permlane16_swap_b32_e32 v2, v3
	v_add_f32_e32 v2, v2, v3
	v_mov_b32_e32 v3, v2
	s_nop 1
	v_permlane32_swap_b32_e32 v2, v3
	v_add_f32_e32 v2, v2, v3
	v_fmamk_f32 v2, v2, 0x3c800000, v223
	v_rsq_f32_e32 v26, v2
	v_mov_b64_e32 v[2:3], 0
	ds_write_b64 v222, v[232:233] offset:36928
	ds_write_b64 v222, v[234:235] offset:36960
	ds_read_b128 v[228:231], v224 offset:36864
	ds_read_b128 v[232:235], v224 offset:37008
	s_waitcnt lgkmcnt(1)
	global_store_dwordx4 v[236:237], v[228:231], off
	s_waitcnt lgkmcnt(0)
	global_store_dwordx4 v[236:237], v[232:235], off offset:1024
	v_pk_mul_f32 v[10:11], v[10:11], v[26:27] op_sel_hi:[1,0]
	v_pk_mul_f32 v[2:3], v[14:15], v[26:27] op_sel_hi:[1,0]
	v_pk_mul_f32 v[6:7], v[16:17], v[26:27] op_sel_hi:[1,0]
	v_pk_mul_f32 v[16:17], v[142:143], v[2:3]
	v_pk_mul_f32 v[2:3], v[12:13], v[26:27] op_sel_hi:[1,0]
	v_pk_mul_f32 v[12:13], v[138:139], v[10:11]
	v_pk_mul_f32 v[10:11], v[22:23], v[26:27] op_sel_hi:[1,0]
	v_pk_mul_f32 v[8:9], v[8:9], v[26:27] op_sel_hi:[1,0]
	v_pk_mul_f32 v[14:15], v[24:25], v[26:27] op_sel_hi:[1,0]
	v_pk_mul_f32 v[4:5], v[4:5], v[26:27] op_sel_hi:[1,0]
	v_pk_mul_f32 v[6:7], v[144:145], v[6:7]
	v_pk_mul_f32 v[2:3], v[140:141], v[2:3]
	v_pk_mul_f32 v[8:9], v[136:137], v[8:9]
	v_pk_mul_f32 v[10:11], v[134:135], v[10:11]
	v_pk_mul_f32 v[4:5], v[132:133], v[4:5]
	s_and_b64 vcc, exec, s[42:43]
	v_pk_mul_f32 v[14:15], v[130:131], v[14:15]
	s_cbranch_vccnz .LBB0_676
	v_add_u32_e32 v18, 0xb0, v216
	v_ashrrev_i32_e32 v18, 6, v18
	v_cvt_f32_i32_e32 v25, v18
	v_mul_f32_e32 v18, v0, v25
	v_mul_f32_e32 v19, v165, v25
	v_floor_f32_e32 v18, v18
	v_floor_f32_e32 v19, v19
	v_fma_f32 v20, v0, v25, -v18
	v_fma_f32 v21, v165, v25, -v19
	v_sin_f32_e32 v18, v20
	v_cos_f32_e32 v20, v20
	v_sin_f32_e32 v19, v21
	v_cos_f32_e32 v21, v21
	v_mul_f32_e32 v22, v167, v25
	v_floor_f32_e32 v22, v22
	v_mul_f32_e32 v28, v169, v25
	v_fma_f32 v22, v167, v25, -v22
	v_floor_f32_e32 v28, v28
	v_cos_f32_e32 v27, v22
	v_sin_f32_e32 v30, v22
	v_fma_f32 v25, v169, v25, -v28
	v_pk_mul_f32 v[22:23], v[18:19], v[12:13]
	v_pk_mul_f32 v[12:13], v[20:21], v[12:13]
	v_sin_f32_e32 v29, v25
	v_cos_f32_e32 v28, v25
	v_pk_fma_f32 v[20:21], v[20:21], v[16:17], v[22:23] neg_lo:[0,0,1] neg_hi:[0,0,1]
	v_pk_fma_f32 v[12:13], v[18:19], v[16:17], v[12:13]
	v_floor_f32_e32 v16, v88
	v_fma_f32 v0, v0, v84, -v16
	v_mul_f32_e32 v26, v30, v2
	v_mul_f32_e32 v32, v27, v2
	v_mov_b32_e32 v2, v7
	v_sin_f32_e32 v16, v0
	v_cos_f32_e32 v18, v0
	v_floor_f32_e32 v0, v87
	v_mul_f32_e32 v24, v27, v6
	v_mul_f32_e32 v30, v30, v6
	v_pk_mul_f32 v[6:7], v[28:29], v[2:3]
	v_fma_f32 v0, v165, v84, -v0
	v_mov_b32_e32 v25, v6
	v_mov_b32_e32 v27, v7
	v_mov_b32_e32 v6, v29
	v_mov_b32_e32 v7, v28
	v_sin_f32_e32 v17, v0
	v_cos_f32_e32 v19, v0
	v_floor_f32_e32 v0, v86
	v_pk_mul_f32 v[2:3], v[6:7], v[2:3]
	v_pk_add_f32 v[6:7], v[24:25], v[26:27] neg_lo:[0,1] neg_hi:[0,1]
	v_fma_f32 v0, v167, v84, -v0
	v_floor_f32_e32 v27, v85
	v_cos_f32_e32 v25, v0
	v_sin_f32_e32 v0, v0
	v_fma_f32 v27, v169, v84, -v27
	v_sin_f32_e32 v29, v27
	v_cos_f32_e32 v28, v27
	v_mov_b32_e32 v31, v2
	v_mov_b32_e32 v33, v3
	v_pk_add_f32 v[2:3], v[30:31], v[32:33]
	v_mul_f32_e32 v26, v0, v4
	v_mul_f32_e32 v32, v25, v4
	v_mov_b32_e32 v4, v9
	v_mul_f32_e32 v24, v25, v8
	v_mul_f32_e32 v30, v0, v8
	v_pk_mul_f32 v[8:9], v[28:29], v[4:5]
	v_pk_mul_f32 v[22:23], v[16:17], v[14:15]
	v_mov_b32_e32 v25, v8
	v_mov_b32_e32 v27, v9
	v_mov_b32_e32 v8, v29
	v_mov_b32_e32 v9, v28
	v_pk_mul_f32 v[4:5], v[8:9], v[4:5]
	v_pk_mul_f32 v[14:15], v[18:19], v[14:15]
	v_mov_b32_e32 v31, v4
	v_mov_b32_e32 v33, v5
	v_pk_fma_f32 v[18:19], v[18:19], v[10:11], v[22:23] neg_lo:[0,0,1] neg_hi:[0,0,1]
	v_pk_add_f32 v[8:9], v[24:25], v[26:27] neg_lo:[0,1] neg_hi:[0,1]
	v_pk_fma_f32 v[14:15], v[16:17], v[10:11], v[14:15]
	v_pk_add_f32 v[4:5], v[30:31], v[32:33]
	v_mov_b32_e32 v16, v20
	v_mov_b32_e32 v17, v21
	v_mov_b32_e32 v10, v18
	v_mov_b32_e32 v11, v19
.LBB0_676:
	v_pk_mul_f32 v[6:7], v[6:7], s[12:13] op_sel_hi:[1,0]
	v_pk_mul_f32 v[16:17], v[16:17], s[12:13] op_sel_hi:[1,0]
	s_mov_b32 s2, 0x2c000
	v_mbcnt_lo_u32_b32 v232, -1, 0
	v_mbcnt_hi_u32_b32 v232, -1, v232
	v_and_b32_e32 v233, 15, v232
	v_lshrrev_b32_e32 v234, 4, v232
	v_mul_u32_u24_e32 v222, 0x90, v233
	v_lshl_add_u32 v222, v234, 3, v222
	v_add_u32_e32 v222, m0, v222
	v_bfe_u32 v235, v232, 3, 1
	v_lshlrev_b32_e32 v235, 3, v235
	v_lshl_add_u32 v235, v234, 1, v235
	v_and_b32_e32 v232, 7, v232
	v_mul_u32_u24_e32 v224, 0x90, v235
	v_lshl_add_u32 v224, v232, 4, v224
	v_add_u32_e32 v224, m0, v224
	v_sub_u32_e32 v235, v235, v233
	v_mul_i32_i24_e32 v236, 0x400, v235
	v_lshl_add_u32 v236, v232, 4, v236
	v_lshlrev_b32_e32 v234, 3, v234
	v_sub_u32_e32 v236, v236, v234
	v_ashrrev_i32_e32 v237, 31, v236
	v_cvt_pk_bf16_f32 v228, v16, v17
	v_cvt_pk_bf16_f32 v229, v6, v7
	v_add_co_u32_e32 v6, vcc, s2, v162
	v_pk_mul_f32 v[2:3], v[2:3], s[12:13] op_sel_hi:[1,0]
	v_pk_mul_f32 v[12:13], v[12:13], s[12:13] op_sel_hi:[1,0]
	v_addc_co_u32_e32 v7, vcc, 0, v163, vcc
	v_pk_mul_f32 v[8:9], v[8:9], s[12:13] op_sel_hi:[1,0]
	v_pk_mul_f32 v[10:11], v[10:11], s[12:13] op_sel_hi:[1,0]
	v_lshl_add_u64 v[236:237], v[6:7], 0, v[236:237]
	v_cvt_pk_bf16_f32 v230, v12, v13
	v_cvt_pk_bf16_f32 v231, v2, v3
	ds_write_b64 v222, v[228:229] offset:36864
	ds_write_b64 v222, v[230:231] offset:36896
	v_cvt_pk_bf16_f32 v232, v10, v11
	v_cvt_pk_bf16_f32 v233, v8, v9
	v_pk_mul_f32 v[4:5], v[4:5], s[12:13] op_sel_hi:[1,0]
	v_pk_mul_f32 v[14:15], v[14:15], s[12:13] op_sel_hi:[1,0]
	s_nop 0
	v_cvt_pk_bf16_f32 v234, v14, v15
	v_cvt_pk_bf16_f32 v235, v4, v5
	ds_write_b64 v222, v[232:233] offset:36928
	ds_write_b64 v222, v[234:235] offset:36960
	ds_read_b128 v[228:231], v224 offset:36864
	ds_read_b128 v[232:235], v224 offset:37008
	s_waitcnt lgkmcnt(1)
	global_store_dwordx4 v[236:237], v[228:231], off
	s_waitcnt lgkmcnt(0)
	global_store_dwordx4 v[236:237], v[232:235], off offset:1024
	s_andn2_b64 vcc, exec, s[40:41]
	s_mov_b64 s[2:3], -1
	s_cbranch_vccnz .LBB0_592
